# combination: K-fragment ring in QK^T segments + counted waits in PV segments (attention), peeled SrcC=0 first K-iteration in all GEMM loops, relaxed first-iteration waits in G5
# speedup vs baseline: 1.0052x; 1.0052x over previous
.LBB0_497:
	v_exp_f32_e64 v151, -|v85|
	v_cmp_lt_f32_e32 vcc, 0, v85
	v_add_f32_e32 v168, 1.0, v151
	v_rcp_f32_e32 v168, v168
	s_nop 0
	v_mul_f32_e32 v151, v151, v168
	v_cndmask_b32_e32 v85, v151, v168, vcc
	v_cndmask_b32_e32 v151, v168, v151, vcc
	v_exp_f32_e64 v168, -|v69|
	v_cmp_lt_f32_e32 vcc, 0, v69
	v_add_f32_e32 v169, 1.0, v168
	v_rcp_f32_e32 v169, v169
	s_nop 0
	v_mul_f32_e32 v168, v168, v169
	v_cndmask_b32_e32 v69, v168, v169, vcc
	v_cndmask_b32_e32 v168, v169, v168, vcc
	v_exp_f32_e64 v169, -|v84|
	v_cmp_lt_f32_e32 vcc, 0, v84
	v_add_f32_e32 v179, 1.0, v169
	v_rcp_f32_e32 v179, v179
	s_nop 0
	v_mul_f32_e32 v169, v169, v179
	v_cndmask_b32_e32 v84, v169, v179, vcc
	v_cndmask_b32_e32 v169, v179, v169, vcc
	v_mul_f32_e32 v84, v151, v84
	v_mul_f32_e32 v151, v151, v169
	v_exp_f32_e64 v169, -|v68|
	v_cmp_lt_f32_e32 vcc, 0, v68
	v_add_f32_e32 v179, 1.0, v169
	v_rcp_f32_e32 v179, v179
	s_nop 0
	v_mul_f32_e32 v169, v169, v179
	v_cndmask_b32_e32 v68, v169, v179, vcc
	v_cndmask_b32_e32 v169, v179, v169, vcc
	v_mul_f32_e32 v68, v168, v68
	v_mul_f32_e32 v168, v168, v169
	v_exp_f32_e64 v169, -|v83|
	v_cmp_lt_f32_e32 vcc, 0, v83
	v_add_f32_e32 v179, 1.0, v169
	v_rcp_f32_e32 v179, v179
	s_nop 0
	v_mul_f32_e32 v169, v169, v179
	v_cndmask_b32_e32 v83, v169, v179, vcc
	v_cndmask_b32_e32 v169, v179, v169, vcc
	v_mul_f32_e32 v83, v83, v151
	v_mul_f32_e32 v151, v169, v151
	v_exp_f32_e64 v169, -|v67|
	v_cmp_lt_f32_e32 vcc, 0, v67
	v_add_f32_e32 v179, 1.0, v169
	v_rcp_f32_e32 v179, v179
	s_nop 0
	v_mul_f32_e32 v169, v169, v179
	v_cndmask_b32_e32 v67, v169, v179, vcc
	v_cndmask_b32_e32 v169, v179, v169, vcc
	v_mul_f32_e32 v67, v67, v168
	v_mul_f32_e32 v169, v169, v168
	v_exp_f32_e64 v168, -|v82|
	v_cmp_lt_f32_e32 vcc, 0, v82
	v_add_f32_e32 v179, 1.0, v168
	v_rcp_f32_e32 v179, v179
	s_nop 0
	v_mul_f32_e32 v168, v168, v179
	v_cndmask_b32_e32 v82, v168, v179, vcc
	v_cndmask_b32_e32 v168, v179, v168, vcc
	v_mul_f32_e32 v82, v82, v151
	v_mul_f32_e32 v168, v168, v151
	v_exp_f32_e64 v151, -|v66|
	v_cmp_lt_f32_e32 vcc, 0, v66
	v_add_f32_e32 v179, 1.0, v151
	v_rcp_f32_e32 v179, v179
	s_nop 0
	v_mul_f32_e32 v151, v151, v179
	v_cndmask_b32_e32 v66, v151, v179, vcc
	v_cndmask_b32_e32 v151, v179, v151, vcc
	v_mul_f32_e32 v66, v66, v169
	v_mul_f32_e32 v169, v151, v169
	v_exp_f32_e64 v151, -|v89|
	v_cmp_lt_f32_e32 vcc, 0, v89
	v_add_f32_e32 v179, 1.0, v151
	v_rcp_f32_e32 v179, v179
	s_nop 0
	v_mul_f32_e32 v151, v151, v179
	v_cndmask_b32_e32 v89, v151, v179, vcc
	v_cndmask_b32_e32 v151, v179, v151, vcc
	v_exp_f32_e64 v179, -|v73|
	v_cmp_lt_f32_e32 vcc, 0, v73
	v_add_f32_e32 v180, 1.0, v179
	v_rcp_f32_e32 v180, v180
	s_nop 0
	v_mul_f32_e32 v179, v179, v180
	v_cndmask_b32_e32 v73, v179, v180, vcc
	v_cndmask_b32_e32 v179, v180, v179, vcc
	v_exp_f32_e64 v180, -|v88|
	v_cmp_lt_f32_e32 vcc, 0, v88
	v_add_f32_e32 v181, 1.0, v180
	v_rcp_f32_e32 v181, v181
	s_nop 0
	v_mul_f32_e32 v180, v180, v181
	v_cndmask_b32_e32 v88, v180, v181, vcc
	v_cndmask_b32_e32 v180, v181, v180, vcc
	v_mul_f32_e32 v88, v151, v88
	v_mul_f32_e32 v151, v151, v180
	v_exp_f32_e64 v180, -|v72|
	v_cmp_lt_f32_e32 vcc, 0, v72
	v_add_f32_e32 v181, 1.0, v180
	v_rcp_f32_e32 v181, v181
	s_nop 0
	v_mul_f32_e32 v180, v180, v181
	v_cndmask_b32_e32 v72, v180, v181, vcc
	v_cndmask_b32_e32 v180, v181, v180, vcc
	v_mul_f32_e32 v72, v179, v72
	v_mul_f32_e32 v179, v179, v180
	v_exp_f32_e64 v180, -|v87|
	v_cmp_lt_f32_e32 vcc, 0, v87
	v_add_f32_e32 v181, 1.0, v180
	v_rcp_f32_e32 v181, v181
	s_nop 0
	v_mul_f32_e32 v180, v180, v181
	v_cndmask_b32_e32 v87, v180, v181, vcc
	v_cndmask_b32_e32 v180, v181, v180, vcc
	v_mul_f32_e32 v87, v87, v151
	v_mul_f32_e32 v151, v180, v151
	v_exp_f32_e64 v180, -|v71|
	v_cmp_lt_f32_e32 vcc, 0, v71
	v_add_f32_e32 v181, 1.0, v180
	v_rcp_f32_e32 v181, v181
	s_nop 0
	v_mul_f32_e32 v180, v180, v181
	v_cndmask_b32_e32 v71, v180, v181, vcc
	v_cndmask_b32_e32 v180, v181, v180, vcc
	v_mul_f32_e32 v71, v71, v179
	v_mul_f32_e32 v180, v180, v179
	v_exp_f32_e64 v179, -|v86|
	v_cmp_lt_f32_e32 vcc, 0, v86
	v_add_f32_e32 v181, 1.0, v179
	v_rcp_f32_e32 v181, v181
	s_nop 0
	v_mul_f32_e32 v179, v179, v181
	v_cndmask_b32_e32 v86, v179, v181, vcc
	v_cndmask_b32_e32 v179, v181, v179, vcc
	v_mul_f32_e32 v86, v86, v151
	v_mul_f32_e32 v179, v179, v151
	v_exp_f32_e64 v151, -|v70|
	v_cmp_lt_f32_e32 vcc, 0, v70
	v_add_f32_e32 v181, 1.0, v151
	v_rcp_f32_e32 v181, v181
	s_nop 0
	v_mul_f32_e32 v151, v151, v181
	v_cndmask_b32_e32 v70, v151, v181, vcc
	v_cndmask_b32_e32 v151, v181, v151, vcc
	v_mul_f32_e32 v70, v70, v180
	v_mul_f32_e32 v180, v151, v180
	v_exp_f32_e64 v151, -|v93|
	v_cmp_lt_f32_e32 vcc, 0, v93
	v_add_f32_e32 v181, 1.0, v151
	v_rcp_f32_e32 v181, v181
	s_nop 0
	v_mul_f32_e32 v151, v151, v181
	v_cndmask_b32_e32 v93, v151, v181, vcc
	v_cndmask_b32_e32 v151, v181, v151, vcc
	v_exp_f32_e64 v181, -|v77|
	v_cmp_lt_f32_e32 vcc, 0, v77
	v_add_f32_e32 v182, 1.0, v181
	v_rcp_f32_e32 v182, v182
	s_nop 0
	v_mul_f32_e32 v181, v181, v182
	v_cndmask_b32_e32 v77, v181, v182, vcc
	v_cndmask_b32_e32 v181, v182, v181, vcc
	v_exp_f32_e64 v182, -|v92|
	v_cmp_lt_f32_e32 vcc, 0, v92
	v_add_f32_e32 v183, 1.0, v182
	v_rcp_f32_e32 v183, v183
	s_nop 0
	v_mul_f32_e32 v182, v182, v183
	v_cndmask_b32_e32 v92, v182, v183, vcc
	v_cndmask_b32_e32 v182, v183, v182, vcc
	v_mul_f32_e32 v92, v151, v92
	v_mul_f32_e32 v151, v151, v182
	v_exp_f32_e64 v182, -|v76|
	v_cmp_lt_f32_e32 vcc, 0, v76
	v_add_f32_e32 v183, 1.0, v182
	v_rcp_f32_e32 v183, v183
	s_nop 0
	v_mul_f32_e32 v182, v182, v183
	v_cndmask_b32_e32 v76, v182, v183, vcc
	v_cndmask_b32_e32 v182, v183, v182, vcc
	v_mul_f32_e32 v76, v181, v76
	v_mul_f32_e32 v181, v181, v182
	v_exp_f32_e64 v182, -|v91|
	v_cmp_lt_f32_e32 vcc, 0, v91
	v_add_f32_e32 v183, 1.0, v182
	v_rcp_f32_e32 v183, v183
	s_nop 0
	v_mul_f32_e32 v182, v182, v183
	v_cndmask_b32_e32 v91, v182, v183, vcc
	v_cndmask_b32_e32 v182, v183, v182, vcc
	v_mul_f32_e32 v91, v91, v151
	v_mul_f32_e32 v151, v182, v151
	v_exp_f32_e64 v182, -|v75|
	v_cmp_lt_f32_e32 vcc, 0, v75
	v_add_f32_e32 v183, 1.0, v182
	v_rcp_f32_e32 v183, v183
	s_nop 0
	v_mul_f32_e32 v182, v182, v183
	v_cndmask_b32_e32 v75, v182, v183, vcc
	v_cndmask_b32_e32 v182, v183, v182, vcc
	v_mul_f32_e32 v75, v75, v181
	v_mul_f32_e32 v182, v182, v181
	v_exp_f32_e64 v181, -|v90|
	v_cmp_lt_f32_e32 vcc, 0, v90
	v_add_f32_e32 v183, 1.0, v181
	v_rcp_f32_e32 v183, v183
	s_nop 0
	v_mul_f32_e32 v181, v181, v183
	v_cndmask_b32_e32 v90, v181, v183, vcc
	v_cndmask_b32_e32 v181, v183, v181, vcc
	v_mul_f32_e32 v90, v90, v151
	v_mul_f32_e32 v181, v181, v151
	v_exp_f32_e64 v151, -|v74|
	v_cmp_lt_f32_e32 vcc, 0, v74
	v_add_f32_e32 v183, 1.0, v151
	v_rcp_f32_e32 v183, v183
	s_nop 0
	v_mul_f32_e32 v151, v151, v183
	v_cndmask_b32_e32 v74, v151, v183, vcc
	v_cndmask_b32_e32 v151, v183, v151, vcc
	v_mul_f32_e32 v74, v74, v182
	v_mul_f32_e32 v151, v151, v182
	v_exp_f32_e64 v182, -|v97|
	v_cmp_lt_f32_e32 vcc, 0, v97
	v_add_f32_e32 v183, 1.0, v182
	v_rcp_f32_e32 v183, v183
	s_nop 0
	v_mul_f32_e32 v182, v182, v183
	v_cndmask_b32_e32 v97, v182, v183, vcc
	v_cndmask_b32_e32 v182, v183, v182, vcc
	v_exp_f32_e64 v183, -|v81|
	v_cmp_lt_f32_e32 vcc, 0, v81
	v_add_f32_e32 v184, 1.0, v183
	v_rcp_f32_e32 v184, v184
	s_nop 0
	v_mul_f32_e32 v183, v183, v184
	v_cndmask_b32_e32 v185, v183, v184, vcc
	v_cndmask_b32_e32 v81, v184, v183, vcc
	v_exp_f32_e64 v183, -|v96|
	v_cmp_lt_f32_e32 vcc, 0, v96
	v_add_f32_e32 v184, 1.0, v183
	v_rcp_f32_e32 v184, v184
	s_nop 0
	v_mul_f32_e32 v183, v183, v184
	v_cndmask_b32_e32 v96, v183, v184, vcc
	v_cndmask_b32_e32 v183, v184, v183, vcc
	v_mul_f32_e32 v96, v182, v96
	v_mul_f32_e32 v182, v182, v183
	v_exp_f32_e64 v183, -|v80|
	v_cmp_lt_f32_e32 vcc, 0, v80
	v_add_f32_e32 v184, 1.0, v183
	v_rcp_f32_e32 v184, v184
	s_nop 0
	v_mul_f32_e32 v183, v183, v184
	v_cndmask_b32_e32 v80, v183, v184, vcc
	v_mul_f32_e32 v186, v81, v80
	v_cndmask_b32_e32 v80, v184, v183, vcc
	v_mul_f32_e32 v80, v81, v80
	v_exp_f32_e64 v81, -|v95|
	v_cmp_lt_f32_e32 vcc, 0, v95
	v_add_f32_e32 v183, 1.0, v81
	v_rcp_f32_e32 v183, v183
	s_nop 0
	v_mul_f32_e32 v81, v81, v183
	v_cndmask_b32_e32 v95, v81, v183, vcc
	v_cndmask_b32_e32 v81, v183, v81, vcc
	v_mul_f32_e32 v95, v95, v182
	v_mul_f32_e32 v81, v81, v182
	v_exp_f32_e64 v182, -|v79|
	v_cmp_lt_f32_e32 vcc, 0, v79
	v_add_f32_e32 v183, 1.0, v182
	v_rcp_f32_e32 v183, v183
	s_nop 0
	v_mul_f32_e32 v182, v182, v183
	v_cndmask_b32_e32 v79, v182, v183, vcc
	v_mul_f32_e32 v184, v79, v80
	v_cndmask_b32_e32 v79, v183, v182, vcc
	v_mul_f32_e32 v79, v79, v80
	v_exp_f32_e64 v80, -|v94|
	v_cmp_lt_f32_e32 vcc, 0, v94
	v_add_f32_e32 v182, 1.0, v80
	v_rcp_f32_e32 v182, v182
	s_nop 0
	v_mul_f32_e32 v80, v80, v182
	v_cndmask_b32_e32 v94, v80, v182, vcc
	v_cndmask_b32_e32 v80, v182, v80, vcc
	v_mul_f32_e32 v182, v80, v81
	v_exp_f32_e64 v80, -|v78|
	v_mul_f32_e32 v94, v94, v81
	v_cmp_lt_f32_e32 vcc, 0, v78
	v_add_f32_e32 v81, 1.0, v80
	v_rcp_f32_e32 v81, v81
	s_nop 0
	v_mul_f32_e32 v80, v80, v81
	v_cndmask_b32_e32 v78, v80, v81, vcc
	v_mul_f32_e32 v183, v78, v79
	v_cndmask_b32_e32 v78, v81, v80, vcc
	v_mul_f32_e32 v78, v78, v79
	v_mov_b32_e32 v79, v78
	s_nop 1
	v_permlane32_swap_b32_e32 v78, v79
	v_mul_f32_e32 v80, v150, v79
	v_mul_f32_e32 v78, v78, v79
	v_mov_b32_e32 v79, v151
	s_nop 1
	v_permlane32_swap_b32_e32 v151, v79
	v_cndmask_b32_e64 v187, v150, v80, s[38:39]
	v_pk_mul_f32 v[80:81], v[150:151], v[78:79]
	s_nop 0
	v_mul_f32_e32 v78, v80, v79
	v_cndmask_b32_e64 v151, v80, v78, s[38:39]
	v_pk_mul_f32 v[78:79], v[80:81], v[80:81] op_sel:[0,1] op_sel_hi:[1,0]
	v_mov_b32_e32 v81, v169
	v_mov_b32_e32 v79, v180
	s_nop 1
	v_permlane32_swap_b32_e32 v180, v79
	v_mul_f32_e32 v80, v78, v79
	v_permlane32_swap_b32_e32 v169, v81
	v_cndmask_b32_e64 v188, v78, v80, s[38:39]
	v_mul_f32_e32 v80, v180, v79
	v_mov_b32_e32 v79, v169
	v_pk_mul_f32 v[78:79], v[78:79], v[80:81]
	s_nop 0
	v_mul_f32_e32 v80, v78, v81
	v_cndmask_b32_e64 v169, v78, v80, s[38:39]
	v_pk_mul_f32 v[78:79], v[78:79], v[78:79] op_sel:[0,1] op_sel_hi:[1,0]
	v_mov_b32_e32 v81, v181
	v_mov_b32_e32 v79, v182
	s_nop 1
	v_permlane32_swap_b32_e32 v182, v79
	v_mul_f32_e32 v80, v78, v79
	v_permlane32_swap_b32_e32 v181, v81
	v_cndmask_b32_e64 v180, v78, v80, s[38:39]
	v_mul_f32_e32 v80, v182, v79
	v_mov_b32_e32 v79, v181
	v_pk_mul_f32 v[78:79], v[78:79], v[80:81]
	s_nop 0
	v_mul_f32_e32 v80, v78, v81
	v_cndmask_b32_e64 v181, v78, v80, s[38:39]
	v_pk_mul_f32 v[78:79], v[78:79], v[78:79] op_sel:[0,1] op_sel_hi:[1,0]
	v_mov_b32_e32 v81, v168
	v_mov_b32_e32 v79, v179
	s_nop 1
	v_permlane32_swap_b32_e32 v179, v79
	v_mul_f32_e32 v80, v78, v79
	v_permlane32_swap_b32_e32 v168, v81
	v_cndmask_b32_e64 v182, v78, v80, s[38:39]
	v_mul_f32_e32 v80, v179, v79
	v_mov_b32_e32 v79, v168
	v_pk_mul_f32 v[78:79], v[78:79], v[80:81]
	s_nop 0
	v_mul_f32_e32 v80, v78, v81
	v_mul_f32_e32 v150, v78, v79
	v_cndmask_b32_e64 v80, v78, v80, s[38:39]
	v_cmp_eq_f32_e32 vcc, 0, v150
	v_mul_f32_e32 v78, v82, v80
	v_mul_f32_e32 v79, v66, v169
	v_mul_f32_e32 v66, v83, v80
	v_mul_f32_e32 v81, v67, v169
	v_mul_f32_e32 v67, v84, v80
	v_mul_f32_e32 v82, v68, v169
	v_mul_f32_e32 v68, v85, v80
	v_mul_f32_e32 v80, v69, v169
	v_mul_f32_e32 v69, v86, v182
	v_mul_f32_e32 v83, v188, v70
	v_mul_f32_e32 v70, v87, v182
	v_mul_f32_e32 v84, v71, v188
	v_mul_f32_e32 v71, v88, v182
	v_mul_f32_e32 v85, v72, v188
	v_mul_f32_e32 v72, v89, v182
	v_mul_f32_e32 v86, v73, v188
	v_mul_f32_e32 v73, v90, v181
	v_mul_f32_e32 v87, v151, v74
	v_mul_f32_e32 v74, v91, v181
	v_mul_f32_e32 v88, v151, v75
	v_mul_f32_e32 v75, v92, v181
	v_mul_f32_e32 v89, v76, v151
	v_mul_f32_e32 v76, v93, v181
	v_mul_f32_e32 v90, v77, v151
	v_mul_f32_e32 v77, v94, v180
	s_cmp_eq_u64 vcc, exec
	v_mul_f32_e32 v91, v187, v183
	v_mul_f32_e32 v92, v95, v180
	v_mul_f32_e32 v93, v187, v184
	v_mul_f32_e32 v94, v96, v180
	v_mul_f32_e32 v95, v187, v186
	v_mul_f32_e32 v96, v97, v180
	v_mul_f32_e32 v97, v187, v185
	s_cselect_b64 s[0:1], -1, 0
	v_cvt_pk_bf16_f32 v66, v78, v66
	v_cvt_pk_bf16_f32 v67, v67, v68
	v_cvt_pk_bf16_f32 v68, v69, v70
	v_cvt_pk_bf16_f32 v69, v71, v72
	v_cvt_pk_bf16_f32 v70, v73, v74
	v_cvt_pk_bf16_f32 v71, v75, v76
	v_cvt_pk_bf16_f32 v72, v77, v92
	v_cvt_pk_bf16_f32 v73, v94, v96
	v_cvt_pk_bf16_f32 v74, v79, v81
	v_cvt_pk_bf16_f32 v75, v82, v80
	v_cvt_pk_bf16_f32 v76, v83, v84
	v_cvt_pk_bf16_f32 v77, v85, v86
	v_cvt_pk_bf16_f32 v78, v87, v88
	v_cvt_pk_bf16_f32 v79, v89, v90
	v_cvt_pk_bf16_f32 v80, v91, v93
	v_cvt_pk_bf16_f32 v81, v95, v97
	s_nop 0
	v_permlane32_swap_b32_e32 v66, v68
	v_permlane32_swap_b32_e32 v67, v69
	v_permlane32_swap_b32_e32 v70, v72
	v_permlane32_swap_b32_e32 v71, v73
	v_permlane32_swap_b32_e32 v74, v76
	v_permlane32_swap_b32_e32 v75, v77
	v_permlane32_swap_b32_e32 v78, v80
	v_permlane32_swap_b32_e32 v79, v81
	v_add_u32_e32 v151, s21, v165
	ds_read_b64_tr_b16 v[82:83], v151 offset:0
	ds_read_b64_tr_b16 v[84:85], v151 offset:0x800
	ds_read_b64_tr_b16 v[86:87], v151 offset:0x1000
	ds_read_b64_tr_b16 v[88:89], v151 offset:0x1800
	ds_read_b64_tr_b16 v[90:91], v151 offset:0x2000
	ds_read_b64_tr_b16 v[92:93], v151 offset:0x2800
	ds_read_b64_tr_b16 v[94:95], v151 offset:0x3000
	ds_read_b64_tr_b16 v[96:97], v151 offset:0x3800
	s_nop 0
	s_waitcnt lgkmcnt(6)
	v_mfma_f32_32x32x16_bf16 v[50:65], v[66:69], v[82:85], v[50:65]
	ds_read_b64_tr_b16 v[82:83], v151 offset:0x200
	ds_read_b64_tr_b16 v[84:85], v151 offset:0xa00
	s_waitcnt lgkmcnt(6)
	v_mfma_f32_32x32x16_bf16 v[50:65], v[70:73], v[86:89], v[50:65]
	ds_read_b64_tr_b16 v[86:87], v151 offset:0x1200
	ds_read_b64_tr_b16 v[88:89], v151 offset:0x1a00
	s_waitcnt lgkmcnt(6)
	v_mfma_f32_32x32x16_bf16 v[50:65], v[74:77], v[90:93], v[50:65]
	ds_read_b64_tr_b16 v[90:91], v151 offset:0x2200
	ds_read_b64_tr_b16 v[92:93], v151 offset:0x2a00
	s_waitcnt lgkmcnt(6)
	v_mfma_f32_32x32x16_bf16 v[50:65], v[78:81], v[94:97], v[50:65]
	ds_read_b64_tr_b16 v[94:95], v151 offset:0x3200
	ds_read_b64_tr_b16 v[96:97], v151 offset:0x3a00
	s_waitcnt lgkmcnt(6)
	v_mfma_f32_32x32x16_bf16 v[34:49], v[66:69], v[82:85], v[34:49]
	ds_read_b64_tr_b16 v[82:83], v151 offset:0x400
	ds_read_b64_tr_b16 v[84:85], v151 offset:0xc00
	s_waitcnt lgkmcnt(6)
	v_mfma_f32_32x32x16_bf16 v[34:49], v[70:73], v[86:89], v[34:49]
	ds_read_b64_tr_b16 v[86:87], v151 offset:0x1400
	ds_read_b64_tr_b16 v[88:89], v151 offset:0x1c00
	s_waitcnt lgkmcnt(6)
	v_mfma_f32_32x32x16_bf16 v[34:49], v[74:77], v[90:93], v[34:49]
	ds_read_b64_tr_b16 v[90:91], v151 offset:0x2400
	ds_read_b64_tr_b16 v[92:93], v151 offset:0x2c00
	s_waitcnt lgkmcnt(6)
	v_mfma_f32_32x32x16_bf16 v[34:49], v[78:81], v[94:97], v[34:49]
	ds_read_b64_tr_b16 v[94:95], v151 offset:0x3400
	ds_read_b64_tr_b16 v[96:97], v151 offset:0x3c00
	s_waitcnt lgkmcnt(6)
	v_mfma_f32_32x32x16_bf16 v[18:33], v[66:69], v[82:85], v[18:33]
	ds_read_b64_tr_b16 v[82:83], v151 offset:0x600
	ds_read_b64_tr_b16 v[84:85], v151 offset:0xe00
	s_waitcnt lgkmcnt(6)
	v_mfma_f32_32x32x16_bf16 v[18:33], v[70:73], v[86:89], v[18:33]
	ds_read_b64_tr_b16 v[86:87], v151 offset:0x1600
	ds_read_b64_tr_b16 v[88:89], v151 offset:0x1e00
	s_waitcnt lgkmcnt(6)
	v_mfma_f32_32x32x16_bf16 v[18:33], v[74:77], v[90:93], v[18:33]
	ds_read_b64_tr_b16 v[90:91], v151 offset:0x2600
	ds_read_b64_tr_b16 v[92:93], v151 offset:0x2e00
	s_waitcnt lgkmcnt(6)
	v_mfma_f32_32x32x16_bf16 v[18:33], v[78:81], v[94:97], v[18:33]
	ds_read_b64_tr_b16 v[94:95], v151 offset:0x3600
	ds_read_b64_tr_b16 v[96:97], v151 offset:0x3e00
	s_waitcnt lgkmcnt(6)
	v_mfma_f32_32x32x16_bf16 v[2:17], v[66:69], v[82:85], v[2:17]
	s_waitcnt lgkmcnt(4)
	v_mfma_f32_32x32x16_bf16 v[2:17], v[70:73], v[86:89], v[2:17]
	s_waitcnt lgkmcnt(2)
	v_mfma_f32_32x32x16_bf16 v[2:17], v[74:77], v[90:93], v[2:17]
	s_waitcnt lgkmcnt(0)
	v_mfma_f32_32x32x16_bf16 v[2:17], v[78:81], v[94:97], v[2:17]

.LBB0_645:
	v_add_u32_e32 v218, s11, v192
	v_add_u32_e32 v81, 1, v218
	v_mad_i64_i32 v[82:83], s[0:1], v81, s33, v[164:165]
	v_add_u32_e32 v86, 33, v218
	v_mad_i64_i32 v[84:85], s[0:1], v86, s33, v[164:165]
	global_load_dwordx4 v[146:149], v[82:83], off
	global_load_dwordx4 v[150:153], v[84:85], off
	v_mad_i64_i32 v[82:83], s[0:1], v81, s33, v[166:167]
	v_mad_i64_i32 v[84:85], s[0:1], v86, s33, v[166:167]
	global_load_dwordx4 v[154:157], v[82:83], off
	global_load_dwordx4 v[158:161], v[84:85], off
	ds_read_b128 v[228:231], v191 offset:49152
	ds_read_b128 v[232:235], v190 offset:49152
	ds_read_b128 v[236:239], v191 offset:57344
	ds_read_b128 v[248:251], v190 offset:57344
	ds_read_b128 v[252:255], v189 offset:49152
	s_waitcnt lgkmcnt(4)
	v_mfma_f32_32x32x16_bf16 v[98:113], v[228:231], v[142:145], 0
	ds_read_b128 v[228:231], v189 offset:57344
	s_waitcnt lgkmcnt(4)
	v_mfma_f32_32x32x16_bf16 v[98:113], v[232:235], v[138:141], v[98:113]
	ds_read_b128 v[232:235], v188 offset:49152
	s_waitcnt lgkmcnt(4)
	v_mfma_f32_32x32x16_bf16 v[82:97], v[236:239], v[142:145], 0
	ds_read_b128 v[236:239], v188 offset:57344
	s_waitcnt lgkmcnt(4)
	v_mfma_f32_32x32x16_bf16 v[82:97], v[248:251], v[138:141], v[82:97]
	ds_read_b128 v[248:251], v191 offset:49280
	s_waitcnt lgkmcnt(4)
	v_mfma_f32_32x32x16_bf16 v[98:113], v[252:255], v[134:137], v[98:113]
	ds_read_b128 v[252:255], v191 offset:57472
	s_waitcnt lgkmcnt(4)
	v_mfma_f32_32x32x16_bf16 v[82:97], v[228:231], v[134:137], v[82:97]
	ds_read_b128 v[228:231], v190 offset:49280
	s_waitcnt lgkmcnt(4)
	v_mfma_f32_32x32x16_bf16 v[98:113], v[232:235], v[130:133], v[98:113]
	ds_read_b128 v[232:235], v190 offset:57472
	s_waitcnt lgkmcnt(4)
	v_mfma_f32_32x32x16_bf16 v[82:97], v[236:239], v[130:133], v[82:97]
	ds_read_b128 v[236:239], v189 offset:49280
	s_waitcnt lgkmcnt(4)
	v_mfma_f32_32x32x16_bf16 v[98:113], v[248:251], v[126:129], v[98:113]
	ds_read_b128 v[248:251], v189 offset:57472
	s_waitcnt lgkmcnt(4)
	v_mfma_f32_32x32x16_bf16 v[82:97], v[252:255], v[126:129], v[82:97]
	ds_read_b128 v[252:255], v188 offset:49280
	s_waitcnt lgkmcnt(4)
	v_mfma_f32_32x32x16_bf16 v[98:113], v[228:231], v[122:125], v[98:113]
	ds_read_b128 v[228:231], v188 offset:57472
	s_waitcnt lgkmcnt(4)
	v_mfma_f32_32x32x16_bf16 v[82:97], v[232:235], v[122:125], v[82:97]
	s_waitcnt lgkmcnt(3)
	v_mfma_f32_32x32x16_bf16 v[98:113], v[236:239], v[118:121], v[98:113]
	s_waitcnt lgkmcnt(2)
	v_mfma_f32_32x32x16_bf16 v[82:97], v[248:251], v[118:121], v[82:97]
	s_waitcnt lgkmcnt(1)
	v_mfma_f32_32x32x16_bf16 v[98:113], v[252:255], v[114:117], v[98:113]
	s_waitcnt lgkmcnt(0)
	v_mfma_f32_32x32x16_bf16 v[82:97], v[228:231], v[114:117], v[82:97]
	v_exp_f32_e32 v226, v66
	v_add_f32_e32 v66, 0, v215
	v_add_f32_e32 v66, v217, v66
	v_add_f32_e32 v66, v213, v66
	v_add_f32_e32 v66, v216, v66
	v_add_f32_e32 v66, v211, v66
	v_add_f32_e32 v66, v214, v66
	v_add_f32_e32 v66, v210, v66
	v_add_f32_e32 v66, v212, v66
	v_add_f32_e32 v66, v207, v66
	v_add_f32_e32 v66, v209, v66
	v_add_f32_e32 v66, v205, v66
	v_add_f32_e32 v66, v208, v66
	v_exp_f32_e32 v80, v80
	v_add_f32_e32 v66, v203, v66
	v_exp_f32_e32 v1, v1
	v_add_f32_e32 v66, v206, v66
	v_exp_f32_e32 v78, v78
	v_add_f32_e32 v66, v202, v66
	v_exp_f32_e32 v79, v79
	v_add_f32_e32 v66, v204, v66
	v_exp_f32_e32 v76, v76
	v_add_f32_e32 v66, v80, v66
	v_exp_f32_e32 v77, v77
	v_add_f32_e32 v66, v1, v66
	v_exp_f32_e32 v81, v74
	v_add_f32_e32 v66, v78, v66
	v_exp_f32_e32 v219, v75
	v_add_f32_e32 v66, v79, v66
	v_exp_f32_e32 v220, v72
	v_add_f32_e32 v66, v76, v66
	v_exp_f32_e32 v221, v73
	v_add_f32_e32 v66, v77, v66
	v_exp_f32_e32 v222, v70
	v_add_f32_e32 v66, v81, v66
	v_exp_f32_e32 v223, v71
	v_add_f32_e32 v66, v219, v66
	v_exp_f32_e32 v224, v68
	v_add_f32_e32 v66, v220, v66
	v_exp_f32_e32 v225, v69
	v_add_f32_e32 v66, v221, v66
	v_add_f32_e32 v66, v222, v66
	v_exp_f32_e32 v227, v67
	v_add_f32_e32 v66, v223, v66
	v_add_f32_e32 v66, v224, v66
	v_add_f32_e32 v66, v225, v66
	v_add_f32_e32 v66, v226, v66
	v_add_f32_e32 v200, v227, v66
	v_mov_b32_e32 v201, v200
	v_cvt_pk_bf16_f32 v66, v215, v217
	v_cvt_pk_bf16_f32 v67, v213, v216
	v_cvt_pk_bf16_f32 v68, v211, v214
	v_cvt_pk_bf16_f32 v69, v210, v212
	v_cvt_pk_bf16_f32 v70, v207, v209
	v_cvt_pk_bf16_f32 v71, v205, v208
	v_cvt_pk_bf16_f32 v72, v203, v206
	v_cvt_pk_bf16_f32 v73, v202, v204
	v_cvt_pk_bf16_f32 v74, v80, v1
	v_cvt_pk_bf16_f32 v75, v78, v79
	v_cvt_pk_bf16_f32 v76, v76, v77
	v_cvt_pk_bf16_f32 v77, v81, v219
	v_cvt_pk_bf16_f32 v78, v220, v221
	v_cvt_pk_bf16_f32 v79, v222, v223
	v_cvt_pk_bf16_f32 v80, v224, v225
	v_cvt_pk_bf16_f32 v81, v226, v227
	s_nop 1
	v_permlane32_swap_b32_e32 v200, v201
	v_permlane32_swap_b32_e32 v66, v68
	v_permlane32_swap_b32_e32 v67, v69
	v_permlane32_swap_b32_e32 v70, v72
	v_permlane32_swap_b32_e32 v71, v73
	v_permlane32_swap_b32_e32 v74, v76
	v_permlane32_swap_b32_e32 v75, v77
	v_permlane32_swap_b32_e32 v78, v80
	v_permlane32_swap_b32_e32 v79, v81
	ds_read_b64_tr_b16 v[202:203], v183 offset:0
	ds_read_b64_tr_b16 v[204:205], v183 offset:0x800
	ds_read_b64_tr_b16 v[206:207], v183 offset:0x1000
	ds_read_b64_tr_b16 v[208:209], v183 offset:0x1800
	ds_read_b64_tr_b16 v[210:211], v183 offset:0x2000
	ds_read_b64_tr_b16 v[212:213], v183 offset:0x2800
	ds_read_b64_tr_b16 v[214:215], v183 offset:0x3000
	ds_read_b64_tr_b16 v[216:217], v183 offset:0x3800
	s_nop 0
	s_waitcnt lgkmcnt(6)
	v_mfma_f32_32x32x16_bf16 v[50:65], v[66:69], v[202:205], v[50:65]
	ds_read_b64_tr_b16 v[202:203], v183 offset:0x200
	ds_read_b64_tr_b16 v[204:205], v183 offset:0xa00
	s_waitcnt lgkmcnt(6)
	v_mfma_f32_32x32x16_bf16 v[50:65], v[70:73], v[206:209], v[50:65]
	ds_read_b64_tr_b16 v[206:207], v183 offset:0x1200
	ds_read_b64_tr_b16 v[208:209], v183 offset:0x1a00
	s_waitcnt lgkmcnt(6)
	v_mfma_f32_32x32x16_bf16 v[50:65], v[74:77], v[210:213], v[50:65]
	ds_read_b64_tr_b16 v[210:211], v183 offset:0x2200
	ds_read_b64_tr_b16 v[212:213], v183 offset:0x2a00
	s_waitcnt lgkmcnt(6)
	v_mfma_f32_32x32x16_bf16 v[50:65], v[78:81], v[214:217], v[50:65]
	ds_read_b64_tr_b16 v[214:215], v183 offset:0x3200
	ds_read_b64_tr_b16 v[216:217], v183 offset:0x3a00
	s_waitcnt lgkmcnt(6)
	v_mfma_f32_32x32x16_bf16 v[34:49], v[66:69], v[202:205], v[34:49]
	ds_read_b64_tr_b16 v[202:203], v183 offset:0x400
	ds_read_b64_tr_b16 v[204:205], v183 offset:0xc00
	s_waitcnt lgkmcnt(6)
	v_mfma_f32_32x32x16_bf16 v[34:49], v[70:73], v[206:209], v[34:49]
	ds_read_b64_tr_b16 v[206:207], v183 offset:0x1400
	ds_read_b64_tr_b16 v[208:209], v183 offset:0x1c00
	s_waitcnt lgkmcnt(6)
	v_mfma_f32_32x32x16_bf16 v[34:49], v[74:77], v[210:213], v[34:49]
	ds_read_b64_tr_b16 v[210:211], v183 offset:0x2400
	ds_read_b64_tr_b16 v[212:213], v183 offset:0x2c00
	s_waitcnt lgkmcnt(6)
	v_mfma_f32_32x32x16_bf16 v[34:49], v[78:81], v[214:217], v[34:49]
	ds_read_b64_tr_b16 v[214:215], v183 offset:0x3400
	ds_read_b64_tr_b16 v[216:217], v183 offset:0x3c00
	s_waitcnt lgkmcnt(6)
	v_mfma_f32_32x32x16_bf16 v[18:33], v[66:69], v[202:205], v[18:33]
	ds_read_b64_tr_b16 v[202:203], v183 offset:0x600
	ds_read_b64_tr_b16 v[204:205], v183 offset:0xe00
	s_waitcnt lgkmcnt(6)
	v_mfma_f32_32x32x16_bf16 v[18:33], v[70:73], v[206:209], v[18:33]
	ds_read_b64_tr_b16 v[206:207], v183 offset:0x1600
	ds_read_b64_tr_b16 v[208:209], v183 offset:0x1e00
	s_waitcnt lgkmcnt(6)
	v_mfma_f32_32x32x16_bf16 v[18:33], v[74:77], v[210:213], v[18:33]
	ds_read_b64_tr_b16 v[210:211], v183 offset:0x2600
	ds_read_b64_tr_b16 v[212:213], v183 offset:0x2e00
	s_waitcnt lgkmcnt(6)
	v_mfma_f32_32x32x16_bf16 v[18:33], v[78:81], v[214:217], v[18:33]
	ds_read_b64_tr_b16 v[214:215], v183 offset:0x3600
	ds_read_b64_tr_b16 v[216:217], v183 offset:0x3e00
	s_waitcnt lgkmcnt(6)
	v_mfma_f32_32x32x16_bf16 v[2:17], v[66:69], v[202:205], v[2:17]
	s_waitcnt lgkmcnt(4)
	v_mfma_f32_32x32x16_bf16 v[2:17], v[70:73], v[206:209], v[2:17]
	s_waitcnt lgkmcnt(2)
	v_mfma_f32_32x32x16_bf16 v[2:17], v[74:77], v[210:213], v[2:17]
	s_waitcnt lgkmcnt(0)
	v_mfma_f32_32x32x16_bf16 v[2:17], v[78:81], v[214:217], v[2:17]
	ds_read_b128 v[66:69], v198
	ds_read_b128 v[70:73], v198 offset:32
	ds_read_b128 v[202:205], v198 offset:128
	ds_read_b128 v[206:209], v198 offset:160
	ds_read_b128 v[76:79], v198 offset:64
	ds_read_b128 v[210:213], v198 offset:96
	ds_read_b128 v[214:217], v198 offset:192
	ds_read_b128 v[220:223], v198 offset:224
	s_waitcnt lgkmcnt(7)
	v_xor_b32_e32 v69, 0x80000000, v69
	s_waitcnt lgkmcnt(3)
	v_xor_b32_e32 v225, 0x80000000, v79
	v_xor_b32_e32 v224, 0x80000000, v78
	v_xor_b32_e32 v68, 0x80000000, v68
	v_xor_b32_e32 v73, 0x80000000, v73
	v_xor_b32_e32 v72, 0x80000000, v72
	s_waitcnt lgkmcnt(2)
	v_xor_b32_e32 v81, 0x80000000, v213
	v_xor_b32_e32 v80, 0x80000000, v212
	v_pk_fma_f32 v[74:75], v[110:111], s[12:13], v[210:211] op_sel_hi:[1,0,1] neg_lo:[0,0,1] neg_hi:[0,0,1]
	v_pk_fma_f32 v[78:79], v[106:107], s[12:13], v[76:77] op_sel_hi:[1,0,1] neg_lo:[0,0,1] neg_hi:[0,0,1]
	v_pk_fma_f32 v[102:103], v[102:103], s[12:13], v[70:71] op_sel_hi:[1,0,1] neg_lo:[0,0,1] neg_hi:[0,0,1]
	v_pk_fma_f32 v[106:107], v[108:109], s[12:13], v[224:225] op_sel_hi:[1,0,1]
	v_xor_b32_e32 v109, 0x80000000, v205
	v_xor_b32_e32 v108, 0x80000000, v204
	v_xor_b32_e32 v111, 0x80000000, v209
	v_xor_b32_e32 v110, 0x80000000, v208
	s_waitcnt lgkmcnt(1)
	v_xor_b32_e32 v77, 0x80000000, v217
	v_xor_b32_e32 v76, 0x80000000, v216
	s_waitcnt lgkmcnt(0)
	v_xor_b32_e32 v71, 0x80000000, v223
	v_xor_b32_e32 v70, 0x80000000, v222
	v_pk_fma_f32 v[80:81], v[112:113], s[12:13], v[80:81] op_sel_hi:[1,0,1]
	v_pk_fma_f32 v[104:105], v[104:105], s[12:13], v[72:73] op_sel_hi:[1,0,1]
	v_pk_fma_f32 v[100:101], v[100:101], s[12:13], v[68:69] op_sel_hi:[1,0,1]
	v_pk_fma_f32 v[98:99], v[98:99], s[12:13], v[66:67] op_sel_hi:[1,0,1] neg_lo:[0,0,1] neg_hi:[0,0,1]
	v_pk_fma_f32 v[66:67], v[94:95], s[12:13], v[220:221] op_sel_hi:[1,0,1] neg_lo:[0,0,1] neg_hi:[0,0,1]
	v_pk_fma_f32 v[68:69], v[90:91], s[12:13], v[214:215] op_sel_hi:[1,0,1] neg_lo:[0,0,1] neg_hi:[0,0,1]
	v_pk_fma_f32 v[72:73], v[86:87], s[12:13], v[206:207] op_sel_hi:[1,0,1] neg_lo:[0,0,1] neg_hi:[0,0,1]
	v_pk_fma_f32 v[70:71], v[96:97], s[12:13], v[70:71] op_sel_hi:[1,0,1]
	v_pk_fma_f32 v[76:77], v[92:93], s[12:13], v[76:77] op_sel_hi:[1,0,1]
	v_pk_fma_f32 v[86:87], v[88:89], s[12:13], v[110:111] op_sel_hi:[1,0,1]
	v_pk_fma_f32 v[84:85], v[84:85], s[12:13], v[108:109] op_sel_hi:[1,0,1]
	s_cmp_le_i32 s11, s27
	v_pk_fma_f32 v[82:83], v[82:83], s[12:13], v[202:203] op_sel_hi:[1,0,1] neg_lo:[0,0,1] neg_hi:[0,0,1]
	s_cbranch_scc1 .LBB0_647
	v_add_u32_e32 v1, 64, v199
	v_cmp_gt_i32_e64 s[92:93], 26, v1
	v_cmp_gt_i32_e64 s[94:95], 27, v1
	v_cmp_gt_i32_e64 s[90:91], 25, v1
	s_and_b64 s[92:93], s[94:95], s[92:93]
	v_cmp_gt_i32_e64 s[88:89], 24, v1
	s_and_b64 s[90:91], s[92:93], s[90:91]
	v_cmp_gt_i32_e64 s[86:87], 19, v1
	s_and_b64 s[88:89], s[90:91], s[88:89]
	v_cmp_gt_i32_e64 s[84:85], 18, v1
	s_and_b64 s[86:87], s[88:89], s[86:87]
	v_cmp_gt_i32_e64 s[82:83], 17, v1
	s_and_b64 s[84:85], s[86:87], s[84:85]
	v_cmp_gt_i32_e64 s[80:81], 16, v1
	s_and_b64 s[82:83], s[84:85], s[82:83]
	v_cmp_gt_i32_e64 s[78:79], 11, v1
	s_and_b64 s[80:81], s[82:83], s[80:81]
	v_cmp_gt_i32_e64 s[76:77], 10, v1
	s_and_b64 s[78:79], s[80:81], s[78:79]
	v_cmp_gt_i32_e64 s[74:75], 9, v1
	s_and_b64 s[76:77], s[78:79], s[76:77]
	v_cmp_gt_i32_e64 s[72:73], 8, v1
	s_and_b64 s[74:75], s[76:77], s[74:75]
	v_cmp_gt_i32_e64 s[70:71], 3, v1
	s_and_b64 s[72:73], s[74:75], s[72:73]
	v_cmp_gt_i32_e64 s[68:69], 2, v1
	s_and_b64 s[70:71], s[72:73], s[70:71]
	v_cmp_gt_i32_e64 s[2:3], 1, v1
	s_and_b64 s[68:69], s[70:71], s[68:69]
	v_cmp_gt_i32_e64 s[0:1], 0, v1
	s_and_b64 s[2:3], s[68:69], s[2:3]
	s_and_b64 s[0:1], s[2:3], s[0:1]
	v_cmp_gt_i32_e64 s[66:67], 58, v1
	v_cndmask_b32_e64 v98, v98, v175, s[0:1]
	v_cmp_gt_i32_e64 s[0:1], 59, v1
	v_cmp_gt_i32_e64 s[64:65], 57, v1
	v_cmp_gt_i32_e64 s[62:63], 56, v1
	v_cndmask_b32_e64 v71, v71, v175, s[0:1]
	s_and_b64 s[0:1], s[0:1], s[66:67]
	v_cndmask_b32_e64 v70, v70, v175, s[0:1]
	s_and_b64 s[0:1], s[0:1], s[64:65]
	v_cmp_gt_i32_e64 s[60:61], 51, v1
	v_cndmask_b32_e64 v67, v67, v175, s[0:1]
	s_and_b64 s[0:1], s[0:1], s[62:63]
	v_cmp_gt_i32_e64 s[58:59], 50, v1
	v_cndmask_b32_e64 v66, v66, v175, s[0:1]
	s_and_b64 s[0:1], s[0:1], s[60:61]
	v_cmp_gt_i32_e64 s[56:57], 49, v1
	v_cndmask_b32_e64 v77, v77, v175, s[0:1]
	s_and_b64 s[0:1], s[0:1], s[58:59]
	v_cmp_gt_i32_e64 s[54:55], 48, v1
	v_cndmask_b32_e64 v76, v76, v175, s[0:1]
	s_and_b64 s[0:1], s[0:1], s[56:57]
	v_cmp_gt_i32_e64 s[52:53], 43, v1
	v_cndmask_b32_e64 v69, v69, v175, s[0:1]
	s_and_b64 s[0:1], s[0:1], s[54:55]
	v_cmp_gt_i32_e64 s[50:51], 42, v1
	v_cndmask_b32_e64 v68, v68, v175, s[0:1]
	s_and_b64 s[0:1], s[0:1], s[52:53]
	v_cmp_gt_i32_e64 s[48:49], 41, v1
	v_cndmask_b32_e64 v87, v87, v175, s[0:1]
	s_and_b64 s[0:1], s[0:1], s[50:51]
	v_cmp_gt_i32_e64 s[46:47], 40, v1
	v_cndmask_b32_e64 v86, v86, v175, s[0:1]
	s_and_b64 s[0:1], s[0:1], s[48:49]
	v_cmp_gt_i32_e64 s[44:45], 35, v1
	v_cndmask_b32_e64 v73, v73, v175, s[0:1]
	s_and_b64 s[0:1], s[0:1], s[46:47]
	v_cmp_gt_i32_e64 s[42:43], 34, v1
	v_cndmask_b32_e64 v72, v72, v175, s[0:1]
	s_and_b64 s[0:1], s[0:1], s[44:45]
	v_cmp_gt_i32_e64 s[40:41], 33, v1
	v_cndmask_b32_e64 v85, v85, v175, s[0:1]
	s_and_b64 s[0:1], s[0:1], s[42:43]
	v_cmp_gt_i32_e32 vcc, 32, v1
	v_cndmask_b32_e64 v84, v84, v175, s[0:1]
	s_and_b64 s[0:1], s[0:1], s[40:41]
	v_cndmask_b32_e64 v74, v74, v175, s[88:89]
	v_readlane_b32 s88, v242, 2
	s_and_b64 vcc, s[0:1], vcc
	v_cndmask_b32_e64 v81, v81, v175, s[94:95]
	v_cndmask_b32_e64 v80, v80, v175, s[92:93]
	s_movk_i32 s93, 0x6018
	s_mov_b32 s92, 0xf800000
	v_cndmask_b32_e64 v75, v75, v175, s[90:91]
	s_mov_b64 s[90:91], s[16:17]
	v_readlane_b32 s89, v242, 3
	v_cndmask_b32_e64 v107, v107, v175, s[86:87]
	v_readlane_b32 s86, v242, 0
	v_cndmask_b32_e64 v106, v106, v175, s[84:85]
	v_cndmask_b32_e64 v79, v79, v175, s[82:83]
	s_movk_i32 s83, 0x6000
	v_cndmask_b32_e64 v78, v78, v175, s[80:81]
	v_cndmask_b32_e64 v105, v105, v175, s[78:79]
	v_cndmask_b32_e64 v104, v104, v175, s[76:77]
	v_cndmask_b32_e64 v103, v103, v175, s[74:75]
	v_cndmask_b32_e64 v102, v102, v175, s[72:73]
	v_cndmask_b32_e64 v101, v101, v175, s[70:71]
	v_cndmask_b32_e64 v100, v100, v175, s[68:69]
	v_cndmask_b32_e64 v99, v99, v175, s[2:3]
	s_mov_b32 s56, s30
	v_cndmask_b32_e64 v83, v83, v175, s[0:1]
	v_cndmask_b32_e32 v82, v82, v175, vcc
	v_readlane_b32 s87, v242, 1

.LBB0_653:
	v_sub_f32_e32 v104, v82, v1
	v_sub_f32_e32 v105, v83, v1
	v_sub_f32_e32 v208, v84, v1
	v_sub_f32_e32 v209, v85, v1
	v_sub_f32_e32 v210, v72, v1
	v_sub_f32_e32 v211, v73, v1
	v_sub_f32_e32 v212, v86, v1
	v_sub_f32_e32 v213, v87, v1
	v_sub_f32_e32 v214, v68, v1
	v_sub_f32_e32 v215, v69, v1
	v_sub_f32_e32 v216, v76, v1
	v_sub_f32_e32 v217, v77, v1
	v_sub_f32_e32 v218, v66, v1
	v_sub_f32_e32 v219, v67, v1
	v_sub_f32_e32 v220, v70, v1
	v_sub_f32_e32 v221, v71, v1
	ds_read_b128 v[228:231], v191 offset:32768
	ds_read_b128 v[232:235], v190 offset:32768
	ds_read_b128 v[236:239], v191 offset:40960
	ds_read_b128 v[248:251], v190 offset:40960
	ds_read_b128 v[252:255], v189 offset:32768
	s_waitcnt lgkmcnt(4)
	v_mfma_f32_32x32x16_bf16 v[82:97], v[228:231], v[142:145], 0
	ds_read_b128 v[228:231], v189 offset:40960
	s_waitcnt lgkmcnt(4)
	v_mfma_f32_32x32x16_bf16 v[82:97], v[232:235], v[138:141], v[82:97]
	ds_read_b128 v[232:235], v188 offset:32768
	s_waitcnt lgkmcnt(4)
	v_mfma_f32_32x32x16_bf16 v[66:81], v[236:239], v[142:145], 0
	ds_read_b128 v[236:239], v188 offset:40960
	s_waitcnt lgkmcnt(4)
	v_mfma_f32_32x32x16_bf16 v[66:81], v[248:251], v[138:141], v[66:81]
	ds_read_b128 v[248:251], v191 offset:32896
	s_waitcnt lgkmcnt(4)
	v_mfma_f32_32x32x16_bf16 v[82:97], v[252:255], v[134:137], v[82:97]
	ds_read_b128 v[252:255], v191 offset:41088
	s_waitcnt lgkmcnt(4)
	v_mfma_f32_32x32x16_bf16 v[66:81], v[228:231], v[134:137], v[66:81]
	ds_read_b128 v[228:231], v190 offset:32896
	s_waitcnt lgkmcnt(4)
	v_mfma_f32_32x32x16_bf16 v[82:97], v[232:235], v[130:133], v[82:97]
	ds_read_b128 v[232:235], v190 offset:41088
	s_waitcnt lgkmcnt(4)
	v_mfma_f32_32x32x16_bf16 v[66:81], v[236:239], v[130:133], v[66:81]
	ds_read_b128 v[236:239], v189 offset:32896
	s_waitcnt lgkmcnt(4)
	v_mfma_f32_32x32x16_bf16 v[82:97], v[248:251], v[126:129], v[82:97]
	ds_read_b128 v[248:251], v189 offset:41088
	s_waitcnt lgkmcnt(4)
	v_mfma_f32_32x32x16_bf16 v[66:81], v[252:255], v[126:129], v[66:81]
	ds_read_b128 v[252:255], v188 offset:32896
	s_waitcnt lgkmcnt(4)
	v_mfma_f32_32x32x16_bf16 v[82:97], v[228:231], v[122:125], v[82:97]
	ds_read_b128 v[228:231], v188 offset:41088
	s_waitcnt lgkmcnt(4)
	v_mfma_f32_32x32x16_bf16 v[66:81], v[232:235], v[122:125], v[66:81]
	s_waitcnt lgkmcnt(3)
	v_mfma_f32_32x32x16_bf16 v[82:97], v[236:239], v[118:121], v[82:97]
	s_waitcnt lgkmcnt(2)
	v_mfma_f32_32x32x16_bf16 v[66:81], v[248:251], v[118:121], v[66:81]
	s_waitcnt lgkmcnt(1)
	v_mfma_f32_32x32x16_bf16 v[82:97], v[252:255], v[114:117], v[82:97]
	s_waitcnt lgkmcnt(0)
	v_mfma_f32_32x32x16_bf16 v[66:81], v[228:231], v[114:117], v[66:81]
	v_exp_f32_e32 v222, v104
	v_add_f32_e32 v104, 0, v196
	v_add_f32_e32 v104, v203, v104
	v_add_f32_e32 v104, v112, v104
	v_add_f32_e32 v104, v202, v104
	v_add_f32_e32 v104, v110, v104
	v_add_f32_e32 v104, v113, v104
	v_add_f32_e32 v104, v109, v104
	v_add_f32_e32 v104, v111, v104
	v_add_f32_e32 v104, v103, v104
	v_add_f32_e32 v104, v107, v104
	v_add_f32_e32 v104, v101, v104
	v_add_f32_e32 v104, v106, v104
	v_add_f32_e32 v104, v99, v104
	v_exp_f32_e32 v223, v105
	v_add_f32_e32 v104, v102, v104
	v_exp_f32_e32 v208, v208
	v_add_f32_e32 v104, v98, v104
	v_exp_f32_e32 v209, v209
	v_add_f32_e32 v104, v100, v104
	v_exp_f32_e32 v210, v210
	v_add_f32_e32 v104, v222, v104
	v_exp_f32_e32 v211, v211
	v_add_f32_e32 v104, v223, v104
	v_exp_f32_e32 v212, v212
	v_add_f32_e32 v104, v208, v104
	v_exp_f32_e32 v213, v213
	v_add_f32_e32 v104, v209, v104
	v_exp_f32_e32 v214, v214
	v_add_f32_e32 v104, v210, v104
	v_exp_f32_e32 v215, v215
	v_add_f32_e32 v104, v211, v104
	v_exp_f32_e32 v216, v216
	v_add_f32_e32 v104, v212, v104
	v_exp_f32_e32 v217, v217
	v_add_f32_e32 v104, v213, v104
	v_exp_f32_e32 v218, v218
	v_add_f32_e32 v104, v214, v104
	v_exp_f32_e32 v219, v219
	v_add_f32_e32 v104, v215, v104
	v_exp_f32_e32 v220, v220
	v_add_f32_e32 v104, v216, v104
	v_exp_f32_e32 v221, v221
	v_add_f32_e32 v104, v217, v104
	v_add_f32_e32 v104, v218, v104
	v_add_f32_e32 v104, v219, v104
	v_add_f32_e32 v104, v220, v104
	v_add_f32_e32 v104, v221, v104
	v_mov_b32_e32 v105, v104
	v_cvt_pk_bf16_f32 v204, v196, v203
	v_cvt_pk_bf16_f32 v205, v112, v202
	v_cvt_pk_bf16_f32 v206, v110, v113
	v_cvt_pk_bf16_f32 v207, v109, v111
	v_cvt_pk_bf16_f32 v110, v103, v107
	v_cvt_pk_bf16_f32 v111, v101, v106
	v_cvt_pk_bf16_f32 v112, v99, v102
	v_cvt_pk_bf16_f32 v113, v98, v100
	v_cvt_pk_bf16_f32 v98, v222, v223
	v_cvt_pk_bf16_f32 v99, v208, v209
	v_cvt_pk_bf16_f32 v100, v210, v211
	v_cvt_pk_bf16_f32 v101, v212, v213
	s_nop 1
	v_permlane32_swap_b32_e32 v104, v105
	v_permlane32_swap_b32_e32 v98, v100
	v_permlane32_swap_b32_e32 v99, v101
	v_cvt_pk_bf16_f32 v208, v214, v215
	v_cvt_pk_bf16_f32 v209, v216, v217
	v_cvt_pk_bf16_f32 v210, v218, v219
	v_cvt_pk_bf16_f32 v211, v220, v221
	v_permlane32_swap_b32_e32 v204, v206
	v_permlane32_swap_b32_e32 v205, v207
	v_permlane32_swap_b32_e32 v110, v112
	v_permlane32_swap_b32_e32 v111, v113
	v_permlane32_swap_b32_e32 v208, v210
	v_permlane32_swap_b32_e32 v209, v211
	ds_read_b64_tr_b16 v[212:213], v183 offset:0x4000
	ds_read_b64_tr_b16 v[214:215], v183 offset:0x4800
	ds_read_b64_tr_b16 v[216:217], v183 offset:0x5000
	ds_read_b64_tr_b16 v[218:219], v183 offset:0x5800
	ds_read_b64_tr_b16 v[220:221], v183 offset:0x6000
	ds_read_b64_tr_b16 v[222:223], v183 offset:0x6800
	ds_read_b64_tr_b16 v[224:225], v183 offset:0x7000
	ds_read_b64_tr_b16 v[226:227], v183 offset:0x7800
	s_nop 0
	s_waitcnt lgkmcnt(6)
	v_mfma_f32_32x32x16_bf16 v[50:65], v[204:207], v[212:215], v[50:65]
	ds_read_b64_tr_b16 v[212:213], v183 offset:0x4200
	ds_read_b64_tr_b16 v[214:215], v183 offset:0x4a00
	s_waitcnt lgkmcnt(6)
	v_mfma_f32_32x32x16_bf16 v[50:65], v[110:113], v[216:219], v[50:65]
	ds_read_b64_tr_b16 v[216:217], v183 offset:0x5200
	ds_read_b64_tr_b16 v[218:219], v183 offset:0x5a00
	s_waitcnt lgkmcnt(6)
	v_mfma_f32_32x32x16_bf16 v[50:65], v[98:101], v[220:223], v[50:65]
	ds_read_b64_tr_b16 v[220:221], v183 offset:0x6200
	ds_read_b64_tr_b16 v[222:223], v183 offset:0x6a00
	s_waitcnt lgkmcnt(6)
	v_mfma_f32_32x32x16_bf16 v[50:65], v[208:211], v[224:227], v[50:65]
	ds_read_b64_tr_b16 v[224:225], v183 offset:0x7200
	ds_read_b64_tr_b16 v[226:227], v183 offset:0x7a00
	s_waitcnt lgkmcnt(6)
	v_mfma_f32_32x32x16_bf16 v[34:49], v[204:207], v[212:215], v[34:49]
	ds_read_b64_tr_b16 v[212:213], v183 offset:0x4400
	ds_read_b64_tr_b16 v[214:215], v183 offset:0x4c00
	s_waitcnt lgkmcnt(6)
	v_mfma_f32_32x32x16_bf16 v[34:49], v[110:113], v[216:219], v[34:49]
	ds_read_b64_tr_b16 v[216:217], v183 offset:0x5400
	ds_read_b64_tr_b16 v[218:219], v183 offset:0x5c00
	s_waitcnt lgkmcnt(6)
	v_mfma_f32_32x32x16_bf16 v[34:49], v[98:101], v[220:223], v[34:49]
	ds_read_b64_tr_b16 v[220:221], v183 offset:0x6400
	ds_read_b64_tr_b16 v[222:223], v183 offset:0x6c00
	s_waitcnt lgkmcnt(6)
	v_mfma_f32_32x32x16_bf16 v[34:49], v[208:211], v[224:227], v[34:49]
	ds_read_b64_tr_b16 v[224:225], v183 offset:0x7400
	ds_read_b64_tr_b16 v[226:227], v183 offset:0x7c00
	s_waitcnt lgkmcnt(6)
	v_mfma_f32_32x32x16_bf16 v[18:33], v[204:207], v[212:215], v[18:33]
	ds_read_b64_tr_b16 v[212:213], v183 offset:0x4600
	ds_read_b64_tr_b16 v[214:215], v183 offset:0x4e00
	s_waitcnt lgkmcnt(6)
	v_mfma_f32_32x32x16_bf16 v[18:33], v[110:113], v[216:219], v[18:33]
	ds_read_b64_tr_b16 v[216:217], v183 offset:0x5600
	ds_read_b64_tr_b16 v[218:219], v183 offset:0x5e00
	s_waitcnt lgkmcnt(6)
	v_mfma_f32_32x32x16_bf16 v[18:33], v[98:101], v[220:223], v[18:33]
	ds_read_b64_tr_b16 v[220:221], v183 offset:0x6600
	ds_read_b64_tr_b16 v[222:223], v183 offset:0x6e00
	s_waitcnt lgkmcnt(6)
	v_mfma_f32_32x32x16_bf16 v[18:33], v[208:211], v[224:227], v[18:33]
	ds_read_b64_tr_b16 v[224:225], v183 offset:0x7600
	ds_read_b64_tr_b16 v[226:227], v183 offset:0x7e00
	s_waitcnt lgkmcnt(6)
	v_mfma_f32_32x32x16_bf16 v[2:17], v[204:207], v[212:215], v[2:17]
	s_waitcnt lgkmcnt(4)
	v_mfma_f32_32x32x16_bf16 v[2:17], v[110:113], v[216:219], v[2:17]
	s_waitcnt lgkmcnt(2)
	v_mfma_f32_32x32x16_bf16 v[2:17], v[98:101], v[220:223], v[2:17]
	s_waitcnt lgkmcnt(0)
	v_mfma_f32_32x32x16_bf16 v[2:17], v[208:211], v[224:227], v[2:17]
	ds_read_b128 v[100:103], v198 offset:256
	ds_read_b128 v[110:113], v198 offset:288
	ds_read_b128 v[202:205], v198 offset:384
	ds_read_b128 v[206:209], v198 offset:416
	ds_read_b128 v[210:213], v198 offset:320
	ds_read_b128 v[214:217], v198 offset:352
	ds_read_b128 v[218:221], v198 offset:448
	ds_read_b128 v[222:225], v198 offset:480
	s_waitcnt lgkmcnt(7)
	v_xor_b32_e32 v103, 0x80000000, v103
	v_xor_b32_e32 v102, 0x80000000, v102
	s_waitcnt lgkmcnt(6)
	v_xor_b32_e32 v107, 0x80000000, v113
	v_xor_b32_e32 v106, 0x80000000, v112
	s_waitcnt lgkmcnt(3)
	v_xor_b32_e32 v113, 0x80000000, v213
	v_xor_b32_e32 v112, 0x80000000, v212
	s_waitcnt lgkmcnt(2)
	v_xor_b32_e32 v213, 0x80000000, v217
	v_xor_b32_e32 v212, 0x80000000, v216
	v_pk_fma_f32 v[98:99], v[86:87], s[12:13], v[110:111] op_sel_hi:[1,0,1] neg_lo:[0,0,1] neg_hi:[0,0,1]
	v_pk_fma_f32 v[86:87], v[96:97], s[12:13], v[212:213] op_sel_hi:[1,0,1]
	v_pk_fma_f32 v[88:89], v[88:89], s[12:13], v[106:107] op_sel_hi:[1,0,1]
	v_pk_fma_f32 v[84:85], v[84:85], s[12:13], v[102:103] op_sel_hi:[1,0,1]
	v_pk_fma_f32 v[96:97], v[82:83], s[12:13], v[100:101] op_sel_hi:[1,0,1] neg_lo:[0,0,1] neg_hi:[0,0,1]
	v_xor_b32_e32 v103, 0x80000000, v205
	v_xor_b32_e32 v102, 0x80000000, v204
	v_xor_b32_e32 v101, 0x80000000, v209
	v_xor_b32_e32 v100, 0x80000000, v208
	s_waitcnt lgkmcnt(1)
	v_xor_b32_e32 v107, 0x80000000, v221
	v_xor_b32_e32 v106, 0x80000000, v220
	s_waitcnt lgkmcnt(0)
	v_xor_b32_e32 v111, 0x80000000, v225
	v_xor_b32_e32 v110, 0x80000000, v224
	s_add_i32 s0, s11, 64
	v_pk_fma_f32 v[94:95], v[94:95], s[12:13], v[214:215] op_sel_hi:[1,0,1] neg_lo:[0,0,1] neg_hi:[0,0,1]
	v_pk_fma_f32 v[90:91], v[90:91], s[12:13], v[210:211] op_sel_hi:[1,0,1] neg_lo:[0,0,1] neg_hi:[0,0,1]
	v_pk_fma_f32 v[92:93], v[92:93], s[12:13], v[112:113] op_sel_hi:[1,0,1]
	v_pk_fma_f32 v[82:83], v[78:79], s[12:13], v[222:223] op_sel_hi:[1,0,1] neg_lo:[0,0,1] neg_hi:[0,0,1]
	v_pk_fma_f32 v[74:75], v[74:75], s[12:13], v[218:219] op_sel_hi:[1,0,1] neg_lo:[0,0,1] neg_hi:[0,0,1]
	v_pk_fma_f32 v[78:79], v[70:71], s[12:13], v[206:207] op_sel_hi:[1,0,1] neg_lo:[0,0,1] neg_hi:[0,0,1]
	v_pk_fma_f32 v[70:71], v[80:81], s[12:13], v[110:111] op_sel_hi:[1,0,1]
	v_pk_fma_f32 v[76:77], v[76:77], s[12:13], v[106:107] op_sel_hi:[1,0,1]
	v_pk_fma_f32 v[100:101], v[72:73], s[12:13], v[100:101] op_sel_hi:[1,0,1]
	v_pk_fma_f32 v[102:103], v[68:69], s[12:13], v[102:103] op_sel_hi:[1,0,1]
	s_cmp_le_i32 s0, s27
	v_pk_fma_f32 v[80:81], v[66:67], s[12:13], v[202:203] op_sel_hi:[1,0,1] neg_lo:[0,0,1] neg_hi:[0,0,1]
	s_cbranch_scc1 .LBB0_655
	v_cmp_gt_i32_e64 s[92:93], 26, v199
	v_cmp_gt_i32_e64 s[94:95], 27, v199
	v_cmp_gt_i32_e64 s[90:91], 25, v199
	s_and_b64 s[92:93], s[94:95], s[92:93]
	v_cmp_gt_i32_e64 s[88:89], 24, v199
	s_and_b64 s[90:91], s[92:93], s[90:91]
	v_cmp_gt_i32_e64 s[86:87], 19, v199
	s_and_b64 s[88:89], s[90:91], s[88:89]
	v_cmp_gt_i32_e64 s[84:85], 18, v199
	s_and_b64 s[86:87], s[88:89], s[86:87]
	v_cmp_gt_i32_e64 s[82:83], 17, v199
	s_and_b64 s[84:85], s[86:87], s[84:85]
	v_cmp_gt_i32_e64 s[80:81], 16, v199
	s_and_b64 s[82:83], s[84:85], s[82:83]
	v_cmp_gt_i32_e64 s[78:79], 11, v199
	s_and_b64 s[80:81], s[82:83], s[80:81]
	v_cmp_gt_i32_e64 s[76:77], 10, v199
	s_and_b64 s[78:79], s[80:81], s[78:79]
	v_cmp_gt_i32_e64 s[74:75], 9, v199
	s_and_b64 s[76:77], s[78:79], s[76:77]
	v_cmp_gt_i32_e64 s[72:73], 8, v199
	s_and_b64 s[74:75], s[76:77], s[74:75]
	v_cmp_gt_i32_e64 s[70:71], 3, v199
	s_and_b64 s[72:73], s[74:75], s[72:73]
	v_cmp_gt_i32_e64 s[68:69], 2, v199
	s_and_b64 s[70:71], s[72:73], s[70:71]
	v_cmp_gt_i32_e64 s[2:3], 1, v199
	s_and_b64 s[68:69], s[70:71], s[68:69]
	v_cmp_gt_i32_e64 s[0:1], 0, v199
	s_and_b64 s[2:3], s[68:69], s[2:3]
	s_and_b64 s[0:1], s[2:3], s[0:1]
	v_cmp_gt_i32_e64 s[66:67], 58, v199
	v_cndmask_b32_e64 v96, v96, v175, s[0:1]
	v_cmp_gt_i32_e64 s[0:1], 59, v199
	v_cmp_gt_i32_e64 s[64:65], 57, v199
	v_cmp_gt_i32_e64 s[62:63], 56, v199
	v_cndmask_b32_e64 v71, v71, v175, s[0:1]
	s_and_b64 s[0:1], s[0:1], s[66:67]
	v_cndmask_b32_e64 v70, v70, v175, s[0:1]
	s_and_b64 s[0:1], s[0:1], s[64:65]
	v_cmp_gt_i32_e64 s[60:61], 51, v199
	v_cndmask_b32_e64 v83, v83, v175, s[0:1]
	s_and_b64 s[0:1], s[0:1], s[62:63]
	v_cmp_gt_i32_e64 s[58:59], 50, v199
	v_cndmask_b32_e64 v82, v82, v175, s[0:1]
	s_and_b64 s[0:1], s[0:1], s[60:61]
	v_cmp_gt_i32_e64 s[56:57], 49, v199
	v_cndmask_b32_e64 v77, v77, v175, s[0:1]
	s_and_b64 s[0:1], s[0:1], s[58:59]
	v_cmp_gt_i32_e64 s[54:55], 48, v199
	v_cndmask_b32_e64 v76, v76, v175, s[0:1]
	s_and_b64 s[0:1], s[0:1], s[56:57]
	v_cmp_gt_i32_e64 s[52:53], 43, v199
	v_cndmask_b32_e64 v75, v75, v175, s[0:1]
	s_and_b64 s[0:1], s[0:1], s[54:55]
	v_cmp_gt_i32_e64 s[50:51], 42, v199
	v_cndmask_b32_e64 v74, v74, v175, s[0:1]
	s_and_b64 s[0:1], s[0:1], s[52:53]
	v_cmp_gt_i32_e64 s[48:49], 41, v199
	v_cndmask_b32_e64 v101, v101, v175, s[0:1]
	s_and_b64 s[0:1], s[0:1], s[50:51]
	v_cmp_gt_i32_e64 s[46:47], 40, v199
	v_cndmask_b32_e64 v100, v100, v175, s[0:1]
	s_and_b64 s[0:1], s[0:1], s[48:49]
	v_cmp_gt_i32_e64 s[44:45], 35, v199
	v_cndmask_b32_e64 v79, v79, v175, s[0:1]
	s_and_b64 s[0:1], s[0:1], s[46:47]
	v_cmp_gt_i32_e64 s[42:43], 34, v199
	v_cndmask_b32_e64 v78, v78, v175, s[0:1]
	s_and_b64 s[0:1], s[0:1], s[44:45]
	v_cmp_gt_i32_e64 s[40:41], 33, v199
	v_cndmask_b32_e64 v103, v103, v175, s[0:1]
	s_and_b64 s[0:1], s[0:1], s[42:43]
	v_cmp_gt_i32_e32 vcc, 32, v199
	v_cndmask_b32_e64 v102, v102, v175, s[0:1]
	s_and_b64 s[0:1], s[0:1], s[40:41]
	v_cndmask_b32_e64 v94, v94, v175, s[88:89]
	v_readlane_b32 s88, v242, 2
	s_and_b64 vcc, s[0:1], vcc
	v_cndmask_b32_e64 v87, v87, v175, s[94:95]
	v_cndmask_b32_e64 v86, v86, v175, s[92:93]
	s_movk_i32 s93, 0x6018
	s_mov_b32 s92, 0xf800000
	v_cndmask_b32_e64 v95, v95, v175, s[90:91]
	s_mov_b64 s[90:91], s[16:17]
	v_readlane_b32 s89, v242, 3
	v_cndmask_b32_e64 v93, v93, v175, s[86:87]
	v_readlane_b32 s86, v242, 0
	v_cndmask_b32_e64 v92, v92, v175, s[84:85]
	v_cndmask_b32_e64 v91, v91, v175, s[82:83]
	s_movk_i32 s83, 0x6000
	v_cndmask_b32_e64 v90, v90, v175, s[80:81]
	v_cndmask_b32_e64 v89, v89, v175, s[78:79]
	v_cndmask_b32_e64 v88, v88, v175, s[76:77]
	v_cndmask_b32_e64 v99, v99, v175, s[74:75]
	v_cndmask_b32_e64 v98, v98, v175, s[72:73]
	v_cndmask_b32_e64 v85, v85, v175, s[70:71]
	v_cndmask_b32_e64 v84, v84, v175, s[68:69]
	v_cndmask_b32_e64 v97, v97, v175, s[2:3]
	s_mov_b32 s56, s30
	v_cndmask_b32_e64 v81, v81, v175, s[0:1]
	v_cndmask_b32_e32 v80, v80, v175, vcc
	v_readlane_b32 s87, v242, 1

.LBB0_664:
	ds_read_b128 v[82:85], v191 offset:49152
	ds_read_b128 v[86:89], v191 offset:57344
	s_waitcnt lgkmcnt(1)
	v_mfma_f32_32x32x16_bf16 v[98:113], v[82:85], v[142:145], 0
	s_waitcnt lgkmcnt(0)
	v_mfma_f32_32x32x16_bf16 v[82:97], v[86:89], v[142:145], 0
	ds_read_b128 v[142:145], v190 offset:49152
	s_waitcnt vmcnt(2)
	ds_read_b128 v[148:151], v190 offset:57344
	s_waitcnt lgkmcnt(1)
	v_mfma_f32_32x32x16_bf16 v[98:113], v[142:145], v[138:141], v[98:113]
	s_waitcnt lgkmcnt(0)
	v_mfma_f32_32x32x16_bf16 v[82:97], v[148:151], v[138:141], v[82:97]
	ds_read_b128 v[138:141], v189 offset:49152
	ds_read_b128 v[142:145], v189 offset:57344
	s_waitcnt lgkmcnt(1)
	v_mfma_f32_32x32x16_bf16 v[98:113], v[138:141], v[134:137], v[98:113]
	s_waitcnt lgkmcnt(0)
	v_mfma_f32_32x32x16_bf16 v[82:97], v[142:145], v[134:137], v[82:97]
	ds_read_b128 v[134:137], v188 offset:49152
	ds_read_b128 v[138:141], v188 offset:57344
	s_waitcnt lgkmcnt(1)
	v_mfma_f32_32x32x16_bf16 v[98:113], v[134:137], v[130:133], v[98:113]
	s_waitcnt lgkmcnt(0)
	v_mfma_f32_32x32x16_bf16 v[82:97], v[138:141], v[130:133], v[82:97]
	ds_read_b128 v[130:133], v191 offset:49280
	ds_read_b128 v[134:137], v191 offset:57472
	s_waitcnt lgkmcnt(1)
	v_mfma_f32_32x32x16_bf16 v[98:113], v[130:133], v[126:129], v[98:113]
	s_waitcnt lgkmcnt(0)
	v_mfma_f32_32x32x16_bf16 v[82:97], v[134:137], v[126:129], v[82:97]
	ds_read_b128 v[126:129], v190 offset:49280
	ds_read_b128 v[130:133], v190 offset:57472
	s_waitcnt lgkmcnt(1)
	v_mfma_f32_32x32x16_bf16 v[98:113], v[126:129], v[122:125], v[98:113]
	s_waitcnt lgkmcnt(0)
	v_mfma_f32_32x32x16_bf16 v[82:97], v[130:133], v[122:125], v[82:97]
	ds_read_b128 v[122:125], v189 offset:49280
	ds_read_b128 v[126:129], v189 offset:57472
	s_waitcnt lgkmcnt(1)
	v_mfma_f32_32x32x16_bf16 v[98:113], v[122:125], v[118:121], v[98:113]
	s_waitcnt lgkmcnt(0)
	v_mfma_f32_32x32x16_bf16 v[82:97], v[126:129], v[118:121], v[82:97]
	ds_read_b128 v[118:121], v188 offset:49280
	ds_read_b128 v[122:125], v188 offset:57472
	s_waitcnt lgkmcnt(1)
	v_mfma_f32_32x32x16_bf16 v[98:113], v[118:121], v[114:117], v[98:113]
	s_waitcnt lgkmcnt(0)
	v_mfma_f32_32x32x16_bf16 v[82:97], v[122:125], v[114:117], v[82:97]
	v_exp_f32_e32 v81, v1
	v_add_f32_e32 v1, 0, v215
	v_add_f32_e32 v1, v217, v1
	v_add_f32_e32 v1, v213, v1
	v_add_f32_e32 v1, v216, v1
	v_add_f32_e32 v1, v211, v1
	v_add_f32_e32 v1, v214, v1
	v_add_f32_e32 v1, v210, v1
	v_add_f32_e32 v1, v212, v1
	v_add_f32_e32 v1, v207, v1
	v_add_f32_e32 v1, v209, v1
	v_add_f32_e32 v1, v205, v1
	v_add_f32_e32 v1, v208, v1
	v_exp_f32_e32 v80, v80
	v_add_f32_e32 v1, v203, v1
	v_add_f32_e32 v1, v206, v1
	v_exp_f32_e32 v78, v78
	v_add_f32_e32 v1, v202, v1
	v_exp_f32_e32 v79, v79
	v_add_f32_e32 v1, v204, v1
	v_exp_f32_e32 v76, v76
	v_add_f32_e32 v1, v80, v1
	v_exp_f32_e32 v77, v77
	v_add_f32_e32 v1, v81, v1
	v_exp_f32_e32 v115, v74
	v_add_f32_e32 v1, v78, v1
	v_exp_f32_e32 v116, v75
	v_add_f32_e32 v1, v79, v1
	v_exp_f32_e32 v117, v72
	v_add_f32_e32 v1, v76, v1
	v_exp_f32_e32 v118, v73
	v_add_f32_e32 v1, v77, v1
	v_exp_f32_e32 v119, v70
	v_add_f32_e32 v1, v115, v1
	v_exp_f32_e32 v120, v71
	v_add_f32_e32 v1, v116, v1
	v_exp_f32_e32 v121, v68
	v_add_f32_e32 v1, v117, v1
	v_exp_f32_e32 v122, v69
	v_add_f32_e32 v1, v118, v1
	v_exp_f32_e32 v123, v66
	v_add_f32_e32 v1, v119, v1
	v_exp_f32_e32 v124, v67
	v_add_f32_e32 v1, v120, v1
	v_add_f32_e32 v1, v121, v1
	v_add_f32_e32 v1, v122, v1
	v_add_f32_e32 v1, v123, v1
	v_add_f32_e32 v1, v124, v1
	v_mov_b32_e32 v114, v1
	v_cvt_pk_bf16_f32 v66, v215, v217
	v_cvt_pk_bf16_f32 v67, v213, v216
	v_cvt_pk_bf16_f32 v68, v211, v214
	v_cvt_pk_bf16_f32 v69, v210, v212
	v_cvt_pk_bf16_f32 v70, v207, v209
	v_cvt_pk_bf16_f32 v71, v205, v208
	v_cvt_pk_bf16_f32 v72, v203, v206
	v_cvt_pk_bf16_f32 v73, v202, v204
	v_cvt_pk_bf16_f32 v74, v80, v81
	v_cvt_pk_bf16_f32 v75, v78, v79
	v_cvt_pk_bf16_f32 v76, v76, v77
	v_cvt_pk_bf16_f32 v77, v115, v116
	v_cvt_pk_bf16_f32 v78, v117, v118
	v_cvt_pk_bf16_f32 v79, v119, v120
	v_cvt_pk_bf16_f32 v80, v121, v122
	v_cvt_pk_bf16_f32 v81, v123, v124
	s_nop 1
	v_permlane32_swap_b32_e32 v1, v114
	v_permlane32_swap_b32_e32 v66, v68
	v_permlane32_swap_b32_e32 v67, v69
	v_permlane32_swap_b32_e32 v70, v72
	v_permlane32_swap_b32_e32 v71, v73
	v_permlane32_swap_b32_e32 v74, v76
	v_permlane32_swap_b32_e32 v75, v77
	v_permlane32_swap_b32_e32 v78, v80
	v_permlane32_swap_b32_e32 v79, v81
	ds_read_b64_tr_b16 v[116:117], v183 offset:0
	ds_read_b64_tr_b16 v[118:119], v183 offset:0x800
	ds_read_b64_tr_b16 v[120:121], v183 offset:0x1000
	ds_read_b64_tr_b16 v[122:123], v183 offset:0x1800
	ds_read_b64_tr_b16 v[124:125], v183 offset:0x2000
	ds_read_b64_tr_b16 v[126:127], v183 offset:0x2800
	ds_read_b64_tr_b16 v[128:129], v183 offset:0x3000
	ds_read_b64_tr_b16 v[130:131], v183 offset:0x3800
	s_nop 0
	s_waitcnt lgkmcnt(6)
	v_mfma_f32_32x32x16_bf16 v[50:65], v[66:69], v[116:119], v[50:65]
	ds_read_b64_tr_b16 v[116:117], v183 offset:0x200
	ds_read_b64_tr_b16 v[118:119], v183 offset:0xa00
	s_waitcnt lgkmcnt(6)
	v_mfma_f32_32x32x16_bf16 v[50:65], v[70:73], v[120:123], v[50:65]
	ds_read_b64_tr_b16 v[120:121], v183 offset:0x1200
	ds_read_b64_tr_b16 v[122:123], v183 offset:0x1a00
	s_waitcnt lgkmcnt(6)
	v_mfma_f32_32x32x16_bf16 v[50:65], v[74:77], v[124:127], v[50:65]
	ds_read_b64_tr_b16 v[124:125], v183 offset:0x2200
	ds_read_b64_tr_b16 v[126:127], v183 offset:0x2a00
	s_waitcnt lgkmcnt(6)
	v_mfma_f32_32x32x16_bf16 v[50:65], v[78:81], v[128:131], v[50:65]
	ds_read_b64_tr_b16 v[128:129], v183 offset:0x3200
	ds_read_b64_tr_b16 v[130:131], v183 offset:0x3a00
	s_waitcnt lgkmcnt(6)
	v_mfma_f32_32x32x16_bf16 v[34:49], v[66:69], v[116:119], v[34:49]
	ds_read_b64_tr_b16 v[116:117], v183 offset:0x400
	ds_read_b64_tr_b16 v[118:119], v183 offset:0xc00
	s_waitcnt lgkmcnt(6)
	v_mfma_f32_32x32x16_bf16 v[34:49], v[70:73], v[120:123], v[34:49]
	ds_read_b64_tr_b16 v[120:121], v183 offset:0x1400
	ds_read_b64_tr_b16 v[122:123], v183 offset:0x1c00
	s_waitcnt lgkmcnt(6)
	v_mfma_f32_32x32x16_bf16 v[34:49], v[74:77], v[124:127], v[34:49]
	ds_read_b64_tr_b16 v[124:125], v183 offset:0x2400
	ds_read_b64_tr_b16 v[126:127], v183 offset:0x2c00
	s_waitcnt lgkmcnt(6)
	v_mfma_f32_32x32x16_bf16 v[34:49], v[78:81], v[128:131], v[34:49]
	ds_read_b64_tr_b16 v[128:129], v183 offset:0x3400
	ds_read_b64_tr_b16 v[130:131], v183 offset:0x3c00
	s_waitcnt lgkmcnt(6)
	v_mfma_f32_32x32x16_bf16 v[18:33], v[66:69], v[116:119], v[18:33]
	ds_read_b64_tr_b16 v[116:117], v183 offset:0x600
	ds_read_b64_tr_b16 v[118:119], v183 offset:0xe00
	s_waitcnt lgkmcnt(6)
	v_mfma_f32_32x32x16_bf16 v[18:33], v[70:73], v[120:123], v[18:33]
	ds_read_b64_tr_b16 v[120:121], v183 offset:0x1600
	ds_read_b64_tr_b16 v[122:123], v183 offset:0x1e00
	s_waitcnt lgkmcnt(6)
	v_mfma_f32_32x32x16_bf16 v[18:33], v[74:77], v[124:127], v[18:33]
	ds_read_b64_tr_b16 v[124:125], v183 offset:0x2600
	ds_read_b64_tr_b16 v[126:127], v183 offset:0x2e00
	s_waitcnt lgkmcnt(6)
	v_mfma_f32_32x32x16_bf16 v[18:33], v[78:81], v[128:131], v[18:33]
	ds_read_b64_tr_b16 v[128:129], v183 offset:0x3600
	ds_read_b64_tr_b16 v[130:131], v183 offset:0x3e00
	s_waitcnt lgkmcnt(6)
	v_mfma_f32_32x32x16_bf16 v[2:17], v[66:69], v[116:119], v[2:17]
	s_lshl_b32 s1, s25, 6
	s_sub_i32 s0, s1, 64
	s_lshl_b32 s2, s0, 2
	s_add_i32 s2, s2, 0
	v_lshl_add_u32 v66, v186, 2, s2
	v_add_u32_e32 v66, 0x10800, v66
	s_add_i32 s1, s1, -1
	s_waitcnt lgkmcnt(4)
	v_mfma_f32_32x32x16_bf16 v[2:17], v[70:73], v[120:123], v[2:17]
	s_cmp_gt_i32 s1, s27
	s_waitcnt lgkmcnt(2)
	v_mfma_f32_32x32x16_bf16 v[2:17], v[74:77], v[124:127], v[2:17]
	s_waitcnt lgkmcnt(0)
	v_mfma_f32_32x32x16_bf16 v[2:17], v[78:81], v[128:131], v[2:17]
	ds_read_b128 v[116:119], v66 offset:128
	ds_read_b128 v[120:123], v66
	ds_read_b128 v[68:71], v66 offset:32
	ds_read_b128 v[124:127], v66 offset:160
	ds_read_b128 v[72:75], v66 offset:64
	ds_read_b128 v[128:131], v66 offset:192
	ds_read_b128 v[76:79], v66 offset:96
	ds_read_b128 v[132:135], v66 offset:224
	s_waitcnt lgkmcnt(6)
	v_xor_b32_e32 v81, 0x80000000, v123
	v_xor_b32_e32 v80, 0x80000000, v122
	s_waitcnt lgkmcnt(5)
	v_xor_b32_e32 v123, 0x80000000, v71
	v_xor_b32_e32 v122, 0x80000000, v70
	s_waitcnt lgkmcnt(1)
	v_xor_b32_e32 v79, 0x80000000, v79
	v_xor_b32_e32 v78, 0x80000000, v78
	v_xor_b32_e32 v137, 0x80000000, v75
	v_xor_b32_e32 v136, 0x80000000, v74
	v_pk_fma_f32 v[66:67], v[110:111], s[12:13], v[76:77] op_sel_hi:[1,0,1] neg_lo:[0,0,1] neg_hi:[0,0,1]
	v_pk_fma_f32 v[70:71], v[106:107], s[12:13], v[72:73] op_sel_hi:[1,0,1] neg_lo:[0,0,1] neg_hi:[0,0,1]
	v_pk_fma_f32 v[74:75], v[102:103], s[12:13], v[68:69] op_sel_hi:[1,0,1] neg_lo:[0,0,1] neg_hi:[0,0,1]
	v_pk_fma_f32 v[68:69], v[112:113], s[12:13], v[78:79] op_sel_hi:[1,0,1]
	v_pk_fma_f32 v[76:77], v[104:105], s[12:13], v[122:123] op_sel_hi:[1,0,1]
	v_pk_fma_f32 v[78:79], v[100:101], s[12:13], v[80:81] op_sel_hi:[1,0,1]
	v_xor_b32_e32 v101, 0x80000000, v119
	v_xor_b32_e32 v100, 0x80000000, v118
	v_xor_b32_e32 v103, 0x80000000, v127
	v_xor_b32_e32 v102, 0x80000000, v126
	v_xor_b32_e32 v105, 0x80000000, v131
	v_xor_b32_e32 v104, 0x80000000, v130
	s_waitcnt lgkmcnt(0)
	v_xor_b32_e32 v107, 0x80000000, v135
	v_xor_b32_e32 v106, 0x80000000, v134
	v_pk_fma_f32 v[72:73], v[108:109], s[12:13], v[136:137] op_sel_hi:[1,0,1]
	v_pk_fma_f32 v[80:81], v[98:99], s[12:13], v[120:121] op_sel_hi:[1,0,1] neg_lo:[0,0,1] neg_hi:[0,0,1]
	v_pk_fma_f32 v[94:95], v[94:95], s[12:13], v[132:133] op_sel_hi:[1,0,1] neg_lo:[0,0,1] neg_hi:[0,0,1]
	v_pk_fma_f32 v[90:91], v[90:91], s[12:13], v[128:129] op_sel_hi:[1,0,1] neg_lo:[0,0,1] neg_hi:[0,0,1]
	v_pk_fma_f32 v[98:99], v[86:87], s[12:13], v[124:125] op_sel_hi:[1,0,1] neg_lo:[0,0,1] neg_hi:[0,0,1]
	v_pk_fma_f32 v[86:87], v[96:97], s[12:13], v[106:107] op_sel_hi:[1,0,1]
	v_pk_fma_f32 v[92:93], v[92:93], s[12:13], v[104:105] op_sel_hi:[1,0,1]
	v_pk_fma_f32 v[88:89], v[88:89], s[12:13], v[102:103] op_sel_hi:[1,0,1]
	v_pk_fma_f32 v[84:85], v[84:85], s[12:13], v[100:101] op_sel_hi:[1,0,1]
	v_pk_fma_f32 v[82:83], v[82:83], s[12:13], v[116:117] op_sel_hi:[1,0,1] neg_lo:[0,0,1] neg_hi:[0,0,1]
	s_cbranch_scc0 .LBB0_666
	v_subrev_u32_e32 v96, s0, v187
	v_cmp_gt_i32_e64 s[92:93], 26, v96
	v_cmp_gt_i32_e64 s[94:95], 27, v96
	v_cmp_gt_i32_e64 s[90:91], 25, v96
	s_and_b64 s[92:93], s[94:95], s[92:93]
	v_cmp_gt_i32_e64 s[88:89], 24, v96
	s_and_b64 s[90:91], s[92:93], s[90:91]
	v_cmp_gt_i32_e64 s[86:87], 19, v96
	s_and_b64 s[88:89], s[90:91], s[88:89]
	v_cmp_gt_i32_e64 s[84:85], 18, v96
	s_and_b64 s[86:87], s[88:89], s[86:87]
	v_cmp_gt_i32_e64 s[82:83], 17, v96
	s_and_b64 s[84:85], s[86:87], s[84:85]
	v_cmp_gt_i32_e64 s[80:81], 16, v96
	s_and_b64 s[82:83], s[84:85], s[82:83]
	v_cmp_gt_i32_e64 s[78:79], 11, v96
	s_and_b64 s[80:81], s[82:83], s[80:81]
	v_cmp_gt_i32_e64 s[76:77], 10, v96
	s_and_b64 s[78:79], s[80:81], s[78:79]
	v_cmp_gt_i32_e64 s[74:75], 9, v96
	s_and_b64 s[76:77], s[78:79], s[76:77]
	v_cmp_gt_i32_e64 s[72:73], 8, v96
	s_and_b64 s[74:75], s[76:77], s[74:75]
	v_cmp_gt_i32_e64 s[70:71], 3, v96
	s_and_b64 s[72:73], s[74:75], s[72:73]
	v_cmp_gt_i32_e64 s[68:69], 2, v96
	s_and_b64 s[70:71], s[72:73], s[70:71]
	v_cmp_gt_i32_e64 s[2:3], 1, v96
	s_and_b64 s[68:69], s[70:71], s[68:69]
	v_cmp_gt_i32_e64 s[0:1], 0, v96
	s_and_b64 s[2:3], s[68:69], s[2:3]
	s_and_b64 s[0:1], s[2:3], s[0:1]
	v_cmp_gt_i32_e64 s[66:67], 58, v96
	v_cndmask_b32_e64 v80, v80, v175, s[0:1]
	v_cmp_gt_i32_e64 s[0:1], 59, v96
	v_cmp_gt_i32_e64 s[64:65], 57, v96
	v_cmp_gt_i32_e64 s[62:63], 56, v96
	v_cndmask_b32_e64 v87, v87, v175, s[0:1]
	s_and_b64 s[0:1], s[0:1], s[66:67]
	v_cndmask_b32_e64 v86, v86, v175, s[0:1]
	s_and_b64 s[0:1], s[0:1], s[64:65]
	v_cmp_gt_i32_e64 s[60:61], 51, v96
	v_cndmask_b32_e64 v95, v95, v175, s[0:1]
	s_and_b64 s[0:1], s[0:1], s[62:63]
	v_cmp_gt_i32_e64 s[58:59], 50, v96
	v_cndmask_b32_e64 v94, v94, v175, s[0:1]
	s_and_b64 s[0:1], s[0:1], s[60:61]
	v_cmp_gt_i32_e64 s[56:57], 49, v96
	v_cndmask_b32_e64 v93, v93, v175, s[0:1]
	s_and_b64 s[0:1], s[0:1], s[58:59]
	v_cmp_gt_i32_e64 s[54:55], 48, v96
	v_cndmask_b32_e64 v92, v92, v175, s[0:1]
	s_and_b64 s[0:1], s[0:1], s[56:57]
	v_cmp_gt_i32_e64 s[52:53], 43, v96
	v_cndmask_b32_e64 v91, v91, v175, s[0:1]
	s_and_b64 s[0:1], s[0:1], s[54:55]
	v_cmp_gt_i32_e64 s[50:51], 42, v96
	v_cndmask_b32_e64 v90, v90, v175, s[0:1]
	s_and_b64 s[0:1], s[0:1], s[52:53]
	v_cmp_gt_i32_e64 s[48:49], 41, v96
	v_cndmask_b32_e64 v89, v89, v175, s[0:1]
	s_and_b64 s[0:1], s[0:1], s[50:51]
	v_cmp_gt_i32_e64 s[46:47], 40, v96
	v_cndmask_b32_e64 v88, v88, v175, s[0:1]
	s_and_b64 s[0:1], s[0:1], s[48:49]
	v_cmp_gt_i32_e64 s[44:45], 35, v96
	v_cndmask_b32_e64 v99, v99, v175, s[0:1]
	s_and_b64 s[0:1], s[0:1], s[46:47]
	v_cmp_gt_i32_e64 s[42:43], 34, v96
	v_cndmask_b32_e64 v98, v98, v175, s[0:1]
	s_and_b64 s[0:1], s[0:1], s[44:45]
	v_cmp_gt_i32_e64 s[40:41], 33, v96
	v_cndmask_b32_e64 v85, v85, v175, s[0:1]
	s_and_b64 s[0:1], s[0:1], s[42:43]
	v_cmp_gt_i32_e32 vcc, 32, v96
	v_cndmask_b32_e64 v84, v84, v175, s[0:1]
	s_and_b64 s[0:1], s[0:1], s[40:41]
	v_cndmask_b32_e64 v66, v66, v175, s[88:89]
	v_readlane_b32 s88, v242, 2
	s_and_b64 vcc, s[0:1], vcc
	v_cndmask_b32_e64 v69, v69, v175, s[94:95]
	v_cndmask_b32_e64 v68, v68, v175, s[92:93]
	s_movk_i32 s93, 0x6018
	s_mov_b32 s92, 0xf800000
	v_cndmask_b32_e64 v67, v67, v175, s[90:91]
	s_mov_b64 s[90:91], s[16:17]
	v_readlane_b32 s89, v242, 3
	v_cndmask_b32_e64 v73, v73, v175, s[86:87]
	v_readlane_b32 s86, v242, 0
	v_cndmask_b32_e64 v72, v72, v175, s[84:85]
	v_cndmask_b32_e64 v71, v71, v175, s[82:83]
	s_movk_i32 s83, 0x6000
	v_cndmask_b32_e64 v70, v70, v175, s[80:81]
	v_cndmask_b32_e64 v77, v77, v175, s[78:79]
	v_cndmask_b32_e64 v76, v76, v175, s[76:77]
	v_cndmask_b32_e64 v75, v75, v175, s[74:75]
	v_cndmask_b32_e64 v74, v74, v175, s[72:73]
	v_cndmask_b32_e64 v79, v79, v175, s[70:71]
	v_cndmask_b32_e64 v78, v78, v175, s[68:69]
	v_cndmask_b32_e64 v81, v81, v175, s[2:3]
	s_mov_b32 s56, s30
	v_cndmask_b32_e64 v83, v83, v175, s[0:1]
	v_cndmask_b32_e32 v82, v82, v175, vcc
	v_readlane_b32 s87, v242, 1

.LBB0_670:
	v_cndmask_b32_e64 v97, v97, v196, s[40:41]
	v_sub_f32_e32 v80, v80, v97
	v_sub_f32_e32 v81, v81, v97
	v_exp_f32_e32 v80, v80
	v_sub_f32_e32 v78, v78, v97
	v_exp_f32_e32 v81, v81
	v_sub_f32_e32 v79, v79, v97
	v_exp_f32_e32 v78, v78
	v_sub_f32_e32 v74, v74, v97
	v_sub_f32_e32 v66, v66, v97
	v_exp_f32_e32 v79, v79
	v_sub_f32_e32 v75, v75, v97
	v_exp_f32_e32 v74, v74
	v_exp_f32_e32 v102, v66
	v_add_f32_e32 v66, 0, v80
	v_sub_f32_e32 v76, v76, v97
	v_exp_f32_e32 v75, v75
	v_add_f32_e32 v66, v81, v66
	v_sub_f32_e32 v77, v77, v97
	v_exp_f32_e32 v76, v76
	v_add_f32_e32 v66, v78, v66
	v_sub_f32_e32 v70, v70, v97
	v_exp_f32_e32 v77, v77
	v_add_f32_e32 v66, v79, v66
	v_sub_f32_e32 v82, v82, v97
	v_sub_f32_e32 v83, v83, v97
	v_sub_f32_e32 v84, v84, v97
	v_sub_f32_e32 v85, v85, v97
	v_sub_f32_e32 v98, v98, v97
	v_sub_f32_e32 v99, v99, v97
	v_sub_f32_e32 v88, v88, v97
	v_sub_f32_e32 v89, v89, v97
	v_sub_f32_e32 v90, v90, v97
	v_sub_f32_e32 v71, v71, v97
	v_sub_f32_e32 v91, v91, v97
	v_sub_f32_e32 v72, v72, v97
	v_sub_f32_e32 v92, v92, v97
	v_sub_f32_e32 v73, v73, v97
	v_sub_f32_e32 v93, v93, v97
	v_sub_f32_e32 v94, v94, v97
	v_sub_f32_e32 v67, v67, v97
	v_sub_f32_e32 v95, v95, v97
	v_sub_f32_e32 v68, v68, v97
	v_sub_f32_e32 v86, v86, v97
	v_sub_f32_e32 v69, v69, v97
	v_sub_f32_e32 v87, v87, v97
	v_exp_f32_e32 v97, v70
	v_add_f32_e32 v66, v74, v66
	v_exp_f32_e32 v100, v71
	v_add_f32_e32 v66, v75, v66
	v_exp_f32_e32 v101, v72
	v_add_f32_e32 v66, v76, v66
	v_exp_f32_e32 v73, v73
	v_add_f32_e32 v66, v77, v66
	v_add_f32_e32 v66, v97, v66
	v_exp_f32_e32 v103, v67
	v_add_f32_e32 v66, v100, v66
	v_exp_f32_e32 v104, v68
	v_add_f32_e32 v66, v101, v66
	v_exp_f32_e32 v105, v69
	v_add_f32_e32 v66, v73, v66
	v_exp_f32_e32 v82, v82
	v_add_f32_e32 v66, v102, v66
	v_exp_f32_e32 v83, v83
	v_add_f32_e32 v66, v103, v66
	v_exp_f32_e32 v84, v84
	v_add_f32_e32 v66, v104, v66
	v_exp_f32_e32 v85, v85
	v_add_f32_e32 v66, v105, v66
	v_exp_f32_e32 v98, v98
	v_add_f32_e32 v66, v82, v66
	v_exp_f32_e32 v99, v99
	v_add_f32_e32 v66, v83, v66
	v_exp_f32_e32 v88, v88
	v_add_f32_e32 v66, v84, v66
	v_exp_f32_e32 v89, v89
	v_add_f32_e32 v66, v85, v66
	v_exp_f32_e32 v90, v90
	v_add_f32_e32 v66, v98, v66
	v_exp_f32_e32 v91, v91
	v_add_f32_e32 v66, v99, v66
	v_exp_f32_e32 v92, v92
	v_add_f32_e32 v66, v88, v66
	v_exp_f32_e32 v93, v93
	v_add_f32_e32 v66, v89, v66
	v_exp_f32_e32 v94, v94
	v_add_f32_e32 v66, v90, v66
	v_exp_f32_e32 v95, v95
	v_add_f32_e32 v66, v91, v66
	v_exp_f32_e32 v86, v86
	v_add_f32_e32 v66, v92, v66
	v_exp_f32_e32 v87, v87
	v_add_f32_e32 v66, v93, v66
	v_add_f32_e32 v66, v94, v66
	v_add_f32_e32 v66, v95, v66
	v_add_f32_e32 v66, v86, v66
	v_add_f32_e32 v66, v87, v66
	v_mov_b32_e32 v67, v66
	s_nop 1
	v_permlane32_swap_b32_e32 v66, v67
	v_cvt_pk_bf16_f32 v68, v80, v81
	v_cvt_pk_bf16_f32 v69, v78, v79
	v_cvt_pk_bf16_f32 v70, v74, v75
	v_cvt_pk_bf16_f32 v71, v76, v77
	v_cvt_pk_bf16_f32 v72, v97, v100
	v_cvt_pk_bf16_f32 v73, v101, v73
	v_cvt_pk_bf16_f32 v74, v102, v103
	v_cvt_pk_bf16_f32 v75, v104, v105
	v_cvt_pk_bf16_f32 v76, v82, v83
	v_cvt_pk_bf16_f32 v77, v84, v85
	v_cvt_pk_bf16_f32 v78, v98, v99
	v_cvt_pk_bf16_f32 v79, v88, v89
	v_cvt_pk_bf16_f32 v80, v90, v91
	v_cvt_pk_bf16_f32 v81, v92, v93
	v_cvt_pk_bf16_f32 v82, v94, v95
	v_cvt_pk_bf16_f32 v83, v86, v87
	s_nop 0
	v_permlane32_swap_b32_e32 v68, v70
	v_permlane32_swap_b32_e32 v69, v71
	v_permlane32_swap_b32_e32 v72, v74
	v_permlane32_swap_b32_e32 v73, v75
	v_permlane32_swap_b32_e32 v76, v78
	v_permlane32_swap_b32_e32 v77, v79
	v_permlane32_swap_b32_e32 v80, v82
	v_permlane32_swap_b32_e32 v81, v83
	ds_read_b64_tr_b16 v[84:85], v183 offset:0x4000
	ds_read_b64_tr_b16 v[86:87], v183 offset:0x4800
	ds_read_b64_tr_b16 v[88:89], v183 offset:0x5000
	ds_read_b64_tr_b16 v[90:91], v183 offset:0x5800
	ds_read_b64_tr_b16 v[92:93], v183 offset:0x6000
	ds_read_b64_tr_b16 v[94:95], v183 offset:0x6800
	ds_read_b64_tr_b16 v[98:99], v183 offset:0x7000
	ds_read_b64_tr_b16 v[100:101], v183 offset:0x7800
	s_nop 0
	s_waitcnt lgkmcnt(6)
	v_mfma_f32_32x32x16_bf16 v[50:65], v[68:71], v[84:87], v[50:65]
	ds_read_b64_tr_b16 v[84:85], v183 offset:0x4200
	ds_read_b64_tr_b16 v[86:87], v183 offset:0x4a00
	s_waitcnt lgkmcnt(6)
	v_mfma_f32_32x32x16_bf16 v[50:65], v[72:75], v[88:91], v[50:65]
	ds_read_b64_tr_b16 v[88:89], v183 offset:0x5200
	ds_read_b64_tr_b16 v[90:91], v183 offset:0x5a00
	s_waitcnt lgkmcnt(6)
	v_mfma_f32_32x32x16_bf16 v[50:65], v[76:79], v[92:95], v[50:65]
	ds_read_b64_tr_b16 v[92:93], v183 offset:0x6200
	ds_read_b64_tr_b16 v[94:95], v183 offset:0x6a00
	s_waitcnt lgkmcnt(6)
	v_mfma_f32_32x32x16_bf16 v[50:65], v[80:83], v[98:101], v[50:65]
	ds_read_b64_tr_b16 v[98:99], v183 offset:0x7200
	ds_read_b64_tr_b16 v[100:101], v183 offset:0x7a00
	s_waitcnt lgkmcnt(6)
	v_mfma_f32_32x32x16_bf16 v[34:49], v[68:71], v[84:87], v[34:49]
	ds_read_b64_tr_b16 v[84:85], v183 offset:0x4400
	ds_read_b64_tr_b16 v[86:87], v183 offset:0x4c00
	s_waitcnt lgkmcnt(6)
	v_mfma_f32_32x32x16_bf16 v[34:49], v[72:75], v[88:91], v[34:49]
	ds_read_b64_tr_b16 v[88:89], v183 offset:0x5400
	ds_read_b64_tr_b16 v[90:91], v183 offset:0x5c00
	s_waitcnt lgkmcnt(6)
	v_mfma_f32_32x32x16_bf16 v[34:49], v[76:79], v[92:95], v[34:49]
	ds_read_b64_tr_b16 v[92:93], v183 offset:0x6400
	ds_read_b64_tr_b16 v[94:95], v183 offset:0x6c00
	s_waitcnt lgkmcnt(6)
	v_mfma_f32_32x32x16_bf16 v[34:49], v[80:83], v[98:101], v[34:49]
	ds_read_b64_tr_b16 v[98:99], v183 offset:0x7400
	ds_read_b64_tr_b16 v[100:101], v183 offset:0x7c00
	s_waitcnt lgkmcnt(6)
	v_mfma_f32_32x32x16_bf16 v[18:33], v[68:71], v[84:87], v[18:33]
	ds_read_b64_tr_b16 v[84:85], v183 offset:0x4600
	ds_read_b64_tr_b16 v[86:87], v183 offset:0x4e00
	s_waitcnt lgkmcnt(6)
	v_mfma_f32_32x32x16_bf16 v[18:33], v[72:75], v[88:91], v[18:33]
	ds_read_b64_tr_b16 v[88:89], v183 offset:0x5600
	ds_read_b64_tr_b16 v[90:91], v183 offset:0x5e00
	s_waitcnt lgkmcnt(6)
	v_mfma_f32_32x32x16_bf16 v[18:33], v[76:79], v[92:95], v[18:33]
	ds_read_b64_tr_b16 v[92:93], v183 offset:0x6600
	ds_read_b64_tr_b16 v[94:95], v183 offset:0x6e00
	s_waitcnt lgkmcnt(6)
	v_mfma_f32_32x32x16_bf16 v[18:33], v[80:83], v[98:101], v[18:33]
	ds_read_b64_tr_b16 v[98:99], v183 offset:0x7600
	ds_read_b64_tr_b16 v[100:101], v183 offset:0x7e00
	s_waitcnt lgkmcnt(6)
	v_mfma_f32_32x32x16_bf16 v[2:17], v[68:71], v[84:87], v[2:17]
	s_waitcnt lgkmcnt(4)
	v_mfma_f32_32x32x16_bf16 v[2:17], v[72:75], v[88:91], v[2:17]
	s_waitcnt lgkmcnt(2)
	v_mfma_f32_32x32x16_bf16 v[2:17], v[76:79], v[92:95], v[2:17]
	s_waitcnt lgkmcnt(0)
	v_mfma_f32_32x32x16_bf16 v[2:17], v[80:83], v[98:101], v[2:17]
	s_and_saveexec_b64 s[0:1], s[38:39]
	v_add_f32_e32 v1, v1, v114
	v_fmac_f32_e32 v1, v162, v146
	v_add_f32_e32 v66, v66, v67
	v_fmac_f32_e32 v66, v1, v96
	ds_write_b32 v185, v66
	s_or_b64 exec, exec, s[0:1]
	s_waitcnt lgkmcnt(0)
	ds_read_b128 v[78:81], v184
	ds_read_b128 v[74:77], v184 offset:32
	ds_read_b128 v[70:73], v184 offset:64
	ds_read_b128 v[66:69], v184 offset:96
	s_lshl_b32 s0, s5, 13
	s_waitcnt lgkmcnt(3)
	v_rcp_f32_e32 v78, v78
	v_and_b32_e32 v1, 1, v180
	s_add_i32 s2, s0, 0
	v_cmp_eq_u32_e32 vcc, 0, v1
	v_lshlrev_b32_e32 v1, 10, v181
	v_lshlrev_b32_e32 v82, 1, v182
	v_mul_f32_e32 v50, v50, v78
	v_add3_u32 v1, s2, v1, v82
	s_waitcnt lgkmcnt(0)
	v_mov_b32_dpp v82, v50 quad_perm:[1,0,3,2] row_mask:0xf bank_mask:0xf bound_ctrl:1
	s_barrier
	s_and_saveexec_b64 s[0:1], vcc
	s_cbranch_execz .LBB0_674
	v_cvt_pk_bf16_f32 v50, v50, v82
	ds_write_b32 v1, v50

.LBB0_823:
	v_add_u32_e32 v182, s9, v158
	v_add_u32_e32 v66, 1, v182
	v_mad_i64_i32 v[66:67], s[0:1], v66, s33, v[130:131]
	v_add_u32_e32 v68, 33, v182
	v_mad_i64_i32 v[68:69], s[0:1], v68, s33, v[130:131]
	global_load_dwordx4 v[114:117], v[66:67], off offset:2048
	global_load_dwordx4 v[122:125], v[66:67], off offset:1024
	global_load_dwordx4 v[118:121], v[68:69], off offset:2048
	global_load_dwordx4 v[126:129], v[68:69], off offset:1024
	ds_read_b128 v[228:231], v159 offset:49152
	ds_read_b128 v[232:235], v160 offset:49152
	ds_read_b128 v[236:239], v159 offset:57344
	ds_read_b128 v[248:251], v160 offset:57344
	ds_read_b128 v[252:255], v161 offset:49152
	s_waitcnt lgkmcnt(4)
	v_mfma_f32_32x32x16_bf16 v[82:97], v[228:231], v[110:113], 0
	ds_read_b128 v[228:231], v161 offset:57344
	s_waitcnt lgkmcnt(4)
	v_mfma_f32_32x32x16_bf16 v[82:97], v[232:235], v[106:109], v[82:97]
	ds_read_b128 v[232:235], v162 offset:49152
	s_waitcnt lgkmcnt(4)
	v_mfma_f32_32x32x16_bf16 v[66:81], v[236:239], v[110:113], 0
	ds_read_b128 v[236:239], v162 offset:57344
	s_waitcnt lgkmcnt(4)
	v_mfma_f32_32x32x16_bf16 v[66:81], v[248:251], v[106:109], v[66:81]
	s_waitcnt lgkmcnt(3)
	v_mfma_f32_32x32x16_bf16 v[82:97], v[252:255], v[102:105], v[82:97]
	s_waitcnt lgkmcnt(2)
	v_mfma_f32_32x32x16_bf16 v[66:81], v[228:231], v[102:105], v[66:81]
	s_waitcnt lgkmcnt(1)
	v_mfma_f32_32x32x16_bf16 v[82:97], v[232:235], v[98:101], v[82:97]
	s_waitcnt lgkmcnt(0)
	v_mfma_f32_32x32x16_bf16 v[66:81], v[236:239], v[98:101], v[66:81]
	v_exp_f32_e32 v206, v132
	v_add_f32_e32 v132, 0, v197
	v_add_f32_e32 v132, v199, v132
	v_add_f32_e32 v132, v195, v132
	v_add_f32_e32 v132, v198, v132
	v_add_f32_e32 v132, v193, v132
	v_add_f32_e32 v132, v196, v132
	v_add_f32_e32 v132, v192, v132
	v_add_f32_e32 v132, v194, v132
	v_add_f32_e32 v132, v189, v132
	v_add_f32_e32 v132, v191, v132
	v_add_f32_e32 v132, v187, v132
	v_add_f32_e32 v132, v190, v132
	v_exp_f32_e32 v146, v146
	v_add_f32_e32 v132, v185, v132
	v_exp_f32_e32 v147, v147
	v_add_f32_e32 v132, v188, v132
	v_exp_f32_e32 v144, v144
	v_add_f32_e32 v132, v184, v132
	v_exp_f32_e32 v145, v145
	v_add_f32_e32 v132, v186, v132
	v_exp_f32_e32 v142, v142
	v_add_f32_e32 v132, v146, v132
	v_exp_f32_e32 v143, v143
	v_add_f32_e32 v132, v147, v132
	v_exp_f32_e32 v181, v140
	v_add_f32_e32 v132, v144, v132
	v_exp_f32_e32 v183, v141
	v_add_f32_e32 v132, v145, v132
	v_exp_f32_e32 v200, v138
	v_add_f32_e32 v132, v142, v132
	v_exp_f32_e32 v201, v139
	v_add_f32_e32 v132, v143, v132
	v_exp_f32_e32 v202, v136
	v_add_f32_e32 v132, v181, v132
	v_exp_f32_e32 v203, v137
	v_add_f32_e32 v132, v183, v132
	v_exp_f32_e32 v204, v134
	v_add_f32_e32 v132, v200, v132
	v_exp_f32_e32 v205, v135
	v_add_f32_e32 v132, v201, v132
	v_add_f32_e32 v132, v202, v132
	v_exp_f32_e32 v207, v133
	v_add_f32_e32 v132, v203, v132
	v_add_f32_e32 v132, v204, v132
	v_add_f32_e32 v132, v205, v132
	v_add_f32_e32 v132, v206, v132
	v_add_f32_e32 v179, v207, v132
	v_mov_b32_e32 v180, v179
	s_nop 1
	v_permlane32_swap_b32_e32 v179, v180
	v_cvt_pk_bf16_f32 v132, v197, v199
	v_cvt_pk_bf16_f32 v133, v195, v198
	v_cvt_pk_bf16_f32 v134, v193, v196
	v_cvt_pk_bf16_f32 v135, v192, v194
	v_cvt_pk_bf16_f32 v136, v189, v191
	v_cvt_pk_bf16_f32 v137, v187, v190
	v_cvt_pk_bf16_f32 v138, v185, v188
	v_cvt_pk_bf16_f32 v139, v184, v186
	v_cvt_pk_bf16_f32 v140, v146, v147
	v_cvt_pk_bf16_f32 v141, v144, v145
	v_cvt_pk_bf16_f32 v142, v142, v143
	v_cvt_pk_bf16_f32 v143, v181, v183
	v_cvt_pk_bf16_f32 v144, v200, v201
	v_cvt_pk_bf16_f32 v145, v202, v203
	v_cvt_pk_bf16_f32 v146, v204, v205
	v_cvt_pk_bf16_f32 v147, v206, v207
	s_nop 0
	v_permlane32_swap_b32_e32 v132, v134
	v_permlane32_swap_b32_e32 v133, v135
	v_permlane32_swap_b32_e32 v136, v138
	v_permlane32_swap_b32_e32 v137, v139
	v_permlane32_swap_b32_e32 v140, v142
	v_permlane32_swap_b32_e32 v141, v143
	v_permlane32_swap_b32_e32 v144, v146
	v_permlane32_swap_b32_e32 v145, v147
	ds_read_b64_tr_b16 v[184:185], v153 offset:0
	ds_read_b64_tr_b16 v[186:187], v153 offset:0x800
	ds_read_b64_tr_b16 v[188:189], v153 offset:0x1000
	ds_read_b64_tr_b16 v[190:191], v153 offset:0x1800
	ds_read_b64_tr_b16 v[192:193], v153 offset:0x2000
	ds_read_b64_tr_b16 v[194:195], v153 offset:0x2800
	ds_read_b64_tr_b16 v[196:197], v153 offset:0x3000
	ds_read_b64_tr_b16 v[198:199], v153 offset:0x3800
	s_nop 0
	s_waitcnt lgkmcnt(6)
	v_mfma_f32_32x32x16_bf16 v[50:65], v[132:135], v[184:187], v[50:65]
	ds_read_b64_tr_b16 v[184:185], v153 offset:0x200
	ds_read_b64_tr_b16 v[186:187], v153 offset:0xa00
	s_waitcnt lgkmcnt(6)
	v_mfma_f32_32x32x16_bf16 v[50:65], v[136:139], v[188:191], v[50:65]
	ds_read_b64_tr_b16 v[188:189], v153 offset:0x1200
	ds_read_b64_tr_b16 v[190:191], v153 offset:0x1a00
	s_waitcnt lgkmcnt(6)
	v_mfma_f32_32x32x16_bf16 v[50:65], v[140:143], v[192:195], v[50:65]
	ds_read_b64_tr_b16 v[192:193], v153 offset:0x2200
	ds_read_b64_tr_b16 v[194:195], v153 offset:0x2a00
	s_waitcnt lgkmcnt(6)
	v_mfma_f32_32x32x16_bf16 v[50:65], v[144:147], v[196:199], v[50:65]
	ds_read_b64_tr_b16 v[196:197], v153 offset:0x3200
	ds_read_b64_tr_b16 v[198:199], v153 offset:0x3a00
	s_waitcnt lgkmcnt(6)
	v_mfma_f32_32x32x16_bf16 v[34:49], v[132:135], v[184:187], v[34:49]
	ds_read_b64_tr_b16 v[184:185], v153 offset:0x400
	ds_read_b64_tr_b16 v[186:187], v153 offset:0xc00
	s_waitcnt lgkmcnt(6)
	v_mfma_f32_32x32x16_bf16 v[34:49], v[136:139], v[188:191], v[34:49]
	ds_read_b64_tr_b16 v[188:189], v153 offset:0x1400
	ds_read_b64_tr_b16 v[190:191], v153 offset:0x1c00
	s_waitcnt lgkmcnt(6)
	v_mfma_f32_32x32x16_bf16 v[34:49], v[140:143], v[192:195], v[34:49]
	ds_read_b64_tr_b16 v[192:193], v153 offset:0x2400
	ds_read_b64_tr_b16 v[194:195], v153 offset:0x2c00
	s_waitcnt lgkmcnt(6)
	v_mfma_f32_32x32x16_bf16 v[34:49], v[144:147], v[196:199], v[34:49]
	ds_read_b64_tr_b16 v[196:197], v153 offset:0x3400
	ds_read_b64_tr_b16 v[198:199], v153 offset:0x3c00
	s_waitcnt lgkmcnt(6)
	v_mfma_f32_32x32x16_bf16 v[18:33], v[132:135], v[184:187], v[18:33]
	ds_read_b64_tr_b16 v[184:185], v153 offset:0x600
	ds_read_b64_tr_b16 v[186:187], v153 offset:0xe00
	s_waitcnt lgkmcnt(6)
	v_mfma_f32_32x32x16_bf16 v[18:33], v[136:139], v[188:191], v[18:33]
	ds_read_b64_tr_b16 v[188:189], v153 offset:0x1600
	ds_read_b64_tr_b16 v[190:191], v153 offset:0x1e00
	s_waitcnt lgkmcnt(6)
	v_mfma_f32_32x32x16_bf16 v[18:33], v[140:143], v[192:195], v[18:33]
	ds_read_b64_tr_b16 v[192:193], v153 offset:0x2600
	ds_read_b64_tr_b16 v[194:195], v153 offset:0x2e00
	s_waitcnt lgkmcnt(6)
	v_mfma_f32_32x32x16_bf16 v[18:33], v[144:147], v[196:199], v[18:33]
	ds_read_b64_tr_b16 v[196:197], v153 offset:0x3600
	ds_read_b64_tr_b16 v[198:199], v153 offset:0x3e00
	s_waitcnt lgkmcnt(6)
	v_mfma_f32_32x32x16_bf16 v[2:17], v[132:135], v[184:187], v[2:17]
	s_waitcnt lgkmcnt(4)
	v_mfma_f32_32x32x16_bf16 v[2:17], v[136:139], v[188:191], v[2:17]
	s_waitcnt lgkmcnt(2)
	v_mfma_f32_32x32x16_bf16 v[2:17], v[140:143], v[192:195], v[2:17]
	s_waitcnt lgkmcnt(0)
	v_mfma_f32_32x32x16_bf16 v[2:17], v[144:147], v[196:199], v[2:17]
	s_cmp_le_i32 s9, s25
	s_cbranch_scc1 .LBB0_825
	v_add_u32_e32 v132, 64, v169
	v_cmp_gt_i32_e64 s[92:93], 26, v132
	v_cmp_gt_i32_e64 s[94:95], 27, v132
	v_cmp_gt_i32_e64 s[90:91], 25, v132
	s_and_b64 s[92:93], s[94:95], s[92:93]
	v_cmp_gt_i32_e64 s[88:89], 24, v132
	s_and_b64 s[90:91], s[92:93], s[90:91]
	v_cmp_gt_i32_e64 s[86:87], 19, v132
	s_and_b64 s[88:89], s[90:91], s[88:89]
	v_cmp_gt_i32_e64 s[84:85], 18, v132
	s_and_b64 s[86:87], s[88:89], s[86:87]
	v_cmp_gt_i32_e64 s[82:83], 17, v132
	s_and_b64 s[84:85], s[86:87], s[84:85]
	v_cmp_gt_i32_e64 s[80:81], 16, v132
	s_and_b64 s[82:83], s[84:85], s[82:83]
	v_cmp_gt_i32_e64 s[78:79], 11, v132
	s_and_b64 s[80:81], s[82:83], s[80:81]
	v_cmp_gt_i32_e64 s[76:77], 10, v132
	s_and_b64 s[78:79], s[80:81], s[78:79]
	v_cmp_gt_i32_e64 s[74:75], 9, v132
	s_and_b64 s[76:77], s[78:79], s[76:77]
	v_cmp_gt_i32_e64 s[72:73], 8, v132
	s_and_b64 s[74:75], s[76:77], s[74:75]
	v_cmp_gt_i32_e64 s[70:71], 3, v132
	s_and_b64 s[72:73], s[74:75], s[72:73]
	v_cmp_gt_i32_e64 s[68:69], 2, v132
	s_and_b64 s[70:71], s[72:73], s[70:71]
	v_cmp_gt_i32_e64 s[2:3], 1, v132
	s_and_b64 s[68:69], s[70:71], s[68:69]
	v_cmp_gt_i32_e64 s[0:1], 0, v132
	s_and_b64 s[2:3], s[68:69], s[2:3]
	s_and_b64 s[0:1], s[2:3], s[0:1]
	v_cmp_gt_i32_e64 s[66:67], 58, v132
	v_cndmask_b32_e64 v82, v82, v175, s[0:1]
	v_cmp_gt_i32_e64 s[0:1], 59, v132
	v_cmp_gt_i32_e64 s[64:65], 57, v132
	v_cmp_gt_i32_e64 s[62:63], 56, v132
	v_cndmask_b32_e64 v81, v81, v175, s[0:1]
	s_and_b64 s[0:1], s[0:1], s[66:67]
	v_cndmask_b32_e64 v80, v80, v175, s[0:1]
	s_and_b64 s[0:1], s[0:1], s[64:65]
	v_cmp_gt_i32_e64 s[60:61], 51, v132
	v_cndmask_b32_e64 v79, v79, v175, s[0:1]
	s_and_b64 s[0:1], s[0:1], s[62:63]
	v_cmp_gt_i32_e64 s[58:59], 50, v132
	v_cndmask_b32_e64 v78, v78, v175, s[0:1]
	s_and_b64 s[0:1], s[0:1], s[60:61]
	v_cmp_gt_i32_e64 s[56:57], 49, v132
	v_cndmask_b32_e64 v77, v77, v175, s[0:1]
	s_and_b64 s[0:1], s[0:1], s[58:59]
	v_cmp_gt_i32_e64 s[54:55], 48, v132
	v_cndmask_b32_e64 v76, v76, v175, s[0:1]
	s_and_b64 s[0:1], s[0:1], s[56:57]
	v_cmp_gt_i32_e64 s[52:53], 43, v132
	v_cndmask_b32_e64 v75, v75, v175, s[0:1]
	s_and_b64 s[0:1], s[0:1], s[54:55]
	v_cmp_gt_i32_e64 s[50:51], 42, v132
	v_cndmask_b32_e64 v74, v74, v175, s[0:1]
	s_and_b64 s[0:1], s[0:1], s[52:53]
	v_cmp_gt_i32_e64 s[48:49], 41, v132
	v_cndmask_b32_e64 v73, v73, v175, s[0:1]
	s_and_b64 s[0:1], s[0:1], s[50:51]
	v_cmp_gt_i32_e64 s[46:47], 40, v132
	v_cndmask_b32_e64 v72, v72, v175, s[0:1]
	s_and_b64 s[0:1], s[0:1], s[48:49]
	v_cmp_gt_i32_e64 s[44:45], 35, v132
	v_cndmask_b32_e64 v71, v71, v175, s[0:1]
	s_and_b64 s[0:1], s[0:1], s[46:47]
	v_cmp_gt_i32_e64 s[42:43], 34, v132
	v_cndmask_b32_e64 v70, v70, v175, s[0:1]
	s_and_b64 s[0:1], s[0:1], s[44:45]
	v_cmp_gt_i32_e64 s[40:41], 33, v132
	v_cndmask_b32_e64 v69, v69, v175, s[0:1]
	s_and_b64 s[0:1], s[0:1], s[42:43]
	v_cmp_gt_i32_e32 vcc, 32, v132
	v_cndmask_b32_e64 v68, v68, v175, s[0:1]
	s_and_b64 s[0:1], s[0:1], s[40:41]
	s_and_b64 vcc, s[0:1], vcc
	v_cndmask_b32_e64 v97, v97, v175, s[94:95]
	v_cndmask_b32_e64 v96, v96, v175, s[92:93]
	v_cndmask_b32_e64 v95, v95, v175, s[90:91]
	v_cndmask_b32_e64 v94, v94, v175, s[88:89]
	v_cndmask_b32_e64 v93, v93, v175, s[86:87]
	v_cndmask_b32_e64 v92, v92, v175, s[84:85]
	v_cndmask_b32_e64 v91, v91, v175, s[82:83]
	v_cndmask_b32_e64 v90, v90, v175, s[80:81]
	v_cndmask_b32_e64 v89, v89, v175, s[78:79]
	v_cndmask_b32_e64 v88, v88, v175, s[76:77]
	v_cndmask_b32_e64 v87, v87, v175, s[74:75]
	v_cndmask_b32_e64 v86, v86, v175, s[72:73]
	v_cndmask_b32_e64 v85, v85, v175, s[70:71]
	v_cndmask_b32_e64 v84, v84, v175, s[68:69]
	v_cndmask_b32_e64 v83, v83, v175, s[2:3]
	v_cndmask_b32_e64 v67, v67, v175, s[0:1]
	v_cndmask_b32_e32 v66, v66, v175, vcc

.LBB0_831:
	ds_read_b128 v[228:231], v159 offset:32768
	ds_read_b128 v[232:235], v160 offset:32768
	ds_read_b128 v[236:239], v159 offset:40960
	ds_read_b128 v[248:251], v160 offset:40960
	ds_read_b128 v[252:255], v161 offset:32768
	s_waitcnt lgkmcnt(4)
	v_mfma_f32_32x32x16_bf16 v[82:97], v[228:231], v[110:113], 0
	ds_read_b128 v[228:231], v161 offset:40960
	s_waitcnt lgkmcnt(4)
	v_mfma_f32_32x32x16_bf16 v[82:97], v[232:235], v[106:109], v[82:97]
	ds_read_b128 v[232:235], v162 offset:32768
	s_waitcnt lgkmcnt(4)
	v_mfma_f32_32x32x16_bf16 v[66:81], v[236:239], v[110:113], 0
	ds_read_b128 v[236:239], v162 offset:40960
	s_waitcnt lgkmcnt(4)
	v_mfma_f32_32x32x16_bf16 v[66:81], v[248:251], v[106:109], v[66:81]
	s_waitcnt lgkmcnt(3)
	v_mfma_f32_32x32x16_bf16 v[82:97], v[252:255], v[102:105], v[82:97]
	s_waitcnt lgkmcnt(2)
	v_mfma_f32_32x32x16_bf16 v[66:81], v[228:231], v[102:105], v[66:81]
	s_waitcnt lgkmcnt(1)
	v_mfma_f32_32x32x16_bf16 v[82:97], v[232:235], v[98:101], v[82:97]
	s_waitcnt lgkmcnt(0)
	v_mfma_f32_32x32x16_bf16 v[66:81], v[236:239], v[98:101], v[66:81]
	v_add_f32_e32 v182, 0, v146
	v_add_f32_e32 v182, v168, v182
	v_add_f32_e32 v182, v144, v182
	v_add_f32_e32 v182, v147, v182
	v_add_f32_e32 v182, v142, v182
	v_add_f32_e32 v182, v145, v182
	v_add_f32_e32 v182, v141, v182
	v_add_f32_e32 v182, v143, v182
	v_add_f32_e32 v182, v138, v182
	v_add_f32_e32 v182, v140, v182
	v_add_f32_e32 v182, v136, v182
	v_add_f32_e32 v182, v139, v182
	v_exp_f32_e32 v199, v184
	v_add_f32_e32 v182, v134, v182
	v_exp_f32_e32 v200, v185
	v_add_f32_e32 v182, v137, v182
	v_exp_f32_e32 v201, v186
	v_add_f32_e32 v182, v133, v182
	v_exp_f32_e32 v202, v187
	v_add_f32_e32 v182, v135, v182
	v_exp_f32_e32 v188, v188
	v_add_f32_e32 v182, v199, v182
	v_exp_f32_e32 v189, v189
	v_add_f32_e32 v182, v200, v182
	v_exp_f32_e32 v190, v190
	v_add_f32_e32 v182, v201, v182
	v_exp_f32_e32 v191, v191
	v_add_f32_e32 v182, v202, v182
	v_exp_f32_e32 v192, v192
	v_add_f32_e32 v182, v188, v182
	v_exp_f32_e32 v193, v193
	v_add_f32_e32 v182, v189, v182
	v_exp_f32_e32 v194, v194
	v_add_f32_e32 v182, v190, v182
	v_exp_f32_e32 v195, v195
	v_add_f32_e32 v182, v191, v182
	v_exp_f32_e32 v196, v196
	v_add_f32_e32 v182, v192, v182
	v_exp_f32_e32 v197, v197
	v_add_f32_e32 v182, v193, v182
	v_exp_f32_e32 v198, v198
	v_add_f32_e32 v182, v194, v182
	v_exp_f32_e32 v203, v183
	v_add_f32_e32 v182, v195, v182
	v_add_f32_e32 v182, v196, v182
	v_add_f32_e32 v182, v197, v182
	v_add_f32_e32 v182, v198, v182
	v_add_f32_e32 v182, v203, v182
	v_mov_b32_e32 v183, v182
	s_nop 1
	v_permlane32_swap_b32_e32 v182, v183
	v_cvt_pk_bf16_f32 v184, v146, v168
	v_cvt_pk_bf16_f32 v185, v144, v147
	v_cvt_pk_bf16_f32 v186, v142, v145
	v_cvt_pk_bf16_f32 v187, v141, v143
	v_cvt_pk_bf16_f32 v138, v138, v140
	v_cvt_pk_bf16_f32 v139, v136, v139
	v_cvt_pk_bf16_f32 v140, v134, v137
	v_cvt_pk_bf16_f32 v141, v133, v135
	v_cvt_pk_bf16_f32 v134, v199, v200
	v_cvt_pk_bf16_f32 v135, v201, v202
	v_cvt_pk_bf16_f32 v136, v188, v189
	v_cvt_pk_bf16_f32 v137, v190, v191
	v_cvt_pk_bf16_f32 v142, v192, v193
	v_cvt_pk_bf16_f32 v143, v194, v195
	v_cvt_pk_bf16_f32 v144, v196, v197
	v_cvt_pk_bf16_f32 v145, v198, v203
	s_nop 0
	v_permlane32_swap_b32_e32 v184, v186
	v_permlane32_swap_b32_e32 v185, v187
	v_permlane32_swap_b32_e32 v138, v140
	v_permlane32_swap_b32_e32 v139, v141
	v_permlane32_swap_b32_e32 v134, v136
	v_permlane32_swap_b32_e32 v135, v137
	v_permlane32_swap_b32_e32 v142, v144
	v_permlane32_swap_b32_e32 v143, v145
	ds_read_b64_tr_b16 v[188:189], v153 offset:0x4000
	ds_read_b64_tr_b16 v[190:191], v153 offset:0x4800
	ds_read_b64_tr_b16 v[192:193], v153 offset:0x5000
	ds_read_b64_tr_b16 v[194:195], v153 offset:0x5800
	ds_read_b64_tr_b16 v[196:197], v153 offset:0x6000
	ds_read_b64_tr_b16 v[198:199], v153 offset:0x6800
	ds_read_b64_tr_b16 v[200:201], v153 offset:0x7000
	ds_read_b64_tr_b16 v[202:203], v153 offset:0x7800
	s_nop 0
	s_waitcnt lgkmcnt(6)
	v_mfma_f32_32x32x16_bf16 v[50:65], v[184:187], v[188:191], v[50:65]
	ds_read_b64_tr_b16 v[188:189], v153 offset:0x4200
	ds_read_b64_tr_b16 v[190:191], v153 offset:0x4a00
	s_waitcnt lgkmcnt(6)
	v_mfma_f32_32x32x16_bf16 v[50:65], v[138:141], v[192:195], v[50:65]
	ds_read_b64_tr_b16 v[192:193], v153 offset:0x5200
	ds_read_b64_tr_b16 v[194:195], v153 offset:0x5a00
	s_waitcnt lgkmcnt(6)
	v_mfma_f32_32x32x16_bf16 v[50:65], v[134:137], v[196:199], v[50:65]
	ds_read_b64_tr_b16 v[196:197], v153 offset:0x6200
	ds_read_b64_tr_b16 v[198:199], v153 offset:0x6a00
	s_waitcnt lgkmcnt(6)
	v_mfma_f32_32x32x16_bf16 v[50:65], v[142:145], v[200:203], v[50:65]
	ds_read_b64_tr_b16 v[200:201], v153 offset:0x7200
	ds_read_b64_tr_b16 v[202:203], v153 offset:0x7a00
	s_waitcnt lgkmcnt(6)
	v_mfma_f32_32x32x16_bf16 v[34:49], v[184:187], v[188:191], v[34:49]
	ds_read_b64_tr_b16 v[188:189], v153 offset:0x4400
	ds_read_b64_tr_b16 v[190:191], v153 offset:0x4c00
	s_waitcnt lgkmcnt(6)
	v_mfma_f32_32x32x16_bf16 v[34:49], v[138:141], v[192:195], v[34:49]
	ds_read_b64_tr_b16 v[192:193], v153 offset:0x5400
	ds_read_b64_tr_b16 v[194:195], v153 offset:0x5c00
	s_waitcnt lgkmcnt(6)
	v_mfma_f32_32x32x16_bf16 v[34:49], v[134:137], v[196:199], v[34:49]
	ds_read_b64_tr_b16 v[196:197], v153 offset:0x6400
	ds_read_b64_tr_b16 v[198:199], v153 offset:0x6c00
	s_waitcnt lgkmcnt(6)
	v_mfma_f32_32x32x16_bf16 v[34:49], v[142:145], v[200:203], v[34:49]
	ds_read_b64_tr_b16 v[200:201], v153 offset:0x7400
	ds_read_b64_tr_b16 v[202:203], v153 offset:0x7c00
	s_waitcnt lgkmcnt(6)
	v_mfma_f32_32x32x16_bf16 v[18:33], v[184:187], v[188:191], v[18:33]
	ds_read_b64_tr_b16 v[188:189], v153 offset:0x4600
	ds_read_b64_tr_b16 v[190:191], v153 offset:0x4e00
	s_waitcnt lgkmcnt(6)
	v_mfma_f32_32x32x16_bf16 v[18:33], v[138:141], v[192:195], v[18:33]
	ds_read_b64_tr_b16 v[192:193], v153 offset:0x5600
	ds_read_b64_tr_b16 v[194:195], v153 offset:0x5e00
	s_waitcnt lgkmcnt(6)
	v_mfma_f32_32x32x16_bf16 v[18:33], v[134:137], v[196:199], v[18:33]
	ds_read_b64_tr_b16 v[196:197], v153 offset:0x6600
	ds_read_b64_tr_b16 v[198:199], v153 offset:0x6e00
	s_waitcnt lgkmcnt(6)
	v_mfma_f32_32x32x16_bf16 v[18:33], v[142:145], v[200:203], v[18:33]
	ds_read_b64_tr_b16 v[200:201], v153 offset:0x7600
	ds_read_b64_tr_b16 v[202:203], v153 offset:0x7e00
	s_waitcnt lgkmcnt(6)
	v_mfma_f32_32x32x16_bf16 v[2:17], v[184:187], v[188:191], v[2:17]
	s_waitcnt lgkmcnt(4)
	v_mfma_f32_32x32x16_bf16 v[2:17], v[138:141], v[192:195], v[2:17]
	s_waitcnt lgkmcnt(2)
	v_mfma_f32_32x32x16_bf16 v[2:17], v[134:137], v[196:199], v[2:17]
	s_waitcnt lgkmcnt(0)
	v_mfma_f32_32x32x16_bf16 v[2:17], v[142:145], v[200:203], v[2:17]
	s_add_i32 s0, s9, 64
	s_cmp_le_i32 s0, s25
	s_cbranch_scc1 .LBB0_833
	v_cmp_gt_i32_e64 s[92:93], 26, v169
	v_cmp_gt_i32_e64 s[94:95], 27, v169
	v_cmp_gt_i32_e64 s[90:91], 25, v169
	s_and_b64 s[92:93], s[94:95], s[92:93]
	v_cmp_gt_i32_e64 s[88:89], 24, v169
	s_and_b64 s[90:91], s[92:93], s[90:91]
	v_cmp_gt_i32_e64 s[86:87], 19, v169
	s_and_b64 s[88:89], s[90:91], s[88:89]
	v_cmp_gt_i32_e64 s[84:85], 18, v169
	s_and_b64 s[86:87], s[88:89], s[86:87]
	v_cmp_gt_i32_e64 s[82:83], 17, v169
	s_and_b64 s[84:85], s[86:87], s[84:85]
	v_cmp_gt_i32_e64 s[80:81], 16, v169
	s_and_b64 s[82:83], s[84:85], s[82:83]
	v_cmp_gt_i32_e64 s[78:79], 11, v169
	s_and_b64 s[80:81], s[82:83], s[80:81]
	v_cmp_gt_i32_e64 s[76:77], 10, v169
	s_and_b64 s[78:79], s[80:81], s[78:79]
	v_cmp_gt_i32_e64 s[74:75], 9, v169
	s_and_b64 s[76:77], s[78:79], s[76:77]
	v_cmp_gt_i32_e64 s[72:73], 8, v169
	s_and_b64 s[74:75], s[76:77], s[74:75]
	v_cmp_gt_i32_e64 s[70:71], 3, v169
	s_and_b64 s[72:73], s[74:75], s[72:73]
	v_cmp_gt_i32_e64 s[68:69], 2, v169
	s_and_b64 s[70:71], s[72:73], s[70:71]
	v_cmp_gt_i32_e64 s[2:3], 1, v169
	s_and_b64 s[68:69], s[70:71], s[68:69]
	v_cmp_gt_i32_e64 s[0:1], 0, v169
	s_and_b64 s[2:3], s[68:69], s[2:3]
	s_and_b64 s[0:1], s[2:3], s[0:1]
	v_cmp_gt_i32_e64 s[66:67], 58, v169
	v_cndmask_b32_e64 v82, v82, v175, s[0:1]
	v_cmp_gt_i32_e64 s[0:1], 59, v169
	v_cmp_gt_i32_e64 s[64:65], 57, v169
	v_cmp_gt_i32_e64 s[62:63], 56, v169
	v_cndmask_b32_e64 v81, v81, v175, s[0:1]
	s_and_b64 s[0:1], s[0:1], s[66:67]
	v_cndmask_b32_e64 v80, v80, v175, s[0:1]
	s_and_b64 s[0:1], s[0:1], s[64:65]
	v_cmp_gt_i32_e64 s[60:61], 51, v169
	v_cndmask_b32_e64 v79, v79, v175, s[0:1]
	s_and_b64 s[0:1], s[0:1], s[62:63]
	v_cmp_gt_i32_e64 s[58:59], 50, v169
	v_cndmask_b32_e64 v78, v78, v175, s[0:1]
	s_and_b64 s[0:1], s[0:1], s[60:61]
	v_cmp_gt_i32_e64 s[56:57], 49, v169
	v_cndmask_b32_e64 v77, v77, v175, s[0:1]
	s_and_b64 s[0:1], s[0:1], s[58:59]
	v_cmp_gt_i32_e64 s[54:55], 48, v169
	v_cndmask_b32_e64 v76, v76, v175, s[0:1]
	s_and_b64 s[0:1], s[0:1], s[56:57]
	v_cmp_gt_i32_e64 s[52:53], 43, v169
	v_cndmask_b32_e64 v75, v75, v175, s[0:1]
	s_and_b64 s[0:1], s[0:1], s[54:55]
	v_cmp_gt_i32_e64 s[50:51], 42, v169
	v_cndmask_b32_e64 v74, v74, v175, s[0:1]
	s_and_b64 s[0:1], s[0:1], s[52:53]
	v_cmp_gt_i32_e64 s[48:49], 41, v169
	v_cndmask_b32_e64 v73, v73, v175, s[0:1]
	s_and_b64 s[0:1], s[0:1], s[50:51]
	v_cmp_gt_i32_e64 s[46:47], 40, v169
	v_cndmask_b32_e64 v72, v72, v175, s[0:1]
	s_and_b64 s[0:1], s[0:1], s[48:49]
	v_cmp_gt_i32_e64 s[44:45], 35, v169
	v_cndmask_b32_e64 v71, v71, v175, s[0:1]
	s_and_b64 s[0:1], s[0:1], s[46:47]
	v_cmp_gt_i32_e64 s[42:43], 34, v169
	v_cndmask_b32_e64 v70, v70, v175, s[0:1]
	s_and_b64 s[0:1], s[0:1], s[44:45]
	v_cmp_gt_i32_e64 s[40:41], 33, v169
	v_cndmask_b32_e64 v69, v69, v175, s[0:1]
	s_and_b64 s[0:1], s[0:1], s[42:43]
	v_cmp_gt_i32_e32 vcc, 32, v169
	v_cndmask_b32_e64 v68, v68, v175, s[0:1]
	s_and_b64 s[0:1], s[0:1], s[40:41]
	s_and_b64 vcc, s[0:1], vcc
	v_cndmask_b32_e64 v97, v97, v175, s[94:95]
	v_cndmask_b32_e64 v96, v96, v175, s[92:93]
	v_cndmask_b32_e64 v95, v95, v175, s[90:91]
	v_cndmask_b32_e64 v94, v94, v175, s[88:89]
	v_cndmask_b32_e64 v93, v93, v175, s[86:87]
	v_cndmask_b32_e64 v92, v92, v175, s[84:85]
	v_cndmask_b32_e64 v91, v91, v175, s[82:83]
	v_cndmask_b32_e64 v90, v90, v175, s[80:81]
	v_cndmask_b32_e64 v89, v89, v175, s[78:79]
	v_cndmask_b32_e64 v88, v88, v175, s[76:77]
	v_cndmask_b32_e64 v87, v87, v175, s[74:75]
	v_cndmask_b32_e64 v86, v86, v175, s[72:73]
	v_cndmask_b32_e64 v85, v85, v175, s[70:71]
	v_cndmask_b32_e64 v84, v84, v175, s[68:69]
	v_cndmask_b32_e64 v83, v83, v175, s[2:3]
	v_cndmask_b32_e64 v67, v67, v175, s[0:1]
	v_cndmask_b32_e32 v66, v66, v175, vcc

.LBB0_842:
	ds_read_b128 v[66:69], v159 offset:49152
	ds_read_b128 v[70:73], v159 offset:57344
	s_waitcnt lgkmcnt(1)
	v_mfma_f32_32x32x16_bf16 v[82:97], v[66:69], v[110:113], 0
	s_waitcnt lgkmcnt(0)
	v_mfma_f32_32x32x16_bf16 v[66:81], v[70:73], v[110:113], 0
	ds_read_b128 v[110:113], v160 offset:49152
	s_waitcnt vmcnt(1)
	ds_read_b128 v[116:119], v160 offset:57344
	s_waitcnt lgkmcnt(1)
	v_mfma_f32_32x32x16_bf16 v[82:97], v[110:113], v[106:109], v[82:97]
	s_waitcnt lgkmcnt(0)
	v_mfma_f32_32x32x16_bf16 v[66:81], v[116:119], v[106:109], v[66:81]
	ds_read_b128 v[106:109], v161 offset:49152
	ds_read_b128 v[110:113], v161 offset:57344
	s_waitcnt lgkmcnt(1)
	v_mfma_f32_32x32x16_bf16 v[82:97], v[106:109], v[102:105], v[82:97]
	s_waitcnt lgkmcnt(0)
	v_mfma_f32_32x32x16_bf16 v[66:81], v[110:113], v[102:105], v[66:81]
	ds_read_b128 v[102:105], v162 offset:49152
	ds_read_b128 v[106:109], v162 offset:57344
	s_waitcnt lgkmcnt(1)
	v_mfma_f32_32x32x16_bf16 v[82:97], v[102:105], v[98:101], v[82:97]
	s_waitcnt lgkmcnt(0)
	v_mfma_f32_32x32x16_bf16 v[66:81], v[106:109], v[98:101], v[66:81]
	v_add_f32_e32 v98, 0, v197
	v_add_f32_e32 v98, v199, v98
	v_add_f32_e32 v98, v195, v98
	v_add_f32_e32 v98, v198, v98
	v_add_f32_e32 v98, v193, v98
	v_add_f32_e32 v98, v196, v98
	v_add_f32_e32 v98, v192, v98
	v_add_f32_e32 v98, v194, v98
	v_add_f32_e32 v98, v189, v98
	v_add_f32_e32 v98, v191, v98
	v_add_f32_e32 v98, v187, v98
	v_add_f32_e32 v98, v190, v98
	v_exp_f32_e32 v108, v146
	v_add_f32_e32 v98, v185, v98
	v_exp_f32_e32 v109, v147
	v_add_f32_e32 v98, v188, v98
	v_exp_f32_e32 v110, v144
	v_add_f32_e32 v98, v184, v98
	v_exp_f32_e32 v111, v145
	v_add_f32_e32 v98, v186, v98
	v_exp_f32_e32 v112, v142
	v_add_f32_e32 v98, v108, v98
	v_exp_f32_e32 v113, v143
	v_add_f32_e32 v98, v109, v98
	v_exp_f32_e32 v115, v140
	v_add_f32_e32 v98, v110, v98
	v_exp_f32_e32 v116, v141
	v_add_f32_e32 v98, v111, v98
	v_exp_f32_e32 v117, v138
	v_add_f32_e32 v98, v112, v98
	v_exp_f32_e32 v118, v139
	v_add_f32_e32 v98, v113, v98
	v_exp_f32_e32 v119, v136
	v_add_f32_e32 v98, v115, v98
	v_exp_f32_e32 v120, v137
	v_add_f32_e32 v98, v116, v98
	v_exp_f32_e32 v121, v134
	v_add_f32_e32 v98, v117, v98
	v_exp_f32_e32 v122, v135
	v_add_f32_e32 v98, v118, v98
	v_exp_f32_e32 v123, v132
	v_add_f32_e32 v98, v119, v98
	v_exp_f32_e32 v124, v133
	v_add_f32_e32 v98, v120, v98
	v_add_f32_e32 v98, v121, v98
	v_add_f32_e32 v98, v122, v98
	v_add_f32_e32 v98, v123, v98
	v_add_f32_e32 v98, v124, v98
	v_mov_b32_e32 v99, v98
	s_nop 1
	v_permlane32_swap_b32_e32 v98, v99
	v_cvt_pk_bf16_f32 v100, v197, v199
	v_cvt_pk_bf16_f32 v101, v195, v198
	v_cvt_pk_bf16_f32 v102, v193, v196
	v_cvt_pk_bf16_f32 v103, v192, v194
	v_cvt_pk_bf16_f32 v104, v189, v191
	v_cvt_pk_bf16_f32 v105, v187, v190
	v_cvt_pk_bf16_f32 v106, v185, v188
	v_cvt_pk_bf16_f32 v107, v184, v186
	v_cvt_pk_bf16_f32 v108, v108, v109
	v_cvt_pk_bf16_f32 v109, v110, v111
	v_cvt_pk_bf16_f32 v110, v112, v113
	v_cvt_pk_bf16_f32 v111, v115, v116
	v_cvt_pk_bf16_f32 v116, v117, v118
	v_cvt_pk_bf16_f32 v117, v119, v120
	v_cvt_pk_bf16_f32 v118, v121, v122
	v_cvt_pk_bf16_f32 v119, v123, v124
	s_nop 0
	v_permlane32_swap_b32_e32 v100, v102
	v_permlane32_swap_b32_e32 v101, v103
	v_permlane32_swap_b32_e32 v104, v106
	v_permlane32_swap_b32_e32 v105, v107
	v_permlane32_swap_b32_e32 v108, v110
	v_permlane32_swap_b32_e32 v109, v111
	v_permlane32_swap_b32_e32 v116, v118
	v_permlane32_swap_b32_e32 v117, v119
	ds_read_b64_tr_b16 v[120:121], v153 offset:0
	ds_read_b64_tr_b16 v[122:123], v153 offset:0x800
	ds_read_b64_tr_b16 v[124:125], v153 offset:0x1000
	s_waitcnt vmcnt(0)
	ds_read_b64_tr_b16 v[126:127], v153 offset:0x1800
	ds_read_b64_tr_b16 v[128:129], v153 offset:0x2000
	ds_read_b64_tr_b16 v[130:131], v153 offset:0x2800
	ds_read_b64_tr_b16 v[132:133], v153 offset:0x3000
	ds_read_b64_tr_b16 v[134:135], v153 offset:0x3800
	s_waitcnt lgkmcnt(6)
	v_mfma_f32_32x32x16_bf16 v[50:65], v[100:103], v[120:123], v[50:65]
	ds_read_b64_tr_b16 v[120:121], v153 offset:0x200
	ds_read_b64_tr_b16 v[122:123], v153 offset:0xa00
	s_waitcnt lgkmcnt(6)
	v_mfma_f32_32x32x16_bf16 v[50:65], v[104:107], v[124:127], v[50:65]
	ds_read_b64_tr_b16 v[124:125], v153 offset:0x1200
	ds_read_b64_tr_b16 v[126:127], v153 offset:0x1a00
	s_waitcnt lgkmcnt(6)
	v_mfma_f32_32x32x16_bf16 v[50:65], v[108:111], v[128:131], v[50:65]
	ds_read_b64_tr_b16 v[128:129], v153 offset:0x2200
	ds_read_b64_tr_b16 v[130:131], v153 offset:0x2a00
	s_waitcnt lgkmcnt(6)
	v_mfma_f32_32x32x16_bf16 v[50:65], v[116:119], v[132:135], v[50:65]
	ds_read_b64_tr_b16 v[132:133], v153 offset:0x3200
	ds_read_b64_tr_b16 v[134:135], v153 offset:0x3a00
	s_waitcnt lgkmcnt(6)
	v_mfma_f32_32x32x16_bf16 v[34:49], v[100:103], v[120:123], v[34:49]
	ds_read_b64_tr_b16 v[120:121], v153 offset:0x400
	ds_read_b64_tr_b16 v[122:123], v153 offset:0xc00
	s_waitcnt lgkmcnt(6)
	v_mfma_f32_32x32x16_bf16 v[34:49], v[104:107], v[124:127], v[34:49]
	ds_read_b64_tr_b16 v[124:125], v153 offset:0x1400
	ds_read_b64_tr_b16 v[126:127], v153 offset:0x1c00
	s_waitcnt lgkmcnt(6)
	v_mfma_f32_32x32x16_bf16 v[34:49], v[108:111], v[128:131], v[34:49]
	ds_read_b64_tr_b16 v[128:129], v153 offset:0x2400
	ds_read_b64_tr_b16 v[130:131], v153 offset:0x2c00
	s_waitcnt lgkmcnt(6)
	v_mfma_f32_32x32x16_bf16 v[34:49], v[116:119], v[132:135], v[34:49]
	ds_read_b64_tr_b16 v[132:133], v153 offset:0x3400
	ds_read_b64_tr_b16 v[134:135], v153 offset:0x3c00
	s_waitcnt lgkmcnt(6)
	v_mfma_f32_32x32x16_bf16 v[18:33], v[100:103], v[120:123], v[18:33]
	ds_read_b64_tr_b16 v[120:121], v153 offset:0x600
	ds_read_b64_tr_b16 v[122:123], v153 offset:0xe00
	s_waitcnt lgkmcnt(6)
	v_mfma_f32_32x32x16_bf16 v[18:33], v[104:107], v[124:127], v[18:33]
	ds_read_b64_tr_b16 v[124:125], v153 offset:0x1600
	ds_read_b64_tr_b16 v[126:127], v153 offset:0x1e00
	s_waitcnt lgkmcnt(6)
	v_mfma_f32_32x32x16_bf16 v[18:33], v[108:111], v[128:131], v[18:33]
	ds_read_b64_tr_b16 v[128:129], v153 offset:0x2600
	ds_read_b64_tr_b16 v[130:131], v153 offset:0x2e00
	s_waitcnt lgkmcnt(6)
	v_mfma_f32_32x32x16_bf16 v[18:33], v[116:119], v[132:135], v[18:33]
	ds_read_b64_tr_b16 v[132:133], v153 offset:0x3600
	ds_read_b64_tr_b16 v[134:135], v153 offset:0x3e00
	s_waitcnt lgkmcnt(6)
	v_mfma_f32_32x32x16_bf16 v[2:17], v[100:103], v[120:123], v[2:17]
	s_lshl_b32 s0, s27, 6
	s_add_i32 s1, s0, -1
	s_cmp_gt_i32 s1, s25
	s_waitcnt lgkmcnt(4)
	v_mfma_f32_32x32x16_bf16 v[2:17], v[104:107], v[124:127], v[2:17]
	s_waitcnt lgkmcnt(2)
	v_mfma_f32_32x32x16_bf16 v[2:17], v[108:111], v[128:131], v[2:17]
	s_waitcnt lgkmcnt(0)
	v_mfma_f32_32x32x16_bf16 v[2:17], v[116:119], v[132:135], v[2:17]
	s_cbranch_scc0 .LBB0_844
	v_subrev_u32_e32 v100, s0, v156
	v_add_u32_e32 v100, 64, v100
	v_cmp_gt_i32_e64 s[90:91], 26, v100
	v_cmp_gt_i32_e64 s[92:93], 27, v100
	v_cmp_gt_i32_e64 s[88:89], 25, v100
	s_and_b64 s[90:91], s[92:93], s[90:91]
	v_cmp_gt_i32_e64 s[86:87], 24, v100
	s_and_b64 s[88:89], s[90:91], s[88:89]
	v_cmp_gt_i32_e64 s[84:85], 19, v100
	s_and_b64 s[86:87], s[88:89], s[86:87]
	v_cmp_gt_i32_e64 s[82:83], 18, v100
	s_and_b64 s[84:85], s[86:87], s[84:85]
	v_cmp_gt_i32_e64 s[80:81], 17, v100
	s_and_b64 s[82:83], s[84:85], s[82:83]
	v_cmp_gt_i32_e64 s[78:79], 16, v100
	s_and_b64 s[80:81], s[82:83], s[80:81]
	v_cmp_gt_i32_e64 s[76:77], 11, v100
	s_and_b64 s[78:79], s[80:81], s[78:79]
	v_cmp_gt_i32_e64 s[74:75], 10, v100
	s_and_b64 s[76:77], s[78:79], s[76:77]
	v_cmp_gt_i32_e64 s[72:73], 9, v100
	s_and_b64 s[74:75], s[76:77], s[74:75]
	v_cmp_gt_i32_e64 s[70:71], 8, v100
	s_and_b64 s[72:73], s[74:75], s[72:73]
	v_cmp_gt_i32_e64 s[68:69], 3, v100
	s_and_b64 s[70:71], s[72:73], s[70:71]
	v_cmp_gt_i32_e64 s[66:67], 2, v100
	s_and_b64 s[68:69], s[70:71], s[68:69]
	v_cmp_gt_i32_e64 s[2:3], 1, v100
	s_and_b64 s[66:67], s[68:69], s[66:67]
	v_cmp_gt_i32_e64 s[0:1], 0, v100
	s_and_b64 s[2:3], s[66:67], s[2:3]
	s_and_b64 s[0:1], s[2:3], s[0:1]
	v_cmp_gt_i32_e64 s[64:65], 58, v100
	v_cndmask_b32_e64 v82, v82, v175, s[0:1]
	v_cmp_gt_i32_e64 s[0:1], 59, v100
	v_cmp_gt_i32_e64 s[62:63], 57, v100
	v_cmp_gt_i32_e64 s[60:61], 56, v100
	v_cndmask_b32_e64 v81, v81, v175, s[0:1]
	s_and_b64 s[0:1], s[0:1], s[64:65]
	v_cndmask_b32_e64 v80, v80, v175, s[0:1]
	s_and_b64 s[0:1], s[0:1], s[62:63]
	v_cmp_gt_i32_e64 s[58:59], 51, v100
	v_cndmask_b32_e64 v79, v79, v175, s[0:1]
	s_and_b64 s[0:1], s[0:1], s[60:61]
	v_cmp_gt_i32_e64 s[56:57], 50, v100
	v_cndmask_b32_e64 v78, v78, v175, s[0:1]
	s_and_b64 s[0:1], s[0:1], s[58:59]
	v_cmp_gt_i32_e64 s[54:55], 49, v100
	v_cndmask_b32_e64 v77, v77, v175, s[0:1]
	s_and_b64 s[0:1], s[0:1], s[56:57]
	v_cmp_gt_i32_e64 s[52:53], 48, v100
	v_cndmask_b32_e64 v76, v76, v175, s[0:1]
	s_and_b64 s[0:1], s[0:1], s[54:55]
	v_cmp_gt_i32_e64 s[50:51], 43, v100
	v_cndmask_b32_e64 v75, v75, v175, s[0:1]
	s_and_b64 s[0:1], s[0:1], s[52:53]
	v_cmp_gt_i32_e64 s[48:49], 42, v100
	v_cndmask_b32_e64 v74, v74, v175, s[0:1]
	s_and_b64 s[0:1], s[0:1], s[50:51]
	v_cmp_gt_i32_e64 s[46:47], 41, v100
	v_cndmask_b32_e64 v73, v73, v175, s[0:1]
	s_and_b64 s[0:1], s[0:1], s[48:49]
	v_cmp_gt_i32_e64 s[44:45], 40, v100
	v_cndmask_b32_e64 v72, v72, v175, s[0:1]
	s_and_b64 s[0:1], s[0:1], s[46:47]
	v_cmp_gt_i32_e64 s[42:43], 35, v100
	v_cndmask_b32_e64 v71, v71, v175, s[0:1]
	s_and_b64 s[0:1], s[0:1], s[44:45]
	v_cmp_gt_i32_e64 s[40:41], 34, v100
	v_cndmask_b32_e64 v70, v70, v175, s[0:1]
	s_and_b64 s[0:1], s[0:1], s[42:43]
	v_cmp_gt_i32_e64 s[38:39], 33, v100
	v_cndmask_b32_e64 v69, v69, v175, s[0:1]
	s_and_b64 s[0:1], s[0:1], s[40:41]
	v_cmp_gt_i32_e32 vcc, 32, v100
	v_cndmask_b32_e64 v68, v68, v175, s[0:1]
	s_and_b64 s[0:1], s[0:1], s[38:39]
	s_and_b64 vcc, s[0:1], vcc
	v_cndmask_b32_e64 v97, v97, v175, s[92:93]
	v_cndmask_b32_e64 v96, v96, v175, s[90:91]
	v_cndmask_b32_e64 v95, v95, v175, s[88:89]
	v_cndmask_b32_e64 v94, v94, v175, s[86:87]
	v_cndmask_b32_e64 v93, v93, v175, s[84:85]
	v_cndmask_b32_e64 v92, v92, v175, s[82:83]
	v_cndmask_b32_e64 v91, v91, v175, s[80:81]
	v_cndmask_b32_e64 v90, v90, v175, s[78:79]
	v_cndmask_b32_e64 v89, v89, v175, s[76:77]
	v_cndmask_b32_e64 v88, v88, v175, s[74:75]
	v_cndmask_b32_e64 v87, v87, v175, s[72:73]
	v_cndmask_b32_e64 v86, v86, v175, s[70:71]
	v_cndmask_b32_e64 v85, v85, v175, s[68:69]
	v_cndmask_b32_e64 v84, v84, v175, s[66:67]
	v_cndmask_b32_e64 v83, v83, v175, s[2:3]
	v_cndmask_b32_e64 v67, v67, v175, s[0:1]
	v_cndmask_b32_e32 v66, v66, v175, vcc

.LBB0_848:
	v_cndmask_b32_e64 v101, v101, v168, s[38:39]
	v_mul_f32_e32 v101, 0xbe38aa3b, v101
	v_fmamk_f32 v82, v82, 0x3e38aa3b, v101
	v_fmamk_f32 v66, v66, 0x3e38aa3b, v101
	v_fmamk_f32 v83, v83, 0x3e38aa3b, v101
	v_fmamk_f32 v67, v67, 0x3e38aa3b, v101
	v_fmamk_f32 v84, v84, 0x3e38aa3b, v101
	v_fmamk_f32 v68, v68, 0x3e38aa3b, v101
	v_fmamk_f32 v85, v85, 0x3e38aa3b, v101
	v_fmamk_f32 v69, v69, 0x3e38aa3b, v101
	v_fmamk_f32 v86, v86, 0x3e38aa3b, v101
	v_fmamk_f32 v70, v70, 0x3e38aa3b, v101
	v_fmamk_f32 v87, v87, 0x3e38aa3b, v101
	v_fmamk_f32 v71, v71, 0x3e38aa3b, v101
	v_fmamk_f32 v88, v88, 0x3e38aa3b, v101
	v_fmamk_f32 v72, v72, 0x3e38aa3b, v101
	v_fmamk_f32 v89, v89, 0x3e38aa3b, v101
	v_fmamk_f32 v73, v73, 0x3e38aa3b, v101
	v_fmamk_f32 v90, v90, 0x3e38aa3b, v101
	v_fmamk_f32 v74, v74, 0x3e38aa3b, v101
	v_fmamk_f32 v91, v91, 0x3e38aa3b, v101
	v_fmamk_f32 v75, v75, 0x3e38aa3b, v101
	v_fmamk_f32 v92, v92, 0x3e38aa3b, v101
	v_fmamk_f32 v76, v76, 0x3e38aa3b, v101
	v_fmamk_f32 v93, v93, 0x3e38aa3b, v101
	v_fmamk_f32 v77, v77, 0x3e38aa3b, v101
	v_fmamk_f32 v94, v94, 0x3e38aa3b, v101
	v_fmamk_f32 v78, v78, 0x3e38aa3b, v101
	v_fmamk_f32 v95, v95, 0x3e38aa3b, v101
	v_fmamk_f32 v79, v79, 0x3e38aa3b, v101
	v_fmamk_f32 v96, v96, 0x3e38aa3b, v101
	v_fmamk_f32 v80, v80, 0x3e38aa3b, v101
	v_fmamk_f32 v97, v97, 0x3e38aa3b, v101
	v_fmac_f32_e32 v101, 0x3e38aa3b, v81
	v_exp_f32_e32 v81, v82
	v_exp_f32_e32 v82, v83
	v_exp_f32_e32 v83, v84
	v_exp_f32_e32 v84, v85
	v_exp_f32_e32 v85, v86
	v_exp_f32_e32 v86, v87
	v_exp_f32_e32 v87, v88
	v_exp_f32_e32 v88, v89
	v_exp_f32_e32 v89, v90
	v_exp_f32_e32 v90, v91
	v_exp_f32_e32 v91, v92
	v_exp_f32_e32 v92, v93
	v_exp_f32_e32 v93, v94
	v_exp_f32_e32 v94, v95
	v_exp_f32_e32 v95, v96
	v_exp_f32_e32 v96, v97
	v_exp_f32_e32 v97, v66
	v_add_f32_e32 v66, 0, v81
	v_add_f32_e32 v66, v82, v66
	v_add_f32_e32 v66, v83, v66
	v_add_f32_e32 v66, v84, v66
	v_add_f32_e32 v66, v85, v66
	v_add_f32_e32 v66, v86, v66
	v_add_f32_e32 v66, v87, v66
	v_add_f32_e32 v66, v88, v66
	v_add_f32_e32 v66, v89, v66
	v_add_f32_e32 v66, v90, v66
	v_add_f32_e32 v66, v91, v66
	v_add_f32_e32 v66, v92, v66
	v_add_f32_e32 v66, v93, v66
	v_exp_f32_e32 v102, v67
	v_add_f32_e32 v66, v94, v66
	v_exp_f32_e32 v103, v68
	v_add_f32_e32 v66, v95, v66
	v_exp_f32_e32 v104, v69
	v_add_f32_e32 v66, v96, v66
	v_exp_f32_e32 v105, v70
	v_add_f32_e32 v66, v97, v66
	v_exp_f32_e32 v106, v71
	v_add_f32_e32 v66, v102, v66
	v_exp_f32_e32 v107, v72
	v_add_f32_e32 v66, v103, v66
	v_exp_f32_e32 v108, v73
	v_add_f32_e32 v66, v104, v66
	v_exp_f32_e32 v109, v74
	v_add_f32_e32 v66, v105, v66
	v_exp_f32_e32 v110, v75
	v_add_f32_e32 v66, v106, v66
	v_exp_f32_e32 v111, v76
	v_add_f32_e32 v66, v107, v66
	v_exp_f32_e32 v112, v77
	v_add_f32_e32 v66, v108, v66
	v_exp_f32_e32 v113, v78
	v_add_f32_e32 v66, v109, v66
	v_exp_f32_e32 v115, v79
	v_add_f32_e32 v66, v110, v66
	v_exp_f32_e32 v116, v80
	v_add_f32_e32 v66, v111, v66
	v_exp_f32_e32 v101, v101
	v_add_f32_e32 v66, v112, v66
	v_add_f32_e32 v66, v113, v66
	v_add_f32_e32 v66, v115, v66
	v_add_f32_e32 v66, v116, v66
	v_add_f32_e32 v66, v101, v66
	v_mov_b32_e32 v67, v66
	s_nop 1
	v_permlane32_swap_b32_e32 v66, v67
	v_cvt_pk_bf16_f32 v68, v81, v82
	v_cvt_pk_bf16_f32 v69, v83, v84
	v_cvt_pk_bf16_f32 v70, v85, v86
	v_cvt_pk_bf16_f32 v71, v87, v88
	v_cvt_pk_bf16_f32 v72, v89, v90
	v_cvt_pk_bf16_f32 v73, v91, v92
	v_cvt_pk_bf16_f32 v74, v93, v94
	v_cvt_pk_bf16_f32 v75, v95, v96
	v_cvt_pk_bf16_f32 v76, v97, v102
	v_cvt_pk_bf16_f32 v77, v103, v104
	v_cvt_pk_bf16_f32 v78, v105, v106
	v_cvt_pk_bf16_f32 v79, v107, v108
	v_cvt_pk_bf16_f32 v80, v109, v110
	v_cvt_pk_bf16_f32 v81, v111, v112
	v_cvt_pk_bf16_f32 v82, v113, v115
	v_cvt_pk_bf16_f32 v83, v116, v101
	s_nop 0
	v_permlane32_swap_b32_e32 v68, v70
	v_permlane32_swap_b32_e32 v69, v71
	v_permlane32_swap_b32_e32 v72, v74
	v_permlane32_swap_b32_e32 v73, v75
	v_permlane32_swap_b32_e32 v76, v78
	v_permlane32_swap_b32_e32 v77, v79
	v_permlane32_swap_b32_e32 v80, v82
	v_permlane32_swap_b32_e32 v81, v83
	ds_read_b64_tr_b16 v[84:85], v153 offset:0x4000
	ds_read_b64_tr_b16 v[86:87], v153 offset:0x4800
	ds_read_b64_tr_b16 v[88:89], v153 offset:0x5000
	ds_read_b64_tr_b16 v[90:91], v153 offset:0x5800
	ds_read_b64_tr_b16 v[92:93], v153 offset:0x6000
	ds_read_b64_tr_b16 v[94:95], v153 offset:0x6800
	ds_read_b64_tr_b16 v[102:103], v153 offset:0x7000
	ds_read_b64_tr_b16 v[104:105], v153 offset:0x7800
	s_nop 0
	s_waitcnt lgkmcnt(6)
	v_mfma_f32_32x32x16_bf16 v[50:65], v[68:71], v[84:87], v[50:65]
	ds_read_b64_tr_b16 v[84:85], v153 offset:0x4200
	ds_read_b64_tr_b16 v[86:87], v153 offset:0x4a00
	s_waitcnt lgkmcnt(6)
	v_mfma_f32_32x32x16_bf16 v[50:65], v[72:75], v[88:91], v[50:65]
	ds_read_b64_tr_b16 v[88:89], v153 offset:0x5200
	ds_read_b64_tr_b16 v[90:91], v153 offset:0x5a00
	s_waitcnt lgkmcnt(6)
	v_mfma_f32_32x32x16_bf16 v[50:65], v[76:79], v[92:95], v[50:65]
	ds_read_b64_tr_b16 v[92:93], v153 offset:0x6200
	ds_read_b64_tr_b16 v[94:95], v153 offset:0x6a00
	s_waitcnt lgkmcnt(6)
	v_mfma_f32_32x32x16_bf16 v[50:65], v[80:83], v[102:105], v[50:65]
	ds_read_b64_tr_b16 v[102:103], v153 offset:0x7200
	ds_read_b64_tr_b16 v[104:105], v153 offset:0x7a00
	s_waitcnt lgkmcnt(6)
	v_mfma_f32_32x32x16_bf16 v[34:49], v[68:71], v[84:87], v[34:49]
	ds_read_b64_tr_b16 v[84:85], v153 offset:0x4400
	ds_read_b64_tr_b16 v[86:87], v153 offset:0x4c00
	s_waitcnt lgkmcnt(6)
	v_mfma_f32_32x32x16_bf16 v[34:49], v[72:75], v[88:91], v[34:49]
	ds_read_b64_tr_b16 v[88:89], v153 offset:0x5400
	ds_read_b64_tr_b16 v[90:91], v153 offset:0x5c00
	s_waitcnt lgkmcnt(6)
	v_mfma_f32_32x32x16_bf16 v[34:49], v[76:79], v[92:95], v[34:49]
	ds_read_b64_tr_b16 v[92:93], v153 offset:0x6400
	ds_read_b64_tr_b16 v[94:95], v153 offset:0x6c00
	s_waitcnt lgkmcnt(6)
	v_mfma_f32_32x32x16_bf16 v[34:49], v[80:83], v[102:105], v[34:49]
	ds_read_b64_tr_b16 v[102:103], v153 offset:0x7400
	ds_read_b64_tr_b16 v[104:105], v153 offset:0x7c00
	s_waitcnt lgkmcnt(6)
	v_mfma_f32_32x32x16_bf16 v[18:33], v[68:71], v[84:87], v[18:33]
	ds_read_b64_tr_b16 v[84:85], v153 offset:0x4600
	ds_read_b64_tr_b16 v[86:87], v153 offset:0x4e00
	s_waitcnt lgkmcnt(6)
	v_mfma_f32_32x32x16_bf16 v[18:33], v[72:75], v[88:91], v[18:33]
	ds_read_b64_tr_b16 v[88:89], v153 offset:0x5600
	ds_read_b64_tr_b16 v[90:91], v153 offset:0x5e00
	s_waitcnt lgkmcnt(6)
	v_mfma_f32_32x32x16_bf16 v[18:33], v[76:79], v[92:95], v[18:33]
	ds_read_b64_tr_b16 v[92:93], v153 offset:0x6600
	ds_read_b64_tr_b16 v[94:95], v153 offset:0x6e00
	s_waitcnt lgkmcnt(6)
	v_mfma_f32_32x32x16_bf16 v[18:33], v[80:83], v[102:105], v[18:33]
	ds_read_b64_tr_b16 v[102:103], v153 offset:0x7600
	ds_read_b64_tr_b16 v[104:105], v153 offset:0x7e00
	s_waitcnt lgkmcnt(6)
	v_mfma_f32_32x32x16_bf16 v[2:17], v[68:71], v[84:87], v[2:17]
	v_cmp_gt_u32_e32 vcc, 32, v149
	s_waitcnt lgkmcnt(4)
	v_mfma_f32_32x32x16_bf16 v[2:17], v[72:75], v[88:91], v[2:17]
	s_waitcnt lgkmcnt(2)
	v_mfma_f32_32x32x16_bf16 v[2:17], v[76:79], v[92:95], v[2:17]
	s_waitcnt lgkmcnt(0)
	v_mfma_f32_32x32x16_bf16 v[2:17], v[80:83], v[102:105], v[2:17]
	s_and_saveexec_b64 s[0:1], vcc
	v_add_f32_e32 v68, v98, v99
	v_fmac_f32_e32 v68, v157, v114
	v_add_f32_e32 v66, v66, v67
	v_fmac_f32_e32 v66, v68, v100
	ds_write_b32 v155, v66
	s_or_b64 exec, exec, s[0:1]
	s_waitcnt lgkmcnt(0)
	ds_read_b128 v[78:81], v154
	ds_read_b128 v[74:77], v154 offset:32
	ds_read_b128 v[70:73], v154 offset:64
	ds_read_b128 v[66:69], v154 offset:96
	s_lshl_b32 s0, s29, 13
	s_waitcnt lgkmcnt(3)
	v_rcp_f32_e32 v82, v78
	v_and_b32_e32 v78, 1, v150
	s_add_i32 s2, s0, 0
	v_cmp_eq_u32_e32 vcc, 0, v78
	v_lshlrev_b32_e32 v78, 10, v152
	v_lshlrev_b32_e32 v83, 1, v151
	v_mul_f32_e32 v50, v50, v82
	v_add3_u32 v78, s2, v78, v83
	s_waitcnt lgkmcnt(0)
	v_mov_b32_dpp v83, v50 quad_perm:[1,0,3,2] row_mask:0xf bank_mask:0xf bound_ctrl:1
	s_barrier
	s_and_saveexec_b64 s[0:1], vcc
	s_cbranch_execz .LBB0_852
	v_cvt_pk_bf16_f32 v50, v50, v83
	ds_write_b32 v78, v50

.LBB0_1414:
	s_ashr_i32 s4, s34, 5
	v_readlane_b32 s0, v243, 52
	s_add_i32 s0, s4, s0
	s_ashr_i32 s1, s0, 31
	s_and_b32 s2, s29, 0xe0000
	s_lshl_b64 s[0:1], s[0:1], 20
	s_or_b32 s0, s0, s2
	s_lshl_b64 s[0:1], s[0:1], 1
	v_readlane_b32 s2, v245, 20
	s_add_u32 s2, s2, s0
	v_readlane_b32 s3, v245, 23
	s_addc_u32 s5, s3, s1
	s_and_b32 s3, s28, 0x180
	s_waitcnt vmcnt(0)
	v_mov_b32_e32 v155, v0
	s_lshl_b32 s3, s3, 1
	s_add_u32 s18, s2, s3
	v_ashrrev_i32_e32 v146, 4, v155
	v_lshlrev_b32_e32 v2, 3, v155
	v_and_b32_e32 v4, 0xfffff0, v146
	v_lshlrev_b32_e32 v5, 1, v146
	s_addc_u32 s19, s5, 0
	s_ashr_i32 s5, s4, 31
	v_and_b32_e32 v3, 0x78, v2
	v_and_or_b32 v4, v5, 8, v4
	v_lshrrev_b32_e32 v5, 1, v146
	v_and_b32_e32 v6, 3, v146
	v_add_u32_e32 v8, 32, v146
	s_lshl_b64 s[4:5], s[4:5], 19
	v_and_or_b32 v5, v5, 4, v6
	s_waitcnt vmcnt(0) lgkmcnt(0)
	v_lshlrev_b32_e32 v50, 1, v3
	v_and_b32_e32 v3, 0xfffff0, v8
	v_lshlrev_b32_e32 v6, 1, v8
	s_add_u32 s2, s22, s4
	v_and_or_b32 v3, v6, 8, v3
	s_addc_u32 s5, s23, s5
	v_lshrrev_b32_e32 v4, 1, v4
	v_bfe_u32 v2, v2, 5, 2
	v_lshrrev_b32_e32 v3, 1, v3
	s_add_u32 s4, s2, s3
	v_readfirstlane_b32 s2, v155
	v_or_b32_e32 v4, v4, v2
	v_or_b32_e32 v2, v3, v2
	s_addc_u32 s5, s5, 0
	s_ashr_i32 s35, s2, 6
	v_and_b32_e32 v1, 63, v155
	s_and_b32 s2, s2, 0x3fffffc0
	v_lshlrev_b32_e32 v6, 9, v2
	v_lshlrev_b32_e32 v2, 8, v146
	v_and_b32_e32 v3, 0x70, v155
	v_lshlrev_b32_e32 v154, 4, v155
	s_lshl_b32 s2, s2, 2
	v_bitop3_b32 v20, v50, v2, v3 bitop3:0xde
	v_lshlrev_b32_e32 v2, 3, v1
	v_and_b32_e32 v3, 0xc0, v154
	v_lshlrev_b32_e32 v7, 1, v155
	v_and_b32_e32 v156, 31, v155
	s_add_i32 s42, s2, 0
	v_and_or_b32 v3, v2, 24, v3
	v_and_b32_e32 v7, 32, v7
	v_and_b32_e32 v2, 0x100, v2
	s_lshl_b32 s2, s35, 5
	v_or3_b32 v7, v3, v7, v2
	v_or_b32_e32 v2, s2, v156
	v_ashrrev_i32_e32 v3, 31, v2
	v_bfe_u32 v157, v155, 5, 1
	v_lshlrev_b64 v[2:3], 10, v[2:3]
	v_lshl_add_u64 v[2:3], s[18:19], 0, v[2:3]
	v_lshlrev_b32_e32 v162, 4, v157
	v_lshl_add_u64 v[2:3], v[2:3], 0, v[162:163]
	v_ashrrev_i32_e32 v147, 31, v146
	v_ashrrev_i32_e32 v9, 31, v8
	v_lshlrev_b32_e32 v4, 9, v4
	v_lshlrev_b32_e32 v5, 6, v5
	global_load_dwordx4 v[126:129], v[2:3], off
	global_load_dwordx4 v[122:125], v[2:3], off offset:32
	global_load_dwordx4 v[118:121], v[2:3], off offset:64
	global_load_dwordx4 v[114:117], v[2:3], off offset:96
	global_load_dwordx4 v[110:113], v[2:3], off offset:128
	global_load_dwordx4 v[106:109], v[2:3], off offset:160
	global_load_dwordx4 v[102:105], v[2:3], off offset:192
	global_load_dwordx4 v[98:101], v[2:3], off offset:224
	v_and_b32_e32 v2, 48, v50
	v_lshlrev_b64 v[52:53], 11, v[146:147]
	v_lshlrev_b64 v[8:9], 11, v[8:9]
	v_or3_b32 v21, v4, v5, v2
	v_or3_b32 v22, v6, v5, v2
	v_mov_b32_e32 v51, v163
	v_lshl_add_u64 v[2:3], s[4:5], 0, v[52:53]
	v_lshl_add_u64 v[8:9], s[4:5], 0, v[8:9]
	v_lshl_add_u64 v[2:3], v[2:3], 0, v[50:51]
	v_lshl_add_u64 v[16:17], v[8:9], 0, v[50:51]
	v_add_u32_e32 v158, 0, v7
	global_load_dwordx4 v[4:7], v[2:3], off offset:1024
	global_load_dwordx4 v[8:11], v[16:17], off offset:1024
	global_load_dwordx4 v[12:15], v[2:3], off
	s_nop 0
	global_load_dwordx4 v[16:19], v[16:17], off
	v_add_u32_e32 v165, 0, v20
	v_add_u32_e32 v166, 0, v21
	s_mov_b64 s[8:9], 0x20000
	v_add_u32_e32 v167, 0, v22
	s_add_i32 s42, s42, 0x10000
	s_waitcnt vmcnt(1)
	ds_write_b128 v165, v[12:15] offset:32768
	s_waitcnt vmcnt(0)
	ds_write_b128 v165, v[16:19] offset:40960
	ds_write_b128 v166, v[4:7]
	v_lshl_add_u64 v[4:5], v[2:3], 0, s[8:9]
	s_mov_b64 s[8:9], 0x30000
	ds_write_b128 v167, v[8:11]
	s_waitcnt lgkmcnt(0)
	s_barrier
	global_load_dwordx4 v[34:37], v[4:5], off offset:1024
	v_lshl_add_u64 v[4:5], v[2:3], 0, s[8:9]
	s_mov_b32 s8, 0x20000
	global_load_dwordx4 v[38:41], v[4:5], off offset:1024
	v_add_co_u32_e32 v4, vcc, s8, v2
	s_mov_b32 s8, 0x30000
	s_nop 0
	v_addc_co_u32_e32 v5, vcc, 0, v3, vcc
	v_add_co_u32_e32 v2, vcc, s8, v2
	global_load_dwordx4 v[42:45], v[4:5], off
	s_nop 0
	v_addc_co_u32_e32 v3, vcc, 0, v3, vcc
	global_load_dwordx4 v[46:49], v[2:3], off
	s_movk_i32 s8, 0x70
	v_and_b32_e32 v2, 0x70, v154
	v_lshl_add_u32 v3, v156, 8, 0
	v_bitop3_b32 v4, v162, v154, s8 bitop3:0x78
	v_add_u32_e32 v168, v3, v4
	v_bitop3_b32 v4, v162, v2, 32 bitop3:0x36
	s_movk_i32 s8, 0x60
	v_add_u32_e32 v164, v3, v4
	v_bitop3_b32 v4, v162, v2, 64 bitop3:0x36
	v_bitop3_b32 v2, v162, v2, s8 bitop3:0x36
	v_add_u32_e32 v161, v3, v4
	v_add_u32_e32 v160, v3, v2
	ds_read_b128 v[2:5], v168 offset:32768
	ds_read_b128 v[18:21], v168 offset:40960
	s_waitcnt lgkmcnt(1)
	v_mfma_f32_32x32x16_bf16 v[2:17], v[2:5], v[126:129], 0
	ds_read_b128 v[54:57], v164 offset:32768
	ds_read_b128 v[58:61], v164 offset:40960
	v_lshl_add_u64 v[148:149], s[4:5], 0, v[50:51]
	s_mov_b64 s[4:5], 0x40000
	v_cmp_gt_u32_e64 s[38:39], 32, v1
	v_lshl_add_u32 v159, v156, 2, s42
	s_waitcnt lgkmcnt(2)
	v_mfma_f32_32x32x16_bf16 v[18:33], v[18:21], v[126:129], 0
	s_waitcnt lgkmcnt(1)
	v_mfma_f32_32x32x16_bf16 v[2:17], v[54:57], v[122:125], v[2:17]
	s_waitcnt lgkmcnt(0)
	v_mfma_f32_32x32x16_bf16 v[18:33], v[58:61], v[122:125], v[18:33]
	ds_read_b128 v[54:57], v161 offset:32768
	ds_read_b128 v[58:61], v161 offset:40960
	s_waitcnt lgkmcnt(1)
	v_mfma_f32_32x32x16_bf16 v[2:17], v[54:57], v[118:121], v[2:17]
	s_waitcnt lgkmcnt(0)
	v_mfma_f32_32x32x16_bf16 v[18:33], v[58:61], v[118:121], v[18:33]
	ds_read_b128 v[54:57], v160 offset:32768
	ds_read_b128 v[58:61], v160 offset:40960
	s_waitcnt lgkmcnt(1)
	v_mfma_f32_32x32x16_bf16 v[2:17], v[54:57], v[114:117], v[2:17]
	s_waitcnt lgkmcnt(0)
	v_mfma_f32_32x32x16_bf16 v[18:33], v[58:61], v[114:117], v[18:33]
	ds_read_b128 v[54:57], v168 offset:32896
	ds_read_b128 v[58:61], v168 offset:41088
	s_waitcnt lgkmcnt(1)
	v_mfma_f32_32x32x16_bf16 v[2:17], v[54:57], v[110:113], v[2:17]
	s_waitcnt lgkmcnt(0)
	v_mfma_f32_32x32x16_bf16 v[18:33], v[58:61], v[110:113], v[18:33]
	ds_read_b128 v[54:57], v164 offset:32896
	ds_read_b128 v[58:61], v164 offset:41088
	s_waitcnt lgkmcnt(1)
	v_mfma_f32_32x32x16_bf16 v[2:17], v[54:57], v[106:109], v[2:17]
	s_waitcnt lgkmcnt(0)
	v_mfma_f32_32x32x16_bf16 v[18:33], v[58:61], v[106:109], v[18:33]
	ds_read_b128 v[54:57], v161 offset:32896
	ds_read_b128 v[58:61], v161 offset:41088
	s_waitcnt lgkmcnt(1)
	v_mfma_f32_32x32x16_bf16 v[2:17], v[54:57], v[102:105], v[2:17]
	s_waitcnt lgkmcnt(0)
	v_mfma_f32_32x32x16_bf16 v[18:33], v[58:61], v[102:105], v[18:33]
	ds_read_b128 v[54:57], v160 offset:32896
	ds_read_b128 v[58:61], v160 offset:41088
	s_waitcnt vmcnt(1)
	ds_write_b128 v165, v[42:45] offset:49152
	s_waitcnt vmcnt(0)
	ds_write_b128 v165, v[46:49] offset:57344
	ds_write_b128 v166, v[34:37] offset:16384
	ds_write_b128 v167, v[38:41] offset:16384
	v_lshl_add_u64 v[34:35], v[148:149], 0, v[52:53]
	v_lshl_add_u64 v[36:37], v[34:35], 0, s[4:5]
	s_mov_b64 s[4:5], 0x50000
	s_waitcnt lgkmcnt(0)
	s_barrier
	v_mfma_f32_32x32x16_bf16 v[2:17], v[54:57], v[98:101], v[2:17]
	global_load_dwordx4 v[130:133], v[36:37], off offset:1024
	v_lshl_add_u64 v[36:37], v[34:35], 0, s[4:5]
	s_mov_b32 s4, 0x40000
	global_load_dwordx4 v[134:137], v[36:37], off offset:1024
	s_nop 7
	v_max_f32_e32 v54, v3, v3
	v_max_f32_e32 v55, v2, v2
	v_mfma_f32_32x32x16_bf16 v[18:33], v[58:61], v[98:101], v[18:33]
	v_max_f32_e32 v54, v55, v54
	v_max3_f32 v54, v54, v4, v5
	v_max3_f32 v54, v54, v6, v7
	v_max3_f32 v54, v54, v8, v9
	v_max3_f32 v54, v54, v10, v11
	v_max3_f32 v54, v54, v12, v13
	v_max3_f32 v54, v54, v14, v15
	v_max3_f32 v54, v54, v16, v17
	s_nop 3
	v_max3_f32 v54, v54, v18, v19
	v_max3_f32 v54, v54, v20, v21
	v_max3_f32 v54, v54, v22, v23
	v_max3_f32 v54, v54, v24, v25
	v_max3_f32 v54, v54, v26, v27
	v_max3_f32 v54, v54, v28, v29
	v_max3_f32 v54, v54, v30, v31
	v_max3_f32 v54, v54, v32, v33
	v_mov_b32_e32 v55, v54
	s_nop 1
	v_permlane32_swap_b32_e32 v54, v55
	v_max_f32_e32 v55, v55, v55
	v_max_f32_e32 v54, v54, v54
	v_max_f32_e32 v54, v54, v55
	v_add_f32_e32 v55, 0x7149f2ca, v54
	v_mul_f32_e32 v55, 0x3e0293ee, v55
	v_cmp_ge_f32_e32 vcc, s24, v55
	s_cmp_eq_u64 vcc, exec
	v_add_co_u32_e32 v36, vcc, s4, v34
	s_mov_b32 s4, 0x50000
	s_nop 0
	v_addc_co_u32_e32 v37, vcc, 0, v35, vcc
	v_add_co_u32_e32 v34, vcc, s4, v34
	global_load_dwordx4 v[138:141], v[36:37], off
	s_nop 0
	v_addc_co_u32_e32 v35, vcc, 0, v35, vcc
	global_load_dwordx4 v[142:145], v[34:35], off
	s_cselect_b64 s[36:37], -1, 0
	v_max_f32_e32 v151, 0xf149f2ca, v54
	v_cndmask_b32_e64 v150, v151, v177, s[36:37]
	v_mul_f32_e32 v54, 0xbe0293ee, v150
	v_fmamk_f32 v2, v2, 0x3e0293ee, v54
	v_fmamk_f32 v3, v3, 0x3e0293ee, v54
	v_fmamk_f32 v4, v4, 0x3e0293ee, v54
	v_fmamk_f32 v5, v5, 0x3e0293ee, v54
	v_fmamk_f32 v6, v6, 0x3e0293ee, v54
	v_fmamk_f32 v7, v7, 0x3e0293ee, v54
	v_fmamk_f32 v8, v8, 0x3e0293ee, v54
	v_fmamk_f32 v9, v9, 0x3e0293ee, v54
	v_fmamk_f32 v55, v10, 0x3e0293ee, v54
	v_fmamk_f32 v56, v11, 0x3e0293ee, v54
	v_fmamk_f32 v57, v12, 0x3e0293ee, v54
	v_fmamk_f32 v58, v13, 0x3e0293ee, v54
	v_fmamk_f32 v59, v14, 0x3e0293ee, v54
	v_fmamk_f32 v60, v15, 0x3e0293ee, v54
	v_fmamk_f32 v61, v16, 0x3e0293ee, v54
	v_fmamk_f32 v62, v17, 0x3e0293ee, v54
	v_exp_f32_e32 v10, v2
	v_exp_f32_e32 v11, v3
	v_exp_f32_e32 v12, v4
	v_exp_f32_e32 v13, v5
	v_exp_f32_e32 v14, v6
	v_exp_f32_e32 v15, v7
	v_exp_f32_e32 v16, v8
	v_exp_f32_e32 v17, v9
	v_exp_f32_e32 v2, v55
	v_exp_f32_e32 v3, v56
	v_exp_f32_e32 v4, v57
	v_exp_f32_e32 v5, v58
	v_exp_f32_e32 v6, v59
	v_exp_f32_e32 v7, v60
	v_exp_f32_e32 v8, v61
	v_exp_f32_e32 v9, v62
	v_fmamk_f32 v18, v18, 0x3e0293ee, v54
	v_fmamk_f32 v19, v19, 0x3e0293ee, v54
	v_fmamk_f32 v20, v20, 0x3e0293ee, v54
	v_fmamk_f32 v21, v21, 0x3e0293ee, v54
	v_fmamk_f32 v22, v22, 0x3e0293ee, v54
	v_fmamk_f32 v23, v23, 0x3e0293ee, v54
	v_fmamk_f32 v24, v24, 0x3e0293ee, v54
	v_fmamk_f32 v25, v25, 0x3e0293ee, v54
	v_fmamk_f32 v26, v26, 0x3e0293ee, v54
	v_fmamk_f32 v27, v27, 0x3e0293ee, v54
	v_fmamk_f32 v28, v28, 0x3e0293ee, v54
	v_fmamk_f32 v29, v29, 0x3e0293ee, v54
	v_fmamk_f32 v30, v30, 0x3e0293ee, v54
	v_fmamk_f32 v31, v31, 0x3e0293ee, v54
	v_fmamk_f32 v32, v32, 0x3e0293ee, v54
	v_fmac_f32_e32 v54, 0x3e0293ee, v33
	ds_read_b128 v[228:231], v168 offset:49152
	ds_read_b128 v[232:235], v168 offset:57344
	ds_read_b128 v[236:239], v164 offset:49152
	ds_read_b128 v[248:251], v164 offset:57344
	ds_read_b128 v[252:255], v161 offset:49152
	s_waitcnt lgkmcnt(4)
	v_mfma_f32_32x32x16_bf16 v[82:97], v[228:231], v[126:129], 0
	ds_read_b128 v[228:231], v161 offset:57344
	s_waitcnt lgkmcnt(4)
	v_mfma_f32_32x32x16_bf16 v[66:81], v[232:235], v[126:129], 0
	ds_read_b128 v[232:235], v160 offset:49152
	s_waitcnt lgkmcnt(4)
	v_mfma_f32_32x32x16_bf16 v[82:97], v[236:239], v[122:125], v[82:97]
	ds_read_b128 v[236:239], v160 offset:57344
	s_waitcnt lgkmcnt(4)
	v_mfma_f32_32x32x16_bf16 v[66:81], v[248:251], v[122:125], v[66:81]
	ds_read_b128 v[248:251], v168 offset:49280
	s_waitcnt lgkmcnt(4)
	v_mfma_f32_32x32x16_bf16 v[82:97], v[252:255], v[118:121], v[82:97]
	ds_read_b128 v[252:255], v168 offset:57472
	s_waitcnt lgkmcnt(4)
	v_mfma_f32_32x32x16_bf16 v[66:81], v[228:231], v[118:121], v[66:81]
	ds_read_b128 v[228:231], v164 offset:49280
	s_waitcnt lgkmcnt(4)
	v_mfma_f32_32x32x16_bf16 v[82:97], v[232:235], v[114:117], v[82:97]
	ds_read_b128 v[232:235], v164 offset:57472
	s_waitcnt lgkmcnt(4)
	v_mfma_f32_32x32x16_bf16 v[66:81], v[236:239], v[114:117], v[66:81]
	ds_read_b128 v[236:239], v161 offset:49280
	s_waitcnt lgkmcnt(4)
	v_mfma_f32_32x32x16_bf16 v[82:97], v[248:251], v[110:113], v[82:97]
	ds_read_b128 v[248:251], v161 offset:57472
	s_waitcnt lgkmcnt(4)
	v_mfma_f32_32x32x16_bf16 v[66:81], v[252:255], v[110:113], v[66:81]
	ds_read_b128 v[252:255], v160 offset:49280
	s_waitcnt lgkmcnt(4)
	v_mfma_f32_32x32x16_bf16 v[82:97], v[228:231], v[106:109], v[82:97]
	ds_read_b128 v[228:231], v160 offset:57472
	s_waitcnt lgkmcnt(4)
	v_mfma_f32_32x32x16_bf16 v[66:81], v[232:235], v[106:109], v[66:81]
	s_waitcnt lgkmcnt(3)
	v_mfma_f32_32x32x16_bf16 v[82:97], v[236:239], v[102:105], v[82:97]
	s_waitcnt lgkmcnt(2)
	v_mfma_f32_32x32x16_bf16 v[66:81], v[248:251], v[102:105], v[66:81]
	s_waitcnt lgkmcnt(1)
	v_mfma_f32_32x32x16_bf16 v[82:97], v[252:255], v[98:101], v[82:97]
	s_waitcnt lgkmcnt(0)
	v_mfma_f32_32x32x16_bf16 v[66:81], v[228:231], v[98:101], v[66:81]
	v_add_f32_e32 v34, 0, v10
	v_add_f32_e32 v34, v11, v34
	v_add_f32_e32 v34, v12, v34
	v_add_f32_e32 v34, v13, v34
	v_add_f32_e32 v34, v14, v34
	v_add_f32_e32 v34, v15, v34
	v_add_f32_e32 v34, v16, v34
	v_add_f32_e32 v34, v17, v34
	v_add_f32_e32 v34, v2, v34
	v_add_f32_e32 v34, v3, v34
	v_add_f32_e32 v34, v4, v34
	v_add_f32_e32 v34, v5, v34
	v_exp_f32_e32 v18, v18
	v_add_f32_e32 v34, v6, v34
	v_exp_f32_e32 v19, v19
	v_add_f32_e32 v34, v7, v34
	v_exp_f32_e32 v20, v20
	v_add_f32_e32 v34, v8, v34
	v_exp_f32_e32 v21, v21
	v_add_f32_e32 v34, v9, v34
	v_exp_f32_e32 v22, v22
	v_add_f32_e32 v34, v18, v34
	v_exp_f32_e32 v23, v23
	v_add_f32_e32 v34, v19, v34
	v_exp_f32_e32 v24, v24
	v_add_f32_e32 v34, v20, v34
	v_exp_f32_e32 v25, v25
	v_add_f32_e32 v34, v21, v34
	v_exp_f32_e32 v26, v26
	v_add_f32_e32 v34, v22, v34
	v_exp_f32_e32 v27, v27
	v_add_f32_e32 v34, v23, v34
	v_exp_f32_e32 v28, v28
	v_add_f32_e32 v34, v24, v34
	v_exp_f32_e32 v29, v29
	v_add_f32_e32 v34, v25, v34
	v_exp_f32_e32 v30, v30
	v_add_f32_e32 v34, v26, v34
	v_exp_f32_e32 v31, v31
	v_add_f32_e32 v34, v27, v34
	v_exp_f32_e32 v32, v32
	v_add_f32_e32 v34, v28, v34
	v_exp_f32_e32 v33, v54
	v_add_f32_e32 v34, v29, v34
	v_add_f32_e32 v34, v30, v34
	v_add_f32_e32 v34, v31, v34
	v_add_f32_e32 v34, v32, v34
	v_add_f32_e32 v169, v33, v34
	v_mov_b32_e32 v179, v169
	v_cvt_pk_bf16_f32 v50, v10, v11
	v_cvt_pk_bf16_f32 v51, v12, v13
	v_cvt_pk_bf16_f32 v52, v14, v15
	v_cvt_pk_bf16_f32 v53, v16, v17
	v_cvt_pk_bf16_f32 v180, v2, v3
	v_cvt_pk_bf16_f32 v181, v4, v5
	v_cvt_pk_bf16_f32 v182, v6, v7
	s_nop 1
	v_permlane32_swap_b32_e32 v169, v179
	v_permlane32_swap_b32_e32 v50, v52
	v_permlane32_swap_b32_e32 v51, v53
	v_cvt_pk_bf16_f32 v183, v8, v9
	v_permlane32_swap_b32_e32 v180, v182
	v_cvt_pk_bf16_f32 v184, v18, v19
	v_cvt_pk_bf16_f32 v185, v20, v21
	v_cvt_pk_bf16_f32 v186, v22, v23
	v_cvt_pk_bf16_f32 v187, v24, v25
	v_cvt_pk_bf16_f32 v188, v26, v27
	v_cvt_pk_bf16_f32 v189, v28, v29
	v_cvt_pk_bf16_f32 v190, v30, v31
	v_cvt_pk_bf16_f32 v191, v32, v33
	v_permlane32_swap_b32_e32 v181, v183
	v_permlane32_swap_b32_e32 v184, v186
	v_permlane32_swap_b32_e32 v185, v187
	v_permlane32_swap_b32_e32 v188, v190
	v_permlane32_swap_b32_e32 v189, v191
	ds_read_b64_tr_b16 v[2:3], v158 offset:0
	ds_read_b64_tr_b16 v[4:5], v158 offset:0x800
	ds_read_b64_tr_b16 v[18:19], v158 offset:0x1000
	ds_read_b64_tr_b16 v[20:21], v158 offset:0x1800
	ds_read_b64_tr_b16 v[22:23], v158 offset:0x2000
	ds_read_b64_tr_b16 v[24:25], v158 offset:0x2800
	ds_read_b64_tr_b16 v[26:27], v158 offset:0x3000
	ds_read_b64_tr_b16 v[28:29], v158 offset:0x3800
	s_nop 0
	s_waitcnt lgkmcnt(6)
	v_mfma_f32_32x32x16_bf16 v[2:17], v[50:53], v[2:5], 0
	s_waitcnt lgkmcnt(4)
	v_mfma_f32_32x32x16_bf16 v[2:17], v[180:183], v[18:21], v[2:17]
	ds_read_b64_tr_b16 v[18:19], v158 offset:0x200
	ds_read_b64_tr_b16 v[20:21], v158 offset:0xa00
	ds_read_b64_tr_b16 v[34:35], v158 offset:0x1200
	ds_read_b64_tr_b16 v[36:37], v158 offset:0x1a00
	ds_read_b64_tr_b16 v[38:39], v158 offset:0x2200
	ds_read_b64_tr_b16 v[40:41], v158 offset:0x2a00
	ds_read_b64_tr_b16 v[42:43], v158 offset:0x3200
	s_waitcnt lgkmcnt(9)
	v_mfma_f32_32x32x16_bf16 v[2:17], v[184:187], v[22:25], v[2:17]
	ds_read_b64_tr_b16 v[44:45], v158 offset:0x3a00
	s_waitcnt lgkmcnt(8)
	v_mfma_f32_32x32x16_bf16 v[2:17], v[188:191], v[26:29], v[2:17]
	s_waitcnt lgkmcnt(6)
	v_mfma_f32_32x32x16_bf16 v[18:33], v[50:53], v[18:21], 0
	s_waitcnt lgkmcnt(4)
	v_mfma_f32_32x32x16_bf16 v[18:33], v[180:183], v[34:37], v[18:33]
	ds_read_b64_tr_b16 v[34:35], v158 offset:0x400
	ds_read_b64_tr_b16 v[36:37], v158 offset:0xc00
	ds_read_b64_tr_b16 v[54:55], v158 offset:0x1400
	ds_read_b64_tr_b16 v[56:57], v158 offset:0x1c00
	ds_read_b64_tr_b16 v[58:59], v158 offset:0x2400
	ds_read_b64_tr_b16 v[60:61], v158 offset:0x2c00
	ds_read_b64_tr_b16 v[62:63], v158 offset:0x3400
	s_waitcnt lgkmcnt(9)
	v_mfma_f32_32x32x16_bf16 v[18:33], v[184:187], v[38:41], v[18:33]
	ds_read_b64_tr_b16 v[64:65], v158 offset:0x3c00
	s_waitcnt lgkmcnt(8)
	v_mfma_f32_32x32x16_bf16 v[18:33], v[188:191], v[42:45], v[18:33]
	s_waitcnt lgkmcnt(6)
	v_mfma_f32_32x32x16_bf16 v[34:49], v[50:53], v[34:37], 0
	s_waitcnt lgkmcnt(4)
	v_mfma_f32_32x32x16_bf16 v[34:49], v[180:183], v[54:57], v[34:49]
	ds_read_b64_tr_b16 v[54:55], v158 offset:0x600
	ds_read_b64_tr_b16 v[56:57], v158 offset:0xe00
	ds_read_b64_tr_b16 v[192:193], v158 offset:0x1600
	ds_read_b64_tr_b16 v[194:195], v158 offset:0x1e00
	ds_read_b64_tr_b16 v[196:197], v158 offset:0x2600
	ds_read_b64_tr_b16 v[198:199], v158 offset:0x2e00
	ds_read_b64_tr_b16 v[200:201], v158 offset:0x3600
	s_waitcnt lgkmcnt(9)
	v_mfma_f32_32x32x16_bf16 v[34:49], v[184:187], v[58:61], v[34:49]
	ds_read_b64_tr_b16 v[202:203], v158 offset:0x3e00
	s_waitcnt lgkmcnt(8)
	v_mfma_f32_32x32x16_bf16 v[34:49], v[188:191], v[62:65], v[34:49]
	s_waitcnt lgkmcnt(6)
	v_mfma_f32_32x32x16_bf16 v[50:65], v[50:53], v[54:57], 0
	s_waitcnt lgkmcnt(4)
	v_mfma_f32_32x32x16_bf16 v[50:65], v[180:183], v[192:195], v[50:65]
	s_waitcnt lgkmcnt(2)
	v_mfma_f32_32x32x16_bf16 v[50:65], v[184:187], v[196:199], v[50:65]
	s_waitcnt lgkmcnt(0)
	v_mfma_f32_32x32x16_bf16 v[50:65], v[188:191], v[200:203], v[50:65]
	v_max_f32_e32 v152, v83, v83
	v_max_f32_e32 v153, v82, v82
	v_max_f32_e32 v152, v153, v152
	v_max3_f32 v152, v152, v84, v85
	v_max3_f32 v152, v152, v86, v87
	v_max3_f32 v152, v152, v88, v89
	v_max3_f32 v152, v152, v90, v91
	v_max3_f32 v152, v152, v92, v93
	v_max3_f32 v152, v152, v94, v95
	v_max3_f32 v152, v152, v96, v97
	v_max3_f32 v152, v152, v66, v67
	v_max3_f32 v152, v152, v68, v69
	v_max3_f32 v152, v152, v70, v71
	v_max3_f32 v152, v152, v72, v73
	v_max3_f32 v152, v152, v74, v75
	v_max3_f32 v152, v152, v76, v77
	v_max3_f32 v152, v152, v78, v79
	v_max3_f32 v152, v152, v80, v81
	v_mov_b32_e32 v153, v152
	s_nop 1
	v_permlane32_swap_b32_e32 v152, v153
	v_max_f32_e32 v153, v153, v153
	v_max_f32_e32 v152, v152, v152
	v_max_f32_e32 v152, v152, v153
	v_sub_f32_e32 v153, v152, v150
	v_mul_f32_e32 v153, 0x3e0293ee, v153
	v_max_f32_e32 v152, v150, v152
	v_cmp_ge_f32_e32 vcc, s24, v153
	v_sub_f32_e32 v153, v150, v152
	v_mul_f32_e32 v153, 0x3e0293ee, v153
	v_exp_f32_e32 v153, v153
	s_cmp_eq_u64 vcc, exec
	s_cselect_b64 s[40:41], -1, 0
	v_cndmask_b32_e64 v180, v153, 1.0, s[40:41]
	v_cmp_gt_f32_e32 vcc, 1.0, v180
	s_barrier
	s_waitcnt vmcnt(1)
	ds_write_b128 v165, v[138:141] offset:32768
	s_waitcnt vmcnt(0)
	ds_write_b128 v165, v[142:145] offset:40960
	ds_write_b128 v166, v[130:133]
	ds_write_b128 v167, v[134:137]
	s_cbranch_vccz .LBB0_1418
	s_and_saveexec_b64 s[4:5], s[38:39]
	ds_write_b32 v159, v180 offset:128
	s_or_b64 exec, exec, s[4:5]
	s_waitcnt lgkmcnt(0)
	v_add_u32_e32 v142, s42, v162
	ds_read_b128 v[130:133], v142 offset:224
	ds_read_b128 v[134:137], v142 offset:192
	ds_read_b128 v[138:141], v142 offset:160
	ds_read_b128 v[142:145], v142 offset:128
	s_waitcnt lgkmcnt(3)
	v_pk_mul_f32 v[14:15], v[14:15], v[130:131]
	s_waitcnt lgkmcnt(2)
	v_pk_mul_f32 v[10:11], v[10:11], v[134:135]
	s_waitcnt lgkmcnt(1)
	v_pk_mul_f32 v[6:7], v[6:7], v[138:139]
	v_pk_mul_f32 v[16:17], v[16:17], v[132:133]
	v_pk_mul_f32 v[12:13], v[12:13], v[136:137]
	v_pk_mul_f32 v[8:9], v[8:9], v[140:141]
	s_waitcnt lgkmcnt(0)
	v_pk_mul_f32 v[4:5], v[4:5], v[144:145]
	v_pk_mul_f32 v[2:3], v[2:3], v[142:143]
	v_pk_mul_f32 v[30:31], v[30:31], v[130:131]
	v_pk_mul_f32 v[26:27], v[26:27], v[134:135]
	v_pk_mul_f32 v[22:23], v[22:23], v[138:139]
	v_pk_mul_f32 v[32:33], v[32:33], v[132:133]
	v_pk_mul_f32 v[28:29], v[28:29], v[136:137]
	v_pk_mul_f32 v[24:25], v[24:25], v[140:141]
	v_pk_mul_f32 v[20:21], v[20:21], v[144:145]
	v_pk_mul_f32 v[18:19], v[18:19], v[142:143]
	v_pk_mul_f32 v[46:47], v[46:47], v[130:131]
	v_pk_mul_f32 v[42:43], v[42:43], v[134:135]
	v_pk_mul_f32 v[38:39], v[38:39], v[138:139]
	v_pk_mul_f32 v[48:49], v[48:49], v[132:133]
	v_pk_mul_f32 v[44:45], v[44:45], v[136:137]
	v_pk_mul_f32 v[40:41], v[40:41], v[140:141]
	v_pk_mul_f32 v[36:37], v[36:37], v[144:145]
	v_pk_mul_f32 v[34:35], v[34:35], v[142:143]
	v_pk_mul_f32 v[62:63], v[62:63], v[130:131]
	v_pk_mul_f32 v[58:59], v[58:59], v[134:135]
	v_pk_mul_f32 v[54:55], v[54:55], v[138:139]
	v_pk_mul_f32 v[64:65], v[64:65], v[132:133]
	v_pk_mul_f32 v[60:61], v[60:61], v[136:137]
	v_pk_mul_f32 v[56:57], v[56:57], v[140:141]
	v_pk_mul_f32 v[52:53], v[52:53], v[144:145]
	v_pk_mul_f32 v[50:51], v[50:51], v[142:143]
.LBB0_1418:
	v_cndmask_b32_e64 v184, v152, v150, s[40:41]
	v_mul_f32_e32 v182, 0xbe0293ee, v184
	v_fmamk_f32 v183, v66, 0x3e0293ee, v182
	v_fmamk_f32 v66, v83, 0x3e0293ee, v182
	v_fmamk_f32 v197, v67, 0x3e0293ee, v182
	v_fmamk_f32 v67, v84, 0x3e0293ee, v182
	v_exp_f32_e32 v196, v66
	v_exp_f32_e32 v192, v67
	v_lshlrev_b64 v[66:67], 11, v[146:147]
	v_sub_f32_e32 v130, 0xf149f2ca, v151
	v_fmamk_f32 v198, v68, 0x3e0293ee, v182
	v_fmamk_f32 v68, v85, 0x3e0293ee, v182
	v_fmamk_f32 v199, v69, 0x3e0293ee, v182
	v_fmamk_f32 v69, v86, 0x3e0293ee, v182
	v_lshl_add_u64 v[66:67], v[148:149], 0, v[66:67]
	s_mov_b64 s[4:5], 0x60000
	v_mul_f32_e32 v130, 0x3e0293ee, v130
	v_fmamk_f32 v200, v70, 0x3e0293ee, v182
	v_fmamk_f32 v70, v87, 0x3e0293ee, v182
	v_fmamk_f32 v201, v71, 0x3e0293ee, v182
	v_fmamk_f32 v71, v88, 0x3e0293ee, v182
	v_exp_f32_e32 v195, v68
	v_exp_f32_e32 v190, v69
	v_lshl_add_u64 v[68:69], v[66:67], 0, s[4:5]
	s_mov_b64 s[4:5], 0x70000
	v_exp_f32_e32 v181, v130
	v_exp_f32_e32 v193, v70
	v_exp_f32_e32 v189, v71
	s_waitcnt lgkmcnt(0)
	s_barrier
	v_lshl_add_u64 v[70:71], v[66:67], 0, s[4:5]
	global_load_dwordx4 v[130:133], v[68:69], off offset:1024
	global_load_dwordx4 v[134:137], v[70:71], off offset:1024
	v_add_co_u32_e32 v68, vcc, 0x60000, v66
	s_mov_b32 s4, 0x70000
	s_nop 0
	v_addc_co_u32_e32 v69, vcc, 0, v67, vcc
	v_add_co_u32_e32 v66, vcc, s4, v66
	v_fmamk_f32 v82, v82, 0x3e0293ee, v182
	s_nop 0
	v_addc_co_u32_e32 v67, vcc, 0, v67, vcc
	global_load_dwordx4 v[138:141], v[68:69], off
	global_load_dwordx4 v[142:145], v[66:67], off
	v_fmamk_f32 v202, v72, 0x3e0293ee, v182
	v_fmamk_f32 v72, v89, 0x3e0293ee, v182
	v_fmamk_f32 v203, v73, 0x3e0293ee, v182
	v_fmamk_f32 v73, v90, 0x3e0293ee, v182
	v_fmamk_f32 v204, v74, 0x3e0293ee, v182
	v_fmamk_f32 v74, v91, 0x3e0293ee, v182
	v_fmamk_f32 v205, v75, 0x3e0293ee, v182
	v_fmamk_f32 v75, v92, 0x3e0293ee, v182
	v_fmamk_f32 v206, v76, 0x3e0293ee, v182
	v_fmamk_f32 v76, v93, 0x3e0293ee, v182
	v_fmamk_f32 v207, v77, 0x3e0293ee, v182
	v_fmamk_f32 v77, v94, 0x3e0293ee, v182
	v_fmamk_f32 v208, v78, 0x3e0293ee, v182
	v_fmamk_f32 v78, v95, 0x3e0293ee, v182
	v_fmamk_f32 v83, v96, 0x3e0293ee, v182
	v_fmamk_f32 v84, v97, 0x3e0293ee, v182
	v_fmamk_f32 v209, v79, 0x3e0293ee, v182
	v_fmamk_f32 v210, v80, 0x3e0293ee, v182
	v_fmac_f32_e32 v182, 0x3e0293ee, v81
	v_exp_f32_e32 v194, v82
	v_exp_f32_e32 v191, v72
	v_exp_f32_e32 v150, v73
	v_exp_f32_e32 v188, v74
	v_exp_f32_e32 v151, v75
	v_exp_f32_e32 v187, v76
	v_exp_f32_e32 v152, v77
	v_exp_f32_e32 v186, v78
	v_exp_f32_e32 v153, v83
	v_exp_f32_e32 v185, v84
	ds_read_b128 v[228:231], v168 offset:32768
	ds_read_b128 v[232:235], v164 offset:32768
	ds_read_b128 v[236:239], v168 offset:40960
	ds_read_b128 v[248:251], v164 offset:40960
	ds_read_b128 v[252:255], v161 offset:32768
	s_waitcnt lgkmcnt(4)
	v_mfma_f32_32x32x16_bf16 v[82:97], v[228:231], v[126:129], 0
	ds_read_b128 v[228:231], v161 offset:40960
	s_waitcnt lgkmcnt(4)
	v_mfma_f32_32x32x16_bf16 v[82:97], v[232:235], v[122:125], v[82:97]
	ds_read_b128 v[232:235], v160 offset:32768
	s_waitcnt lgkmcnt(4)
	v_mfma_f32_32x32x16_bf16 v[66:81], v[236:239], v[126:129], 0
	ds_read_b128 v[236:239], v160 offset:40960
	s_waitcnt lgkmcnt(4)
	v_mfma_f32_32x32x16_bf16 v[66:81], v[248:251], v[122:125], v[66:81]
	ds_read_b128 v[248:251], v168 offset:32896
	s_waitcnt lgkmcnt(4)
	v_mfma_f32_32x32x16_bf16 v[82:97], v[252:255], v[118:121], v[82:97]
	ds_read_b128 v[252:255], v168 offset:41088
	s_waitcnt lgkmcnt(4)
	v_mfma_f32_32x32x16_bf16 v[66:81], v[228:231], v[118:121], v[66:81]
	ds_read_b128 v[228:231], v164 offset:32896
	s_waitcnt lgkmcnt(4)
	v_mfma_f32_32x32x16_bf16 v[82:97], v[232:235], v[114:117], v[82:97]
	ds_read_b128 v[232:235], v164 offset:41088
	s_waitcnt lgkmcnt(4)
	v_mfma_f32_32x32x16_bf16 v[66:81], v[236:239], v[114:117], v[66:81]
	ds_read_b128 v[236:239], v161 offset:32896
	s_waitcnt lgkmcnt(4)
	v_mfma_f32_32x32x16_bf16 v[82:97], v[248:251], v[110:113], v[82:97]
	ds_read_b128 v[248:251], v161 offset:41088
	s_waitcnt lgkmcnt(4)
	v_mfma_f32_32x32x16_bf16 v[66:81], v[252:255], v[110:113], v[66:81]
	ds_read_b128 v[252:255], v160 offset:32896
	s_waitcnt lgkmcnt(4)
	v_mfma_f32_32x32x16_bf16 v[82:97], v[228:231], v[106:109], v[82:97]
	ds_read_b128 v[228:231], v160 offset:41088
	s_waitcnt lgkmcnt(4)
	v_mfma_f32_32x32x16_bf16 v[66:81], v[232:235], v[106:109], v[66:81]
	s_waitcnt lgkmcnt(3)
	v_mfma_f32_32x32x16_bf16 v[82:97], v[236:239], v[102:105], v[82:97]
	s_waitcnt lgkmcnt(2)
	v_mfma_f32_32x32x16_bf16 v[66:81], v[248:251], v[102:105], v[66:81]
	s_waitcnt lgkmcnt(1)
	v_mfma_f32_32x32x16_bf16 v[82:97], v[252:255], v[98:101], v[82:97]
	s_waitcnt lgkmcnt(0)
	v_mfma_f32_32x32x16_bf16 v[66:81], v[228:231], v[98:101], v[66:81]
	v_add_f32_e32 v146, 0, v194
	v_add_f32_e32 v146, v196, v146
	v_add_f32_e32 v146, v192, v146
	v_add_f32_e32 v146, v195, v146
	v_add_f32_e32 v146, v190, v146
	v_add_f32_e32 v146, v193, v146
	v_add_f32_e32 v146, v189, v146
	v_add_f32_e32 v146, v191, v146
	v_add_f32_e32 v146, v150, v146
	v_add_f32_e32 v146, v188, v146
	v_add_f32_e32 v146, v151, v146
	v_add_f32_e32 v146, v187, v146
	v_exp_f32_e32 v211, v183
	v_add_f32_e32 v146, v152, v146
	v_exp_f32_e32 v197, v197
	v_add_f32_e32 v146, v186, v146
	v_exp_f32_e32 v198, v198
	v_add_f32_e32 v146, v153, v146
	v_exp_f32_e32 v199, v199
	v_add_f32_e32 v146, v185, v146
	v_exp_f32_e32 v200, v200
	v_add_f32_e32 v146, v211, v146
	v_exp_f32_e32 v201, v201
	v_add_f32_e32 v146, v197, v146
	v_exp_f32_e32 v202, v202
	v_add_f32_e32 v146, v198, v146
	v_exp_f32_e32 v203, v203
	v_add_f32_e32 v146, v199, v146
	v_exp_f32_e32 v204, v204
	v_add_f32_e32 v146, v200, v146
	v_exp_f32_e32 v205, v205
	v_add_f32_e32 v146, v201, v146
	v_exp_f32_e32 v206, v206
	v_add_f32_e32 v146, v202, v146
	v_exp_f32_e32 v207, v207
	v_add_f32_e32 v146, v203, v146
	v_exp_f32_e32 v208, v208
	v_add_f32_e32 v146, v204, v146
	v_exp_f32_e32 v209, v209
	v_add_f32_e32 v146, v205, v146
	v_exp_f32_e32 v210, v210
	v_add_f32_e32 v146, v206, v146
	v_exp_f32_e32 v212, v182
	v_add_f32_e32 v146, v207, v146
	v_add_f32_e32 v146, v208, v146
	v_add_f32_e32 v146, v209, v146
	v_add_f32_e32 v146, v210, v146
	v_add_f32_e32 v182, v212, v146
	v_mov_b32_e32 v183, v182
	v_cvt_pk_bf16_f32 v146, v194, v196
	v_cvt_pk_bf16_f32 v147, v192, v195
	v_cvt_pk_bf16_f32 v148, v190, v193
	v_cvt_pk_bf16_f32 v149, v189, v191
	s_nop 1
	v_permlane32_swap_b32_e32 v182, v183
	v_permlane32_swap_b32_e32 v146, v148
	v_permlane32_swap_b32_e32 v147, v149
	v_cvt_pk_bf16_f32 v150, v150, v188
	v_cvt_pk_bf16_f32 v151, v151, v187
	v_cvt_pk_bf16_f32 v152, v152, v186
	v_cvt_pk_bf16_f32 v153, v153, v185
	v_cvt_pk_bf16_f32 v186, v211, v197
	v_cvt_pk_bf16_f32 v187, v198, v199
	v_cvt_pk_bf16_f32 v188, v200, v201
	v_cvt_pk_bf16_f32 v189, v202, v203
	v_cvt_pk_bf16_f32 v190, v204, v205
	v_cvt_pk_bf16_f32 v191, v206, v207
	v_cvt_pk_bf16_f32 v192, v208, v209
	v_cvt_pk_bf16_f32 v193, v210, v212
	s_nop 0
	v_permlane32_swap_b32_e32 v150, v152
	v_permlane32_swap_b32_e32 v151, v153
	v_permlane32_swap_b32_e32 v186, v188
	v_permlane32_swap_b32_e32 v187, v189
	v_permlane32_swap_b32_e32 v190, v192
	v_permlane32_swap_b32_e32 v191, v193
	ds_read_b64_tr_b16 v[194:195], v158 offset:0x4000
	ds_read_b64_tr_b16 v[196:197], v158 offset:0x4800
	ds_read_b64_tr_b16 v[198:199], v158 offset:0x5000
	ds_read_b64_tr_b16 v[200:201], v158 offset:0x5800
	ds_read_b64_tr_b16 v[202:203], v158 offset:0x6000
	ds_read_b64_tr_b16 v[204:205], v158 offset:0x6800
	ds_read_b64_tr_b16 v[206:207], v158 offset:0x7000
	ds_read_b64_tr_b16 v[208:209], v158 offset:0x7800
	s_nop 0
	s_waitcnt lgkmcnt(6)
	v_mfma_f32_32x32x16_bf16 v[2:17], v[146:149], v[194:197], v[2:17]
	ds_read_b64_tr_b16 v[194:195], v158 offset:0x4200
	ds_read_b64_tr_b16 v[196:197], v158 offset:0x4a00
	s_waitcnt lgkmcnt(6)
	v_mfma_f32_32x32x16_bf16 v[2:17], v[150:153], v[198:201], v[2:17]
	ds_read_b64_tr_b16 v[198:199], v158 offset:0x5200
	ds_read_b64_tr_b16 v[200:201], v158 offset:0x5a00
	s_waitcnt lgkmcnt(6)
	v_mfma_f32_32x32x16_bf16 v[2:17], v[186:189], v[202:205], v[2:17]
	ds_read_b64_tr_b16 v[202:203], v158 offset:0x6200
	ds_read_b64_tr_b16 v[204:205], v158 offset:0x6a00
	s_waitcnt lgkmcnt(6)
	v_mfma_f32_32x32x16_bf16 v[2:17], v[190:193], v[206:209], v[2:17]
	ds_read_b64_tr_b16 v[206:207], v158 offset:0x7200
	ds_read_b64_tr_b16 v[208:209], v158 offset:0x7a00
	s_waitcnt lgkmcnt(6)
	v_mfma_f32_32x32x16_bf16 v[18:33], v[146:149], v[194:197], v[18:33]
	ds_read_b64_tr_b16 v[194:195], v158 offset:0x4400
	ds_read_b64_tr_b16 v[196:197], v158 offset:0x4c00
	s_waitcnt lgkmcnt(6)
	v_mfma_f32_32x32x16_bf16 v[18:33], v[150:153], v[198:201], v[18:33]
	ds_read_b64_tr_b16 v[198:199], v158 offset:0x5400
	ds_read_b64_tr_b16 v[200:201], v158 offset:0x5c00
	s_waitcnt lgkmcnt(6)
	v_mfma_f32_32x32x16_bf16 v[18:33], v[186:189], v[202:205], v[18:33]
	ds_read_b64_tr_b16 v[202:203], v158 offset:0x6400
	ds_read_b64_tr_b16 v[204:205], v158 offset:0x6c00
	s_waitcnt lgkmcnt(6)
	v_mfma_f32_32x32x16_bf16 v[18:33], v[190:193], v[206:209], v[18:33]
	ds_read_b64_tr_b16 v[206:207], v158 offset:0x7400
	ds_read_b64_tr_b16 v[208:209], v158 offset:0x7c00
	s_waitcnt lgkmcnt(6)
	v_mfma_f32_32x32x16_bf16 v[34:49], v[146:149], v[194:197], v[34:49]
	ds_read_b64_tr_b16 v[194:195], v158 offset:0x4600
	ds_read_b64_tr_b16 v[196:197], v158 offset:0x4e00
	s_waitcnt lgkmcnt(6)
	v_mfma_f32_32x32x16_bf16 v[34:49], v[150:153], v[198:201], v[34:49]
	ds_read_b64_tr_b16 v[198:199], v158 offset:0x5600
	ds_read_b64_tr_b16 v[200:201], v158 offset:0x5e00
	s_waitcnt lgkmcnt(6)
	v_mfma_f32_32x32x16_bf16 v[34:49], v[186:189], v[202:205], v[34:49]
	ds_read_b64_tr_b16 v[202:203], v158 offset:0x6600
	ds_read_b64_tr_b16 v[204:205], v158 offset:0x6e00
	s_waitcnt lgkmcnt(6)
	v_mfma_f32_32x32x16_bf16 v[34:49], v[190:193], v[206:209], v[34:49]
	ds_read_b64_tr_b16 v[206:207], v158 offset:0x7600
	ds_read_b64_tr_b16 v[208:209], v158 offset:0x7e00
	s_waitcnt lgkmcnt(6)
	v_mfma_f32_32x32x16_bf16 v[50:65], v[146:149], v[194:197], v[50:65]
	s_waitcnt lgkmcnt(4)
	v_mfma_f32_32x32x16_bf16 v[50:65], v[150:153], v[198:201], v[50:65]
	s_waitcnt lgkmcnt(2)
	v_mfma_f32_32x32x16_bf16 v[50:65], v[186:189], v[202:205], v[50:65]
	s_waitcnt lgkmcnt(0)
	v_mfma_f32_32x32x16_bf16 v[50:65], v[190:193], v[206:209], v[50:65]
	v_max_f32_e32 v146, v83, v83
	v_max_f32_e32 v147, v82, v82
	v_max_f32_e32 v146, v147, v146
	v_max3_f32 v146, v146, v84, v85
	v_max3_f32 v146, v146, v86, v87
	v_max3_f32 v146, v146, v88, v89
	v_max3_f32 v146, v146, v90, v91
	v_max3_f32 v146, v146, v92, v93
	v_max3_f32 v146, v146, v94, v95
	v_max3_f32 v146, v146, v96, v97
	v_max3_f32 v146, v146, v66, v67
	v_max3_f32 v146, v146, v68, v69
	v_max3_f32 v146, v146, v70, v71
	v_max3_f32 v146, v146, v72, v73
	v_max3_f32 v146, v146, v74, v75
	v_max3_f32 v146, v146, v76, v77
	v_max3_f32 v146, v146, v78, v79
	v_max3_f32 v146, v146, v80, v81
	v_mov_b32_e32 v147, v146
	s_nop 1
	v_permlane32_swap_b32_e32 v146, v147
	v_max_f32_e32 v147, v147, v147
	v_max_f32_e32 v146, v146, v146
	v_max_f32_e32 v146, v146, v147
	v_sub_f32_e32 v147, v146, v184
	v_mul_f32_e32 v147, 0x3e0293ee, v147
	v_cmp_ge_f32_e32 vcc, s24, v147
	v_max_f32_e32 v147, v184, v184
	v_max_f32_e32 v147, v147, v146
	v_sub_f32_e32 v146, v184, v147
	v_mul_f32_e32 v146, 0x3e0293ee, v146
	v_exp_f32_e32 v146, v146
	s_cmp_eq_u64 vcc, exec
	s_cselect_b64 s[40:41], -1, 0
	v_cndmask_b32_e64 v146, v146, 1.0, s[40:41]
	v_cmp_gt_f32_e32 vcc, 1.0, v146
	s_barrier
	s_waitcnt vmcnt(1)
	ds_write_b128 v165, v[138:141] offset:49152
	s_waitcnt vmcnt(0)
	ds_write_b128 v165, v[142:145] offset:57344
	ds_write_b128 v166, v[130:133] offset:16384
	ds_write_b128 v167, v[134:137] offset:16384
	s_cbranch_vccz .LBB0_1422
	s_and_saveexec_b64 s[4:5], s[38:39]
	ds_write_b32 v159, v146 offset:128
	s_or_b64 exec, exec, s[4:5]
	s_waitcnt lgkmcnt(0)
	v_add_u32_e32 v142, s42, v162
	ds_read_b128 v[130:133], v142 offset:224
	ds_read_b128 v[134:137], v142 offset:192
	ds_read_b128 v[138:141], v142 offset:160
	ds_read_b128 v[142:145], v142 offset:128
	s_waitcnt lgkmcnt(3)
	v_pk_mul_f32 v[14:15], v[14:15], v[130:131]
	s_waitcnt lgkmcnt(2)
	v_pk_mul_f32 v[10:11], v[10:11], v[134:135]
	s_waitcnt lgkmcnt(1)
	v_pk_mul_f32 v[6:7], v[6:7], v[138:139]
	v_pk_mul_f32 v[16:17], v[16:17], v[132:133]
	v_pk_mul_f32 v[12:13], v[12:13], v[136:137]
	v_pk_mul_f32 v[8:9], v[8:9], v[140:141]
	s_waitcnt lgkmcnt(0)
	v_pk_mul_f32 v[4:5], v[4:5], v[144:145]
	v_pk_mul_f32 v[2:3], v[2:3], v[142:143]
	v_pk_mul_f32 v[30:31], v[30:31], v[130:131]
	v_pk_mul_f32 v[26:27], v[26:27], v[134:135]
	v_pk_mul_f32 v[22:23], v[22:23], v[138:139]
	v_pk_mul_f32 v[32:33], v[32:33], v[132:133]
	v_pk_mul_f32 v[28:29], v[28:29], v[136:137]
	v_pk_mul_f32 v[24:25], v[24:25], v[140:141]
	v_pk_mul_f32 v[20:21], v[20:21], v[144:145]
	v_pk_mul_f32 v[18:19], v[18:19], v[142:143]
	v_pk_mul_f32 v[46:47], v[46:47], v[130:131]
	v_pk_mul_f32 v[42:43], v[42:43], v[134:135]
	v_pk_mul_f32 v[38:39], v[38:39], v[138:139]
	v_pk_mul_f32 v[48:49], v[48:49], v[132:133]
	v_pk_mul_f32 v[44:45], v[44:45], v[136:137]
	v_pk_mul_f32 v[40:41], v[40:41], v[140:141]
	v_pk_mul_f32 v[36:37], v[36:37], v[144:145]
	v_pk_mul_f32 v[34:35], v[34:35], v[142:143]
	v_pk_mul_f32 v[62:63], v[62:63], v[130:131]
	v_pk_mul_f32 v[58:59], v[58:59], v[134:135]
	v_pk_mul_f32 v[54:55], v[54:55], v[138:139]
	v_pk_mul_f32 v[64:65], v[64:65], v[132:133]
	v_pk_mul_f32 v[60:61], v[60:61], v[136:137]
	v_pk_mul_f32 v[56:57], v[56:57], v[140:141]
	v_pk_mul_f32 v[52:53], v[52:53], v[144:145]
	v_pk_mul_f32 v[50:51], v[50:51], v[142:143]
.LBB0_1422:
	v_cndmask_b32_e64 v130, v147, v184, s[40:41]
	v_mul_f32_e32 v148, 0xbe0293ee, v130
	v_fmamk_f32 v82, v82, 0x3e0293ee, v148
	v_fmamk_f32 v149, v66, 0x3e0293ee, v148
	v_fmamk_f32 v66, v83, 0x3e0293ee, v148
	v_fmamk_f32 v150, v67, 0x3e0293ee, v148
	v_fmamk_f32 v67, v84, 0x3e0293ee, v148
	v_fmamk_f32 v151, v68, 0x3e0293ee, v148
	v_fmamk_f32 v68, v85, 0x3e0293ee, v148
	v_fmamk_f32 v152, v69, 0x3e0293ee, v148
	v_fmamk_f32 v69, v86, 0x3e0293ee, v148
	v_fmamk_f32 v153, v70, 0x3e0293ee, v148
	v_fmamk_f32 v70, v87, 0x3e0293ee, v148
	v_fmamk_f32 v165, v71, 0x3e0293ee, v148
	v_fmamk_f32 v71, v88, 0x3e0293ee, v148
	v_fmamk_f32 v166, v72, 0x3e0293ee, v148
	v_fmamk_f32 v72, v89, 0x3e0293ee, v148
	v_fmamk_f32 v167, v73, 0x3e0293ee, v148
	v_fmamk_f32 v73, v90, 0x3e0293ee, v148
	v_fmamk_f32 v184, v74, 0x3e0293ee, v148
	v_fmamk_f32 v74, v91, 0x3e0293ee, v148
	v_fmamk_f32 v185, v75, 0x3e0293ee, v148
	v_fmamk_f32 v75, v92, 0x3e0293ee, v148
	v_fmamk_f32 v186, v76, 0x3e0293ee, v148
	v_fmamk_f32 v76, v93, 0x3e0293ee, v148
	v_fmamk_f32 v187, v77, 0x3e0293ee, v148
	v_fmamk_f32 v77, v94, 0x3e0293ee, v148
	v_fmamk_f32 v188, v78, 0x3e0293ee, v148
	v_fmamk_f32 v78, v95, 0x3e0293ee, v148
	v_fmamk_f32 v83, v96, 0x3e0293ee, v148
	v_fmamk_f32 v84, v97, 0x3e0293ee, v148
	v_exp_f32_e32 v144, v82
	v_exp_f32_e32 v147, v66
	v_exp_f32_e32 v142, v67
	v_exp_f32_e32 v145, v68
	v_exp_f32_e32 v140, v69
	v_exp_f32_e32 v143, v70
	v_exp_f32_e32 v139, v71
	v_exp_f32_e32 v141, v72
	v_exp_f32_e32 v136, v73
	v_exp_f32_e32 v138, v74
	v_exp_f32_e32 v134, v75
	v_exp_f32_e32 v137, v76
	v_exp_f32_e32 v132, v77
	v_exp_f32_e32 v135, v78
	v_exp_f32_e32 v131, v83
	v_exp_f32_e32 v133, v84
	v_fmamk_f32 v189, v79, 0x3e0293ee, v148
	v_fmamk_f32 v190, v80, 0x3e0293ee, v148
	v_fmac_f32_e32 v148, 0x3e0293ee, v81
	s_waitcnt lgkmcnt(0)
	s_barrier
	ds_read_b128 v[228:231], v168 offset:49152
	ds_read_b128 v[232:235], v168 offset:57344
	ds_read_b128 v[236:239], v164 offset:49152
	ds_read_b128 v[248:251], v164 offset:57344
	ds_read_b128 v[252:255], v161 offset:49152
	s_waitcnt lgkmcnt(4)
	v_mfma_f32_32x32x16_bf16 v[82:97], v[228:231], v[126:129], 0
	ds_read_b128 v[228:231], v161 offset:57344
	s_waitcnt lgkmcnt(4)
	v_mfma_f32_32x32x16_bf16 v[66:81], v[232:235], v[126:129], 0
	ds_read_b128 v[232:235], v160 offset:49152
	s_waitcnt lgkmcnt(4)
	v_mfma_f32_32x32x16_bf16 v[82:97], v[236:239], v[122:125], v[82:97]
	ds_read_b128 v[236:239], v160 offset:57344
	s_waitcnt lgkmcnt(4)
	v_mfma_f32_32x32x16_bf16 v[66:81], v[248:251], v[122:125], v[66:81]
	ds_read_b128 v[248:251], v168 offset:49280
	s_waitcnt lgkmcnt(4)
	v_mfma_f32_32x32x16_bf16 v[82:97], v[252:255], v[118:121], v[82:97]
	ds_read_b128 v[252:255], v168 offset:57472
	s_waitcnt lgkmcnt(4)
	v_mfma_f32_32x32x16_bf16 v[66:81], v[228:231], v[118:121], v[66:81]
	ds_read_b128 v[228:231], v164 offset:49280
	s_waitcnt lgkmcnt(4)
	v_mfma_f32_32x32x16_bf16 v[82:97], v[232:235], v[114:117], v[82:97]
	ds_read_b128 v[232:235], v164 offset:57472
	s_waitcnt lgkmcnt(4)
	v_mfma_f32_32x32x16_bf16 v[66:81], v[236:239], v[114:117], v[66:81]
	ds_read_b128 v[236:239], v161 offset:49280
	s_waitcnt lgkmcnt(4)
	v_mfma_f32_32x32x16_bf16 v[82:97], v[248:251], v[110:113], v[82:97]
	ds_read_b128 v[248:251], v161 offset:57472
	s_waitcnt lgkmcnt(4)
	v_mfma_f32_32x32x16_bf16 v[66:81], v[252:255], v[110:113], v[66:81]
	ds_read_b128 v[252:255], v160 offset:49280
	s_waitcnt lgkmcnt(4)
	v_mfma_f32_32x32x16_bf16 v[82:97], v[228:231], v[106:109], v[82:97]
	ds_read_b128 v[228:231], v160 offset:57472
	s_waitcnt lgkmcnt(4)
	v_mfma_f32_32x32x16_bf16 v[66:81], v[232:235], v[106:109], v[66:81]
	s_waitcnt lgkmcnt(3)
	v_mfma_f32_32x32x16_bf16 v[82:97], v[236:239], v[102:105], v[82:97]
	s_waitcnt lgkmcnt(2)
	v_mfma_f32_32x32x16_bf16 v[66:81], v[248:251], v[102:105], v[66:81]
	s_waitcnt lgkmcnt(1)
	v_mfma_f32_32x32x16_bf16 v[82:97], v[252:255], v[98:101], v[82:97]
	s_waitcnt lgkmcnt(0)
	v_mfma_f32_32x32x16_bf16 v[66:81], v[228:231], v[98:101], v[66:81]
	v_add_f32_e32 v98, 0, v144
	v_add_f32_e32 v98, v147, v98
	v_add_f32_e32 v98, v142, v98
	v_add_f32_e32 v98, v145, v98
	v_add_f32_e32 v98, v140, v98
	v_add_f32_e32 v98, v143, v98
	v_add_f32_e32 v98, v139, v98
	v_add_f32_e32 v98, v141, v98
	v_add_f32_e32 v98, v136, v98
	v_add_f32_e32 v98, v138, v98
	v_add_f32_e32 v98, v134, v98
	v_add_f32_e32 v98, v137, v98
	v_exp_f32_e32 v108, v149
	v_add_f32_e32 v98, v132, v98
	v_exp_f32_e32 v109, v150
	v_add_f32_e32 v98, v135, v98
	v_exp_f32_e32 v110, v151
	v_add_f32_e32 v98, v131, v98
	v_exp_f32_e32 v111, v152
	v_add_f32_e32 v98, v133, v98
	v_exp_f32_e32 v112, v153
	v_add_f32_e32 v98, v108, v98
	v_exp_f32_e32 v113, v165
	v_add_f32_e32 v98, v109, v98
	v_exp_f32_e32 v114, v166
	v_add_f32_e32 v98, v110, v98
	v_exp_f32_e32 v115, v167
	v_add_f32_e32 v98, v111, v98
	v_exp_f32_e32 v116, v184
	v_add_f32_e32 v98, v112, v98
	v_exp_f32_e32 v117, v185
	v_add_f32_e32 v98, v113, v98
	v_exp_f32_e32 v118, v186
	v_add_f32_e32 v98, v114, v98
	v_exp_f32_e32 v119, v187
	v_add_f32_e32 v98, v115, v98
	v_exp_f32_e32 v120, v188
	v_add_f32_e32 v98, v116, v98
	v_exp_f32_e32 v121, v189
	v_add_f32_e32 v98, v117, v98
	v_exp_f32_e32 v122, v190
	v_add_f32_e32 v98, v118, v98
	v_exp_f32_e32 v123, v148
	v_add_f32_e32 v98, v119, v98
	v_add_f32_e32 v98, v120, v98
	v_add_f32_e32 v98, v121, v98
	v_add_f32_e32 v98, v122, v98
	v_add_f32_e32 v102, v123, v98
	v_mov_b32_e32 v103, v102
	v_cvt_pk_bf16_f32 v98, v144, v147
	v_cvt_pk_bf16_f32 v99, v142, v145
	v_cvt_pk_bf16_f32 v100, v140, v143
	v_cvt_pk_bf16_f32 v101, v139, v141
	s_nop 1
	v_permlane32_swap_b32_e32 v102, v103
	v_permlane32_swap_b32_e32 v98, v100
	v_permlane32_swap_b32_e32 v99, v101
	v_cvt_pk_bf16_f32 v104, v136, v138
	v_cvt_pk_bf16_f32 v105, v134, v137
	v_cvt_pk_bf16_f32 v106, v132, v135
	v_cvt_pk_bf16_f32 v107, v131, v133
	v_cvt_pk_bf16_f32 v108, v108, v109
	v_cvt_pk_bf16_f32 v109, v110, v111
	v_cvt_pk_bf16_f32 v110, v112, v113
	v_cvt_pk_bf16_f32 v111, v114, v115
	v_cvt_pk_bf16_f32 v112, v116, v117
	v_cvt_pk_bf16_f32 v113, v118, v119
	v_cvt_pk_bf16_f32 v114, v120, v121
	v_cvt_pk_bf16_f32 v115, v122, v123
	s_nop 0
	v_permlane32_swap_b32_e32 v104, v106
	v_permlane32_swap_b32_e32 v105, v107
	v_permlane32_swap_b32_e32 v108, v110
	v_permlane32_swap_b32_e32 v109, v111
	v_permlane32_swap_b32_e32 v112, v114
	v_permlane32_swap_b32_e32 v113, v115
	ds_read_b64_tr_b16 v[116:117], v158 offset:0
	ds_read_b64_tr_b16 v[118:119], v158 offset:0x800
	ds_read_b64_tr_b16 v[120:121], v158 offset:0x1000
	ds_read_b64_tr_b16 v[122:123], v158 offset:0x1800
	ds_read_b64_tr_b16 v[124:125], v158 offset:0x2000
	ds_read_b64_tr_b16 v[126:127], v158 offset:0x2800
	ds_read_b64_tr_b16 v[132:133], v158 offset:0x3000
	ds_read_b64_tr_b16 v[134:135], v158 offset:0x3800
	s_nop 0
	s_waitcnt lgkmcnt(6)
	v_mfma_f32_32x32x16_bf16 v[2:17], v[98:101], v[116:119], v[2:17]
	ds_read_b64_tr_b16 v[116:117], v158 offset:0x200
	ds_read_b64_tr_b16 v[118:119], v158 offset:0xa00
	s_waitcnt lgkmcnt(6)
	v_mfma_f32_32x32x16_bf16 v[2:17], v[104:107], v[120:123], v[2:17]
	ds_read_b64_tr_b16 v[120:121], v158 offset:0x1200
	ds_read_b64_tr_b16 v[122:123], v158 offset:0x1a00
	s_waitcnt lgkmcnt(6)
	v_mfma_f32_32x32x16_bf16 v[2:17], v[108:111], v[124:127], v[2:17]
	ds_read_b64_tr_b16 v[124:125], v158 offset:0x2200
	ds_read_b64_tr_b16 v[126:127], v158 offset:0x2a00
	s_waitcnt lgkmcnt(6)
	v_mfma_f32_32x32x16_bf16 v[2:17], v[112:115], v[132:135], v[2:17]
	ds_read_b64_tr_b16 v[132:133], v158 offset:0x3200
	ds_read_b64_tr_b16 v[134:135], v158 offset:0x3a00
	s_waitcnt lgkmcnt(6)
	v_mfma_f32_32x32x16_bf16 v[18:33], v[98:101], v[116:119], v[18:33]
	ds_read_b64_tr_b16 v[116:117], v158 offset:0x400
	ds_read_b64_tr_b16 v[118:119], v158 offset:0xc00
	s_waitcnt lgkmcnt(6)
	v_mfma_f32_32x32x16_bf16 v[18:33], v[104:107], v[120:123], v[18:33]
	ds_read_b64_tr_b16 v[120:121], v158 offset:0x1400
	ds_read_b64_tr_b16 v[122:123], v158 offset:0x1c00
	s_waitcnt lgkmcnt(6)
	v_mfma_f32_32x32x16_bf16 v[18:33], v[108:111], v[124:127], v[18:33]
	ds_read_b64_tr_b16 v[124:125], v158 offset:0x2400
	ds_read_b64_tr_b16 v[126:127], v158 offset:0x2c00
	s_waitcnt lgkmcnt(6)
	v_mfma_f32_32x32x16_bf16 v[18:33], v[112:115], v[132:135], v[18:33]
	ds_read_b64_tr_b16 v[132:133], v158 offset:0x3400
	ds_read_b64_tr_b16 v[134:135], v158 offset:0x3c00
	s_waitcnt lgkmcnt(6)
	v_mfma_f32_32x32x16_bf16 v[34:49], v[98:101], v[116:119], v[34:49]
	ds_read_b64_tr_b16 v[116:117], v158 offset:0x600
	ds_read_b64_tr_b16 v[118:119], v158 offset:0xe00
	s_waitcnt lgkmcnt(6)
	v_mfma_f32_32x32x16_bf16 v[34:49], v[104:107], v[120:123], v[34:49]
	ds_read_b64_tr_b16 v[120:121], v158 offset:0x1600
	ds_read_b64_tr_b16 v[122:123], v158 offset:0x1e00
	s_waitcnt lgkmcnt(6)
	v_mfma_f32_32x32x16_bf16 v[34:49], v[108:111], v[124:127], v[34:49]
	ds_read_b64_tr_b16 v[124:125], v158 offset:0x2600
	ds_read_b64_tr_b16 v[126:127], v158 offset:0x2e00
	s_waitcnt lgkmcnt(6)
	v_mfma_f32_32x32x16_bf16 v[34:49], v[112:115], v[132:135], v[34:49]
	ds_read_b64_tr_b16 v[132:133], v158 offset:0x3600
	ds_read_b64_tr_b16 v[134:135], v158 offset:0x3e00
	s_waitcnt lgkmcnt(6)
	v_mfma_f32_32x32x16_bf16 v[50:65], v[98:101], v[116:119], v[50:65]
	v_max_f32_e32 v98, v83, v83
	v_max_f32_e32 v99, v82, v82
	v_max_f32_e32 v98, v99, v98
	v_max3_f32 v98, v98, v84, v85
	v_max3_f32 v98, v98, v86, v87
	v_max3_f32 v98, v98, v88, v89
	v_max3_f32 v98, v98, v90, v91
	v_max3_f32 v98, v98, v92, v93
	v_max3_f32 v98, v98, v94, v95
	v_max3_f32 v98, v98, v96, v97
	s_waitcnt lgkmcnt(4)
	v_mfma_f32_32x32x16_bf16 v[50:65], v[104:107], v[120:123], v[50:65]
	v_max3_f32 v98, v98, v66, v67
	v_max3_f32 v98, v98, v68, v69
	v_max3_f32 v98, v98, v70, v71
	v_max3_f32 v98, v98, v72, v73
	v_max3_f32 v98, v98, v74, v75
	v_max3_f32 v98, v98, v76, v77
	v_max3_f32 v98, v98, v78, v79
	v_max3_f32 v98, v98, v80, v81
	s_waitcnt lgkmcnt(2)
	v_mfma_f32_32x32x16_bf16 v[50:65], v[108:111], v[124:127], v[50:65]
	v_mov_b32_e32 v99, v98
	s_nop 1
	v_permlane32_swap_b32_e32 v98, v99
	v_max_f32_e32 v99, v99, v99
	v_max_f32_e32 v98, v98, v98
	v_max_f32_e32 v98, v98, v99
	v_sub_f32_e32 v99, v98, v130
	v_mul_f32_e32 v99, 0x3e0293ee, v99
	v_cmp_ge_f32_e32 vcc, s24, v99
	v_max_f32_e32 v99, v130, v130
	v_max_f32_e32 v99, v99, v98
	s_waitcnt lgkmcnt(0)
	v_mfma_f32_32x32x16_bf16 v[50:65], v[112:115], v[132:135], v[50:65]
	v_sub_f32_e32 v98, v130, v99
	v_mul_f32_e32 v98, 0x3e0293ee, v98
	v_exp_f32_e32 v98, v98
	s_cmp_eq_u64 vcc, exec
	s_cselect_b64 s[40:41], -1, 0
	v_cndmask_b32_e64 v98, v98, 1.0, s[40:41]
	v_cmp_gt_f32_e32 vcc, 1.0, v98
	s_cbranch_vccz .LBB0_1426
	s_and_saveexec_b64 s[4:5], s[38:39]
	ds_write_b32 v159, v98 offset:128
	s_or_b64 exec, exec, s[4:5]
	s_waitcnt lgkmcnt(0)
	v_add_u32_e32 v100, s42, v162
	ds_read_b128 v[104:107], v100 offset:224
	ds_read_b128 v[108:111], v100 offset:192
	ds_read_b128 v[112:115], v100 offset:160
	ds_read_b128 v[116:119], v100 offset:128
	s_waitcnt lgkmcnt(3)
	v_pk_mul_f32 v[14:15], v[14:15], v[104:105]
	s_waitcnt lgkmcnt(2)
	v_pk_mul_f32 v[10:11], v[10:11], v[108:109]
	s_waitcnt lgkmcnt(1)
	v_pk_mul_f32 v[6:7], v[6:7], v[112:113]
	v_pk_mul_f32 v[16:17], v[16:17], v[106:107]
	v_pk_mul_f32 v[12:13], v[12:13], v[110:111]
	v_pk_mul_f32 v[8:9], v[8:9], v[114:115]
	s_waitcnt lgkmcnt(0)
	v_pk_mul_f32 v[4:5], v[4:5], v[118:119]
	v_pk_mul_f32 v[2:3], v[2:3], v[116:117]
	v_pk_mul_f32 v[30:31], v[30:31], v[104:105]
	v_pk_mul_f32 v[26:27], v[26:27], v[108:109]
	v_pk_mul_f32 v[22:23], v[22:23], v[112:113]
	v_pk_mul_f32 v[32:33], v[32:33], v[106:107]
	v_pk_mul_f32 v[28:29], v[28:29], v[110:111]
	v_pk_mul_f32 v[24:25], v[24:25], v[114:115]
	v_pk_mul_f32 v[20:21], v[20:21], v[118:119]
	v_pk_mul_f32 v[18:19], v[18:19], v[116:117]
	v_pk_mul_f32 v[46:47], v[46:47], v[104:105]
	v_pk_mul_f32 v[42:43], v[42:43], v[108:109]
	v_pk_mul_f32 v[38:39], v[38:39], v[112:113]
	v_pk_mul_f32 v[48:49], v[48:49], v[106:107]
	v_pk_mul_f32 v[44:45], v[44:45], v[110:111]
	v_pk_mul_f32 v[40:41], v[40:41], v[114:115]
	v_pk_mul_f32 v[36:37], v[36:37], v[118:119]
	v_pk_mul_f32 v[34:35], v[34:35], v[116:117]
	v_pk_mul_f32 v[62:63], v[62:63], v[104:105]
	v_pk_mul_f32 v[58:59], v[58:59], v[108:109]
	v_pk_mul_f32 v[54:55], v[54:55], v[112:113]
	v_pk_mul_f32 v[64:65], v[64:65], v[106:107]
	v_pk_mul_f32 v[60:61], v[60:61], v[110:111]
	v_pk_mul_f32 v[56:57], v[56:57], v[114:115]
	v_pk_mul_f32 v[52:53], v[52:53], v[118:119]
	v_pk_mul_f32 v[50:51], v[50:51], v[116:117]
.LBB0_1426:
	v_cndmask_b32_e64 v99, v99, v130, s[40:41]
	v_mul_f32_e32 v99, 0xbe0293ee, v99
	v_fmamk_f32 v82, v82, 0x3e0293ee, v99
	v_fmamk_f32 v66, v66, 0x3e0293ee, v99
	v_fmamk_f32 v83, v83, 0x3e0293ee, v99
	v_fmamk_f32 v67, v67, 0x3e0293ee, v99
	v_fmamk_f32 v84, v84, 0x3e0293ee, v99
	v_fmamk_f32 v68, v68, 0x3e0293ee, v99
	v_fmamk_f32 v85, v85, 0x3e0293ee, v99
	v_fmamk_f32 v69, v69, 0x3e0293ee, v99
	v_fmamk_f32 v86, v86, 0x3e0293ee, v99
	v_fmamk_f32 v70, v70, 0x3e0293ee, v99
	v_fmamk_f32 v87, v87, 0x3e0293ee, v99
	v_fmamk_f32 v71, v71, 0x3e0293ee, v99
	v_fmamk_f32 v88, v88, 0x3e0293ee, v99
	v_fmamk_f32 v72, v72, 0x3e0293ee, v99
	v_fmamk_f32 v89, v89, 0x3e0293ee, v99
	v_fmamk_f32 v73, v73, 0x3e0293ee, v99
	v_fmamk_f32 v90, v90, 0x3e0293ee, v99
	v_fmamk_f32 v74, v74, 0x3e0293ee, v99
	v_fmamk_f32 v91, v91, 0x3e0293ee, v99
	v_fmamk_f32 v75, v75, 0x3e0293ee, v99
	v_fmamk_f32 v92, v92, 0x3e0293ee, v99
	v_fmamk_f32 v76, v76, 0x3e0293ee, v99
	v_fmamk_f32 v93, v93, 0x3e0293ee, v99
	v_fmamk_f32 v77, v77, 0x3e0293ee, v99
	v_fmamk_f32 v94, v94, 0x3e0293ee, v99
	v_fmamk_f32 v78, v78, 0x3e0293ee, v99
	v_fmamk_f32 v95, v95, 0x3e0293ee, v99
	v_fmamk_f32 v79, v79, 0x3e0293ee, v99
	v_fmamk_f32 v96, v96, 0x3e0293ee, v99
	v_fmamk_f32 v80, v80, 0x3e0293ee, v99
	v_fmamk_f32 v97, v97, 0x3e0293ee, v99
	v_fmac_f32_e32 v99, 0x3e0293ee, v81
	v_exp_f32_e32 v81, v82
	v_exp_f32_e32 v82, v83
	v_exp_f32_e32 v83, v84
	v_exp_f32_e32 v84, v85
	v_exp_f32_e32 v85, v86
	v_exp_f32_e32 v86, v87
	v_exp_f32_e32 v87, v88
	v_exp_f32_e32 v88, v89
	v_exp_f32_e32 v89, v90
	v_exp_f32_e32 v90, v91
	v_exp_f32_e32 v91, v92
	v_exp_f32_e32 v92, v93
	v_exp_f32_e32 v93, v94
	v_exp_f32_e32 v94, v95
	v_exp_f32_e32 v95, v96
	v_exp_f32_e32 v96, v97
	v_exp_f32_e32 v97, v66
	v_add_f32_e32 v66, 0, v81
	v_add_f32_e32 v66, v82, v66
	v_add_f32_e32 v66, v83, v66
	v_add_f32_e32 v66, v84, v66
	v_add_f32_e32 v66, v85, v66
	v_add_f32_e32 v66, v86, v66
	v_add_f32_e32 v66, v87, v66
	v_add_f32_e32 v66, v88, v66
	v_add_f32_e32 v66, v89, v66
	v_add_f32_e32 v66, v90, v66
	v_add_f32_e32 v66, v91, v66
	v_add_f32_e32 v66, v92, v66
	v_add_f32_e32 v66, v93, v66
	v_exp_f32_e32 v100, v67
	v_add_f32_e32 v66, v94, v66
	v_exp_f32_e32 v101, v68
	v_add_f32_e32 v66, v95, v66
	v_exp_f32_e32 v104, v69
	v_add_f32_e32 v66, v96, v66
	v_exp_f32_e32 v105, v70
	v_add_f32_e32 v66, v97, v66
	v_exp_f32_e32 v106, v71
	v_add_f32_e32 v66, v100, v66
	v_exp_f32_e32 v107, v72
	v_add_f32_e32 v66, v101, v66
	v_exp_f32_e32 v108, v73
	v_add_f32_e32 v66, v104, v66
	v_exp_f32_e32 v109, v74
	v_add_f32_e32 v66, v105, v66
	v_exp_f32_e32 v110, v75
	v_add_f32_e32 v66, v106, v66
	v_exp_f32_e32 v111, v76
	v_add_f32_e32 v66, v107, v66
	v_exp_f32_e32 v112, v77
	v_add_f32_e32 v66, v108, v66
	v_exp_f32_e32 v113, v78
	v_add_f32_e32 v66, v109, v66
	v_exp_f32_e32 v114, v79
	v_add_f32_e32 v66, v110, v66
	v_exp_f32_e32 v115, v80
	v_add_f32_e32 v66, v111, v66
	v_exp_f32_e32 v99, v99
	v_add_f32_e32 v66, v112, v66
	v_add_f32_e32 v66, v113, v66
	v_add_f32_e32 v66, v114, v66
	v_add_f32_e32 v66, v115, v66
	v_add_f32_e32 v70, v99, v66
	v_mov_b32_e32 v71, v70
	s_nop 1
	v_permlane32_swap_b32_e32 v70, v71
	v_cvt_pk_bf16_f32 v66, v81, v82
	v_cvt_pk_bf16_f32 v67, v83, v84
	v_cvt_pk_bf16_f32 v68, v85, v86
	v_cvt_pk_bf16_f32 v69, v87, v88
	v_cvt_pk_bf16_f32 v72, v89, v90
	v_cvt_pk_bf16_f32 v73, v91, v92
	v_cvt_pk_bf16_f32 v74, v93, v94
	v_cvt_pk_bf16_f32 v75, v95, v96
	v_cvt_pk_bf16_f32 v76, v97, v100
	v_cvt_pk_bf16_f32 v77, v101, v104
	v_cvt_pk_bf16_f32 v78, v105, v106
	v_cvt_pk_bf16_f32 v79, v107, v108
	v_cvt_pk_bf16_f32 v80, v109, v110
	v_cvt_pk_bf16_f32 v81, v111, v112
	v_cvt_pk_bf16_f32 v82, v113, v114
	v_cvt_pk_bf16_f32 v83, v115, v99
	s_nop 0
	v_permlane32_swap_b32_e32 v66, v68
	v_permlane32_swap_b32_e32 v67, v69
	v_permlane32_swap_b32_e32 v72, v74
	v_permlane32_swap_b32_e32 v73, v75
	v_permlane32_swap_b32_e32 v76, v78
	v_permlane32_swap_b32_e32 v77, v79
	v_permlane32_swap_b32_e32 v80, v82
	v_permlane32_swap_b32_e32 v81, v83
	ds_read_b64_tr_b16 v[84:85], v158 offset:0x4000
	ds_read_b64_tr_b16 v[86:87], v158 offset:0x4800
	ds_read_b64_tr_b16 v[88:89], v158 offset:0x5000
	ds_read_b64_tr_b16 v[90:91], v158 offset:0x5800
	ds_read_b64_tr_b16 v[92:93], v158 offset:0x6000
	ds_read_b64_tr_b16 v[94:95], v158 offset:0x6800
	ds_read_b64_tr_b16 v[104:105], v158 offset:0x7000
	ds_read_b64_tr_b16 v[106:107], v158 offset:0x7800
	s_nop 0
	s_waitcnt lgkmcnt(6)
	v_mfma_f32_32x32x16_bf16 v[2:17], v[66:69], v[84:87], v[2:17]
	ds_read_b64_tr_b16 v[84:85], v158 offset:0x4200
	ds_read_b64_tr_b16 v[86:87], v158 offset:0x4a00
	s_waitcnt lgkmcnt(6)
	v_mfma_f32_32x32x16_bf16 v[2:17], v[72:75], v[88:91], v[2:17]
	ds_read_b64_tr_b16 v[88:89], v158 offset:0x5200
	ds_read_b64_tr_b16 v[90:91], v158 offset:0x5a00
	s_waitcnt lgkmcnt(6)
	v_mfma_f32_32x32x16_bf16 v[2:17], v[76:79], v[92:95], v[2:17]
	ds_read_b64_tr_b16 v[92:93], v158 offset:0x6200
	ds_read_b64_tr_b16 v[94:95], v158 offset:0x6a00
	s_waitcnt lgkmcnt(6)
	v_mfma_f32_32x32x16_bf16 v[2:17], v[80:83], v[104:107], v[2:17]
	ds_read_b64_tr_b16 v[104:105], v158 offset:0x7200
	ds_read_b64_tr_b16 v[106:107], v158 offset:0x7a00
	s_waitcnt lgkmcnt(6)
	v_mfma_f32_32x32x16_bf16 v[18:33], v[66:69], v[84:87], v[18:33]
	ds_read_b64_tr_b16 v[84:85], v158 offset:0x4400
	ds_read_b64_tr_b16 v[86:87], v158 offset:0x4c00
	s_waitcnt lgkmcnt(6)
	v_mfma_f32_32x32x16_bf16 v[18:33], v[72:75], v[88:91], v[18:33]
	ds_read_b64_tr_b16 v[88:89], v158 offset:0x5400
	ds_read_b64_tr_b16 v[90:91], v158 offset:0x5c00
	s_waitcnt lgkmcnt(6)
	v_mfma_f32_32x32x16_bf16 v[18:33], v[76:79], v[92:95], v[18:33]
	ds_read_b64_tr_b16 v[92:93], v158 offset:0x6400
	ds_read_b64_tr_b16 v[94:95], v158 offset:0x6c00
	s_waitcnt lgkmcnt(6)
	v_mfma_f32_32x32x16_bf16 v[18:33], v[80:83], v[104:107], v[18:33]
	ds_read_b64_tr_b16 v[104:105], v158 offset:0x7400
	ds_read_b64_tr_b16 v[106:107], v158 offset:0x7c00
	s_waitcnt lgkmcnt(6)
	v_mfma_f32_32x32x16_bf16 v[34:49], v[66:69], v[84:87], v[34:49]
	ds_read_b64_tr_b16 v[84:85], v158 offset:0x4600
	ds_read_b64_tr_b16 v[86:87], v158 offset:0x4e00
	s_waitcnt lgkmcnt(6)
	v_mfma_f32_32x32x16_bf16 v[34:49], v[72:75], v[88:91], v[34:49]
	ds_read_b64_tr_b16 v[88:89], v158 offset:0x5600
	ds_read_b64_tr_b16 v[90:91], v158 offset:0x5e00
	s_waitcnt lgkmcnt(6)
	v_mfma_f32_32x32x16_bf16 v[34:49], v[76:79], v[92:95], v[34:49]
	ds_read_b64_tr_b16 v[92:93], v158 offset:0x6600
	ds_read_b64_tr_b16 v[94:95], v158 offset:0x6e00
	s_waitcnt lgkmcnt(6)
	v_mfma_f32_32x32x16_bf16 v[34:49], v[80:83], v[104:107], v[34:49]
	ds_read_b64_tr_b16 v[104:105], v158 offset:0x7600
	ds_read_b64_tr_b16 v[106:107], v158 offset:0x7e00
	s_waitcnt lgkmcnt(6)
	v_mfma_f32_32x32x16_bf16 v[50:65], v[66:69], v[84:87], v[50:65]
	s_waitcnt lgkmcnt(4)
	v_mfma_f32_32x32x16_bf16 v[50:65], v[72:75], v[88:91], v[50:65]
	s_waitcnt lgkmcnt(2)
	v_mfma_f32_32x32x16_bf16 v[50:65], v[76:79], v[92:95], v[50:65]
	s_waitcnt lgkmcnt(0)
	v_mfma_f32_32x32x16_bf16 v[50:65], v[80:83], v[104:107], v[50:65]
	s_and_saveexec_b64 s[4:5], s[38:39]
	s_cbranch_execz .LBB0_1428
	v_mul_f32_e32 v66, 0, v181
	v_cndmask_b32_e64 v66, v66, 0, s[36:37]
	v_add_f32_e32 v67, v169, v179
	v_add_f32_e32 v66, v66, v67
	v_add_f32_e32 v67, v182, v183
	v_fmac_f32_e32 v67, v66, v180
	v_add_f32_e32 v66, v102, v103
	v_fmac_f32_e32 v66, v67, v146
	v_add_f32_e32 v67, v70, v71
	v_fmac_f32_e32 v67, v66, v98
	ds_write_b32 v159, v67
